# epilogues of modes 2/6/3/5: operand address arithmetic + first 16 loads issued ahead of the conditional half-workgroup barrier in front of the epilogue
# baseline (speedup 1.0000x reference)
; #define STAGE(P_, BASE, br, kt) do { const u16* _gb = (BASE) + (long)(br) * K + (long)(kt) * BK; \
;     _Pragma("unroll") for (int _i = 0; _i < 2; ++_i) { \
;       __builtin_amdgcn_global_load_lds((const unsigned*)(_gb + (long)_i * 64 * K + lane_off), \
;         (unsigned*)((char*)(P_) + lds_wbase + _i * 8192), 16, 0, 0); } } while (0)
; #define LDA(dst, b, h) _Pragma("unroll") for (int m = 0; m < 4; ++m) _Pragma("unroll") for (int k = 0; k < 2; ++k) \
;     dst[m][k] = *reinterpret_cast<const bf16x8*>((char*)SA(b, h) + lds_byte(wr * 64 + m * 16 + fr, k * 32 + fq * 8))
; #define LDB(dst, b, h) _Pragma("unroll") for (int n = 0; n < 2; ++n) _Pragma("unroll") for (int k = 0; k < 2; ++k) \
;     dst[n][k] = *reinterpret_cast<const bf16x8*>((char*)SB(b, h) + lds_byte(wc * 32 + n * 16 + fr, k * 32 + fq * 8))
; #define MMA(ai, bj, At_, Bt_) do { __builtin_amdgcn_s_setprio(1); \
;     _Pragma("unroll") for (int m = 0; m < 4; ++m) _Pragma("unroll") for (int n = 0; n < 2; ++n) _Pragma("unroll") for (int k = 0; k < 2; ++k) \
;       acc[ai][bj][m][n] = __builtin_amdgcn_mfma_f32_16x16x32_bf16(At_[m][k], Bt_[n][k], acc[ai][bj][m][n], 0, 0, 0); \
;     __builtin_amdgcn_s_setprio(0); } while (0)
; #define WAIT_V(n) asm volatile("s_waitcnt vmcnt(" #n ")" ::: "memory")
; #define WAIT_L(n) asm volatile("s_waitcnt lgkmcnt(" #n ")" ::: "memory")
; #define BAR __builtin_amdgcn_s_barrier()
; #define SCHED __builtin_amdgcn_sched_barrier(0)
; #define STAGEW(P_, BASE, cur, nxt, kt_) do { const bool _wr = (kt_) >= nt; \
;     STAGE(P_, BASE, (_wr ? (nxt) : (cur)), (_wr ? (kt_) - nt : (kt_))); } while (0)
; template <int PRE> ...
;     ...
;   for (int t = 0; t < nt; t += 2) {
;     LDB(B0, 0, 0); SCHED; LDA(At, 0, 0); STAGE(SA(1, 1), A, brow + HALF, t + 1);
;     WAIT_L(8); BAR; WAIT_L(0); MMA(0, 0, At, B0); BAR; SCHED;
;     LDB(B1, 0, 1); STAGEW(SB(0, 0), Bt, bcol, bcol_n, t + 2);
;     BAR; WAIT_L(0); MMA(0, 1, At, B1); BAR;
;     LDA(At, 0, 1); STAGEW(SA(0, 0), A, brow, brow_n, t + 2);
;     BAR; WAIT_L(0); MMA(1, 0, At, B0); BAR; SCHED;
;     STAGEW(SB(0, 1), Bt, bcol + HALF, bcol_n + HALF, t + 2);
;     WAIT_V(6); BAR; MMA(1, 1, At, B1); BAR;
.LBB0_810:
	v_add_u32_e32 v142, s81, v147
	ds_read_b128 v[134:137], v142
	ds_read_b128 v[138:141], v142 offset:1024
	ds_read_b128 v[152:155], v142 offset:2048
	ds_read_b128 v[156:159], v142 offset:3072
	s_add_i32 m0, s10, 0xc000
	ds_read_b128 v[160:163], v144
	ds_read_b128 v[168:171], v144 offset:1024
	ds_read_b128 v[172:175], v148
	ds_read_b128 v[176:179], v148 offset:1024
	ds_read_b128 v[180:183], v149
	ds_read_b128 v[184:187], v149 offset:1024
	ds_read_b128 v[188:191], v150
	ds_read_b128 v[192:195], v150 offset:1024
	global_load_lds_dwordx4 v[132:133], off
	v_lshl_add_u64 v[142:143], v[132:133], 0, s[44:45]
	s_add_i32 m0, s10, 0xe000
	s_nop 0
	global_load_lds_dwordx4 v[142:143], off
	s_waitcnt lgkmcnt(8)
	s_barrier
	s_waitcnt lgkmcnt(0)
	v_mfma_f32_16x16x32_bf16 v[124:127], v[160:163], v[134:137], v[124:127]
	v_mfma_f32_16x16x32_bf16 v[120:123], v[160:163], v[152:155], v[120:123]
	v_mfma_f32_16x16x32_bf16 v[116:119], v[172:175], v[134:137], v[116:119]
	v_mfma_f32_16x16x32_bf16 v[112:115], v[172:175], v[152:155], v[112:115]
	v_mfma_f32_16x16x32_bf16 v[108:111], v[180:183], v[134:137], v[108:111]
	v_mfma_f32_16x16x32_bf16 v[104:107], v[180:183], v[152:155], v[104:107]
	v_mfma_f32_16x16x32_bf16 v[100:103], v[188:191], v[134:137], v[100:103]
	v_mfma_f32_16x16x32_bf16 v[96:99], v[188:191], v[152:155], v[96:99]
	v_mfma_f32_16x16x32_bf16 v[124:127], v[168:171], v[138:141], v[124:127]
	v_mfma_f32_16x16x32_bf16 v[120:123], v[168:171], v[156:159], v[120:123]
	v_mfma_f32_16x16x32_bf16 v[116:119], v[176:179], v[138:141], v[116:119]
	v_mfma_f32_16x16x32_bf16 v[112:115], v[176:179], v[156:159], v[112:115]
	v_mfma_f32_16x16x32_bf16 v[108:111], v[184:187], v[138:141], v[108:111]
	v_mfma_f32_16x16x32_bf16 v[104:107], v[184:187], v[156:159], v[104:107]
	v_mfma_f32_16x16x32_bf16 v[100:103], v[192:195], v[138:141], v[100:103]
	v_mfma_f32_16x16x32_bf16 v[96:99], v[192:195], v[156:159], v[96:99]
	s_barrier
	s_add_i32 s36, s1, 2
	s_cmp_lt_u32 s1, 62
	s_cselect_b64 s[2:3], -1, 0
	s_and_b64 vcc, s[2:3], exec
	s_cselect_b32 s4, s27, s29
	s_cselect_b32 s3, 0, 0xffffffc0
	s_cselect_b32 s38, s0, s28
	s_cselect_b32 s40, s34, s31
	s_cselect_b32 s2, s30, s35
	s_ashr_i32 s5, s4, 31
	s_lshl_b64 s[4:5], s[4:5], 13
	s_add_u32 s37, s66, s4
	s_addc_u32 s39, s67, s5
	s_add_i32 s18, s36, s3
	s_lshl_b64 s[4:5], s[18:19], 7
	s_add_u32 s42, s37, s4
	v_add_u32_e32 v142, s82, v147
	s_addc_u32 s43, s39, s5
	s_mov_b32 m0, s11
	ds_read_b128 v[210:213], v142
	ds_read_b128 v[214:217], v142 offset:1024
	ds_read_b128 v[218:221], v142 offset:2048
	ds_read_b128 v[222:225], v142 offset:3072
	v_lshl_add_u64 v[142:143], s[42:43], 0, v[128:129]
	global_load_lds_dwordx4 v[142:143], off
	v_lshl_add_u64 v[142:143], v[142:143], 0, s[44:45]
	s_mov_b32 m0, s12
	s_nop 0
	global_load_lds_dwordx4 v[142:143], off
	s_barrier
	s_waitcnt lgkmcnt(0)
	v_mfma_f32_16x16x32_bf16 v[92:95], v[160:163], v[210:213], v[92:95]
	v_mfma_f32_16x16x32_bf16 v[88:91], v[160:163], v[218:221], v[88:91]
	v_mfma_f32_16x16x32_bf16 v[84:87], v[172:175], v[210:213], v[84:87]
	v_mfma_f32_16x16x32_bf16 v[80:83], v[172:175], v[218:221], v[80:83]
	v_mfma_f32_16x16x32_bf16 v[76:79], v[180:183], v[210:213], v[76:79]
	v_mfma_f32_16x16x32_bf16 v[72:75], v[180:183], v[218:221], v[72:75]
	v_mfma_f32_16x16x32_bf16 v[68:71], v[188:191], v[210:213], v[68:71]
	v_mfma_f32_16x16x32_bf16 v[64:67], v[188:191], v[218:221], v[64:67]
	v_mfma_f32_16x16x32_bf16 v[92:95], v[168:171], v[214:217], v[92:95]
	v_mfma_f32_16x16x32_bf16 v[88:91], v[168:171], v[222:225], v[88:91]
	v_mfma_f32_16x16x32_bf16 v[84:87], v[176:179], v[214:217], v[84:87]
	v_mfma_f32_16x16x32_bf16 v[80:83], v[176:179], v[222:225], v[80:83]
	v_mfma_f32_16x16x32_bf16 v[76:79], v[184:187], v[214:217], v[76:79]
	v_mfma_f32_16x16x32_bf16 v[72:75], v[184:187], v[222:225], v[72:75]
	v_mfma_f32_16x16x32_bf16 v[68:71], v[192:195], v[214:217], v[68:71]
	v_mfma_f32_16x16x32_bf16 v[64:67], v[192:195], v[222:225], v[64:67]
	s_ashr_i32 s39, s38, 31
	s_lshl_b64 s[38:39], s[38:39], 13
	s_add_u32 s3, s61, s38
	s_addc_u32 s18, s68, s39
	s_add_u32 s38, s3, s4
	s_addc_u32 s39, s18, s5
	s_mov_b32 m0, s10
	v_lshl_add_u64 v[142:143], s[38:39], 0, v[128:129]
	s_barrier
	ds_read_b128 v[160:163], v144 offset:16384
	ds_read_b128 v[168:171], v144 offset:17408
	ds_read_b128 v[172:175], v148 offset:16384
	ds_read_b128 v[176:179], v148 offset:17408
	ds_read_b128 v[180:183], v149 offset:16384
	ds_read_b128 v[184:187], v149 offset:17408
	ds_read_b128 v[188:191], v150 offset:16384
	ds_read_b128 v[192:195], v150 offset:17408
	global_load_lds_dwordx4 v[142:143], off
	v_lshl_add_u64 v[142:143], v[142:143], 0, s[44:45]
	s_mov_b32 m0, s13
	s_nop 0
	global_load_lds_dwordx4 v[142:143], off
	s_barrier
	s_waitcnt lgkmcnt(0)
	v_mfma_f32_16x16x32_bf16 v[60:63], v[160:163], v[134:137], v[60:63]
	v_mfma_f32_16x16x32_bf16 v[56:59], v[160:163], v[152:155], v[56:59]
	v_mfma_f32_16x16x32_bf16 v[52:55], v[172:175], v[134:137], v[52:55]
	v_mfma_f32_16x16x32_bf16 v[48:51], v[172:175], v[152:155], v[48:51]
	v_mfma_f32_16x16x32_bf16 v[44:47], v[180:183], v[134:137], v[44:47]
	v_mfma_f32_16x16x32_bf16 v[40:43], v[180:183], v[152:155], v[40:43]
	v_mfma_f32_16x16x32_bf16 v[36:39], v[188:191], v[134:137], v[36:39]
	v_mfma_f32_16x16x32_bf16 v[32:35], v[188:191], v[152:155], v[32:35]
	v_mfma_f32_16x16x32_bf16 v[60:63], v[168:171], v[138:141], v[60:63]
	v_mfma_f32_16x16x32_bf16 v[56:59], v[168:171], v[156:159], v[56:59]
	v_mfma_f32_16x16x32_bf16 v[52:55], v[176:179], v[138:141], v[52:55]
	v_mfma_f32_16x16x32_bf16 v[48:51], v[176:179], v[156:159], v[48:51]
	v_mfma_f32_16x16x32_bf16 v[44:47], v[184:187], v[138:141], v[44:47]
	v_mfma_f32_16x16x32_bf16 v[40:43], v[184:187], v[156:159], v[40:43]
	v_mfma_f32_16x16x32_bf16 v[36:39], v[192:195], v[138:141], v[36:39]
	v_mfma_f32_16x16x32_bf16 v[32:35], v[192:195], v[156:159], v[32:35]
	s_barrier
; #define LDA(dst, b, h) _Pragma("unroll") for (int m = 0; m < 4; ++m) _Pragma("unroll") for (int k = 0; k < 2; ++k) \
;     dst[m][k] = *reinterpret_cast<const bf16x8*>((char*)SA(b, h) + lds_byte(wr * 64 + m * 16 + fr, k * 32 + fq * 8))
; #define LDB(dst, b, h) _Pragma("unroll") for (int n = 0; n < 2; ++n) _Pragma("unroll") for (int k = 0; k < 2; ++k) \
;     dst[n][k] = *reinterpret_cast<const bf16x8*>((char*)SB(b, h) + lds_byte(wc * 32 + n * 16 + fr, k * 32 + fq * 8))
; #define MMA(ai, bj, At_, Bt_) do { __builtin_amdgcn_s_setprio(1); \
;     _Pragma("unroll") for (int m = 0; m < 4; ++m) _Pragma("unroll") for (int n = 0; n < 2; ++n) _Pragma("unroll") for (int k = 0; k < 2; ++k) \
;       acc[ai][bj][m][n] = __builtin_amdgcn_mfma_f32_16x16x32_bf16(At_[m][k], Bt_[n][k], acc[ai][bj][m][n], 0, 0, 0); \
;     __builtin_amdgcn_s_setprio(0); } while (0)
; #define WAIT_V(n) asm volatile("s_waitcnt vmcnt(" #n ")" ::: "memory")
; #define WAIT_L(n) asm volatile("s_waitcnt lgkmcnt(" #n ")" ::: "memory")
; #define BAR __builtin_amdgcn_s_barrier()
; #define SCHED __builtin_amdgcn_sched_barrier(0)
; #define STAGEW(P_, BASE, cur, nxt, kt_) do { const bool _wr = (kt_) >= nt; \
;     STAGE(P_, BASE, (_wr ? (nxt) : (cur)), (_wr ? (kt_) - nt : (kt_))); } while (0)
; template <int PRE> ...
;     ...
;     BAR; WAIT_L(0); MMA(1, 0, At, B0); BAR; SCHED;
;     STAGEW(SB(0, 1), Bt, bcol + HALF, bcol_n + HALF, t + 2);
;     WAIT_V(6); BAR; MMA(1, 1, At, B1); BAR;
;     LDB(B0, 1, 0); SCHED; LDA(At, 1, 0); STAGEW(SA(0, 1), A, brow + HALF, brow_n + HALF, t + 2);
;     WAIT_L(8); BAR; WAIT_L(0); MMA(0, 0, At, B0); BAR; SCHED;
;     LDB(B1, 1, 1); STAGEW(SB(1, 0), Bt, bcol, bcol_n, t + 3);
;     BAR; WAIT_L(0); MMA(0, 1, At, B1); BAR;
;     LDA(At, 1, 1); STAGEW(SA(1, 0), A, brow, brow_n, t + 3);
	s_ashr_i32 s41, s40, 31
	s_lshl_b64 s[38:39], s[40:41], 13
	s_add_u32 s3, s66, s38
	s_addc_u32 s18, s67, s39
	s_add_u32 s38, s3, s4
	s_addc_u32 s39, s18, s5
	s_mov_b32 m0, s14
	v_lshl_add_u64 v[134:135], s[38:39], 0, v[128:129]
	global_load_lds_dwordx4 v[134:135], off
	v_lshl_add_u64 v[134:135], v[134:135], 0, s[44:45]
	s_mov_b32 m0, s15
	s_nop 0
	global_load_lds_dwordx4 v[134:135], off
	s_waitcnt vmcnt(6)
	s_barrier
	v_mfma_f32_16x16x32_bf16 v[28:31], v[160:163], v[210:213], v[28:31]
	v_mfma_f32_16x16x32_bf16 v[24:27], v[160:163], v[218:221], v[24:27]
	v_mfma_f32_16x16x32_bf16 v[20:23], v[172:175], v[210:213], v[20:23]
	v_mfma_f32_16x16x32_bf16 v[16:19], v[172:175], v[218:221], v[16:19]
	v_mfma_f32_16x16x32_bf16 v[12:15], v[180:183], v[210:213], v[12:15]
	v_mfma_f32_16x16x32_bf16 v[8:11], v[180:183], v[218:221], v[8:11]
	v_mfma_f32_16x16x32_bf16 v[4:7], v[188:191], v[210:213], v[4:7]
	v_mfma_f32_16x16x32_bf16 v[0:3], v[188:191], v[218:221], v[0:3]
	v_mfma_f32_16x16x32_bf16 v[28:31], v[168:171], v[214:217], v[28:31]
	v_mfma_f32_16x16x32_bf16 v[24:27], v[168:171], v[222:225], v[24:27]
	v_mfma_f32_16x16x32_bf16 v[20:23], v[176:179], v[214:217], v[20:23]
	v_mfma_f32_16x16x32_bf16 v[16:19], v[176:179], v[222:225], v[16:19]
	v_mfma_f32_16x16x32_bf16 v[12:15], v[184:187], v[214:217], v[12:15]
	v_mfma_f32_16x16x32_bf16 v[8:11], v[184:187], v[222:225], v[8:11]
	v_mfma_f32_16x16x32_bf16 v[4:7], v[192:195], v[214:217], v[4:7]
	v_mfma_f32_16x16x32_bf16 v[0:3], v[192:195], v[222:225], v[0:3]
	v_add_u32_e32 v142, s83, v147
	s_barrier
	ds_read_b128 v[134:137], v142
	ds_read_b128 v[138:141], v142 offset:1024
	ds_read_b128 v[152:155], v142 offset:2048
	ds_read_b128 v[156:159], v142 offset:3072
	s_ashr_i32 s3, s2, 31
	s_lshl_b64 s[2:3], s[2:3], 13
	s_add_u32 s2, s61, s2
	s_addc_u32 s3, s68, s3
	s_add_u32 s2, s2, s4
	s_addc_u32 s3, s3, s5
	s_mov_b32 m0, s16
	v_lshl_add_u64 v[142:143], s[2:3], 0, v[128:129]
	ds_read_b128 v[160:163], v144 offset:32768
	ds_read_b128 v[168:171], v144 offset:33792
	ds_read_b128 v[172:175], v148 offset:32768
	ds_read_b128 v[176:179], v148 offset:33792
	ds_read_b128 v[180:183], v149 offset:32768
	ds_read_b128 v[184:187], v149 offset:33792
	ds_read_b128 v[188:191], v150 offset:32768
	ds_read_b128 v[192:195], v150 offset:33792
	global_load_lds_dwordx4 v[142:143], off
	v_lshl_add_u64 v[142:143], v[142:143], 0, s[44:45]
	s_mov_b32 m0, s17
	s_nop 0
	global_load_lds_dwordx4 v[142:143], off
	s_waitcnt lgkmcnt(8)
	s_barrier
	s_waitcnt lgkmcnt(0)
	v_mfma_f32_16x16x32_bf16 v[124:127], v[160:163], v[134:137], v[124:127]
	v_mfma_f32_16x16x32_bf16 v[120:123], v[160:163], v[152:155], v[120:123]
	v_mfma_f32_16x16x32_bf16 v[116:119], v[172:175], v[134:137], v[116:119]
	v_mfma_f32_16x16x32_bf16 v[112:115], v[172:175], v[152:155], v[112:115]
	v_mfma_f32_16x16x32_bf16 v[108:111], v[180:183], v[134:137], v[108:111]
	v_mfma_f32_16x16x32_bf16 v[104:107], v[180:183], v[152:155], v[104:107]
	v_mfma_f32_16x16x32_bf16 v[100:103], v[188:191], v[134:137], v[100:103]
	v_mfma_f32_16x16x32_bf16 v[96:99], v[188:191], v[152:155], v[96:99]
	v_mfma_f32_16x16x32_bf16 v[124:127], v[168:171], v[138:141], v[124:127]
	v_mfma_f32_16x16x32_bf16 v[120:123], v[168:171], v[156:159], v[120:123]
	v_mfma_f32_16x16x32_bf16 v[116:119], v[176:179], v[138:141], v[116:119]
	v_mfma_f32_16x16x32_bf16 v[112:115], v[176:179], v[156:159], v[112:115]
	v_mfma_f32_16x16x32_bf16 v[108:111], v[184:187], v[138:141], v[108:111]
	v_mfma_f32_16x16x32_bf16 v[104:107], v[184:187], v[156:159], v[104:107]
	v_mfma_f32_16x16x32_bf16 v[100:103], v[192:195], v[138:141], v[100:103]
	v_mfma_f32_16x16x32_bf16 v[96:99], v[192:195], v[156:159], v[96:99]
	s_barrier
	s_cmp_lt_u32 s1, 61
	s_cselect_b32 s2, s27, s29
	s_cselect_b32 s5, 0, 0xffffffc0
	s_cselect_b32 s4, s0, s28
	s_cselect_b32 s38, s34, s31
	s_ashr_i32 s3, s2, 31
	s_lshl_b64 s[2:3], s[2:3], 13
	s_add_u32 s37, s66, s2
	s_addc_u32 s39, s67, s3
	s_add_i32 s1, s5, s1
	s_add_i32 s18, s1, 3
	s_lshl_b64 s[2:3], s[18:19], 7
	s_add_u32 s40, s37, s2
	v_add_u32_e32 v142, s84, v147
	s_addc_u32 s41, s39, s3
	s_mov_b32 m0, s20
	ds_read_b128 v[210:213], v142
	ds_read_b128 v[214:217], v142 offset:1024
	ds_read_b128 v[218:221], v142 offset:2048
	ds_read_b128 v[222:225], v142 offset:3072
	v_lshl_add_u64 v[142:143], s[40:41], 0, v[128:129]
	global_load_lds_dwordx4 v[142:143], off
	v_lshl_add_u64 v[142:143], v[142:143], 0, s[44:45]
	s_mov_b32 m0, s21
	s_nop 0
	global_load_lds_dwordx4 v[142:143], off
	s_barrier
	s_waitcnt lgkmcnt(0)
	v_mfma_f32_16x16x32_bf16 v[92:95], v[160:163], v[210:213], v[92:95]
	v_mfma_f32_16x16x32_bf16 v[88:91], v[160:163], v[218:221], v[88:91]
	v_mfma_f32_16x16x32_bf16 v[84:87], v[172:175], v[210:213], v[84:87]
	v_mfma_f32_16x16x32_bf16 v[80:83], v[172:175], v[218:221], v[80:83]
	v_mfma_f32_16x16x32_bf16 v[76:79], v[180:183], v[210:213], v[76:79]
	v_mfma_f32_16x16x32_bf16 v[72:75], v[180:183], v[218:221], v[72:75]
	v_mfma_f32_16x16x32_bf16 v[68:71], v[188:191], v[210:213], v[68:71]
	v_mfma_f32_16x16x32_bf16 v[64:67], v[188:191], v[218:221], v[64:67]
	v_mfma_f32_16x16x32_bf16 v[92:95], v[168:171], v[214:217], v[92:95]
	v_mfma_f32_16x16x32_bf16 v[88:91], v[168:171], v[222:225], v[88:91]
	v_mfma_f32_16x16x32_bf16 v[84:87], v[176:179], v[214:217], v[84:87]
	v_mfma_f32_16x16x32_bf16 v[80:83], v[176:179], v[222:225], v[80:83]
	v_mfma_f32_16x16x32_bf16 v[76:79], v[184:187], v[214:217], v[76:79]
	v_mfma_f32_16x16x32_bf16 v[72:75], v[184:187], v[222:225], v[72:75]
	v_mfma_f32_16x16x32_bf16 v[68:71], v[192:195], v[214:217], v[68:71]
	v_mfma_f32_16x16x32_bf16 v[64:67], v[192:195], v[222:225], v[64:67]
	s_ashr_i32 s5, s4, 31
	s_lshl_b64 s[4:5], s[4:5], 13
	s_add_u32 s1, s61, s4
	s_addc_u32 s5, s68, s5
	s_add_u32 s4, s1, s2
	s_addc_u32 s5, s5, s3
	s_mov_b32 m0, s22
	v_lshl_add_u64 v[142:143], s[4:5], 0, v[128:129]
	s_barrier
; __device__ __forceinline__ float bflo(unsigned u) { return __uint_as_float(u << 16); }
; __device__ __forceinline__ float bfhi(unsigned u) { return __uint_as_float(u & 0xffff0000u); }
; __device__ __forceinline__ float sigmoidf_(float x) { return __builtin_amdgcn_rcpf(1.f + __expf(-x)); }
; #define WAIT_V(n) asm volatile("s_waitcnt vmcnt(" #n ")" ::: "memory")
; template <int PRE> ...
;     ...
;     LDA(At, 1, 1); STAGEW(SA(1, 0), A, brow, brow_n, t + 3);
;     BAR; WAIT_L(0); MMA(1, 0, At, B0); BAR; SCHED;
;     STAGEW(SB(1, 1), Bt, bcol + HALF, bcol_n + HALF, t + 3);
;     WAIT_V(6); BAR; MMA(1, 1, At, B1); BAR;
;   }
;   if (wr == 0) BAR;
;     ...
;               const int nc = brow + ai * 128 + wr * 64 + m * 16 + fq * 4;
;               const int tok = bcol + bj * 128 + wc * 32 + n * 16 + fr;
;               const int ncw = brow + ai * 128 + wr * 64 + ((m & ~1) + (fq & 1)) * 16 + (fq & ~1) * 4;
;     ...
;               f32x4 v = acc[ai][bj][m][n];
;               if (MODE == 0) {
;                 if (tn == 52) {
;                   if (ai == 0) *(float4*)((float*)(ws + OFF_DTR) + (size_t)tok * 128 + (nc - 13312)) = make_float4(v[0], v[1], v[2], v[3]);
;                 } else {
;                   u16* dst; int ld, c0;
;                   if (tn < 16) { dst = (u16*)(ws + OFF_Z); ld = 4096; c0 = 0; }
;                   else if (tn < 40) { dst = (u16*)(ws + OFF_RA); ld = 6144; c0 = 4096; }
;                   else if (tn < 48) { dst = (u16*)(ws + OFF_Q); ld = 2048; c0 = 10240; }
;                   else if (tn < 50) { dst = (u16*)(ws + OFF_K); ld = 512; c0 = 12288; }
;                   else { dst = (u16*)(ws + OFF_V); ld = 512; c0 = 12800; }
;                   uint2 o; o.x = pk2(v[0], v[1]); o.y = pk2(v[2], v[3]);
;                   WIDE_STORE(dst, ld, c0, o);
;                 }
;               } else if (MODE == 1) {
;                 uint2 o; o.x = pk2(sigmoidf_(v[0]), sigmoidf_(v[1])); o.y = pk2(sigmoidf_(v[2]), sigmoidf_(v[3]));
;                 WIDE_STORE((u16*)outp, 4096, 0, o);
;               } else if (MODE == 2) {
;                 const u16* gate = (const u16*)outp;
;                 uint2 ga = *(const uint2*)(gate + (size_t)tok * 4096 + nc);
;                 uint2 p1; p1.x = pk2(v[0] * bflo(ga.x), v[1] * bfhi(ga.x)); p1.y = pk2(v[2] * bflo(ga.y), v[3] * bfhi(ga.y));
;                 *(uint2*)((u16*)(ws + OFF_YB) + (size_t)tok * DM + nc) = p1;
	ds_read_b128 v[160:163], v144 offset:49152
	ds_read_b128 v[168:171], v144 offset:50176
	ds_read_b128 v[172:175], v148 offset:49152
	ds_read_b128 v[176:179], v148 offset:50176
	ds_read_b128 v[180:183], v149 offset:49152
	ds_read_b128 v[184:187], v149 offset:50176
	ds_read_b128 v[188:191], v150 offset:49152
	ds_read_b128 v[192:195], v150 offset:50176
	global_load_lds_dwordx4 v[142:143], off
	v_lshl_add_u64 v[142:143], v[142:143], 0, s[44:45]
	s_mov_b32 m0, s23
	s_nop 0
	global_load_lds_dwordx4 v[142:143], off
	s_barrier
	s_waitcnt lgkmcnt(0)
	v_mfma_f32_16x16x32_bf16 v[60:63], v[160:163], v[134:137], v[60:63]
	v_mfma_f32_16x16x32_bf16 v[56:59], v[160:163], v[152:155], v[56:59]
	v_mfma_f32_16x16x32_bf16 v[52:55], v[172:175], v[134:137], v[52:55]
	v_mfma_f32_16x16x32_bf16 v[48:51], v[172:175], v[152:155], v[48:51]
	v_mfma_f32_16x16x32_bf16 v[44:47], v[180:183], v[134:137], v[44:47]
	v_mfma_f32_16x16x32_bf16 v[40:43], v[180:183], v[152:155], v[40:43]
	v_mfma_f32_16x16x32_bf16 v[36:39], v[188:191], v[134:137], v[36:39]
	v_mfma_f32_16x16x32_bf16 v[32:35], v[188:191], v[152:155], v[32:35]
	v_mfma_f32_16x16x32_bf16 v[60:63], v[168:171], v[138:141], v[60:63]
	v_mfma_f32_16x16x32_bf16 v[56:59], v[168:171], v[156:159], v[56:59]
	v_mfma_f32_16x16x32_bf16 v[52:55], v[176:179], v[138:141], v[52:55]
	v_mfma_f32_16x16x32_bf16 v[48:51], v[176:179], v[156:159], v[48:51]
	v_mfma_f32_16x16x32_bf16 v[44:47], v[184:187], v[138:141], v[44:47]
	v_mfma_f32_16x16x32_bf16 v[40:43], v[184:187], v[156:159], v[40:43]
	v_mfma_f32_16x16x32_bf16 v[36:39], v[192:195], v[138:141], v[36:39]
	v_mfma_f32_16x16x32_bf16 v[32:35], v[192:195], v[156:159], v[32:35]
	s_barrier
	s_ashr_i32 s39, s38, 31
	s_lshl_b64 s[4:5], s[38:39], 13
	s_add_u32 s1, s66, s4
	s_addc_u32 s4, s67, s5
	s_add_u32 s2, s1, s2
	s_addc_u32 s3, s4, s3
	s_mov_b32 m0, s24
	v_lshl_add_u64 v[134:135], s[2:3], 0, v[128:129]
	global_load_lds_dwordx4 v[134:135], off
	v_lshl_add_u64 v[134:135], v[134:135], 0, s[44:45]
	s_mov_b32 m0, s25
	s_nop 0
	global_load_lds_dwordx4 v[134:135], off
	s_waitcnt vmcnt(6)
	s_barrier
	v_mfma_f32_16x16x32_bf16 v[28:31], v[160:163], v[210:213], v[28:31]
	v_mfma_f32_16x16x32_bf16 v[24:27], v[160:163], v[218:221], v[24:27]
	v_mfma_f32_16x16x32_bf16 v[20:23], v[172:175], v[210:213], v[20:23]
	v_mfma_f32_16x16x32_bf16 v[16:19], v[172:175], v[218:221], v[16:19]
	v_mfma_f32_16x16x32_bf16 v[12:15], v[180:183], v[210:213], v[12:15]
	v_mfma_f32_16x16x32_bf16 v[8:11], v[180:183], v[218:221], v[8:11]
	v_mfma_f32_16x16x32_bf16 v[4:7], v[188:191], v[210:213], v[4:7]
	v_mfma_f32_16x16x32_bf16 v[0:3], v[188:191], v[218:221], v[0:3]
	v_mfma_f32_16x16x32_bf16 v[28:31], v[168:171], v[214:217], v[28:31]
	v_mfma_f32_16x16x32_bf16 v[24:27], v[168:171], v[222:225], v[24:27]
	v_mfma_f32_16x16x32_bf16 v[20:23], v[176:179], v[214:217], v[20:23]
	v_mfma_f32_16x16x32_bf16 v[16:19], v[176:179], v[222:225], v[16:19]
	v_mfma_f32_16x16x32_bf16 v[12:15], v[184:187], v[214:217], v[12:15]
	v_mfma_f32_16x16x32_bf16 v[8:11], v[184:187], v[222:225], v[8:11]
	v_mfma_f32_16x16x32_bf16 v[4:7], v[192:195], v[214:217], v[4:7]
	v_mfma_f32_16x16x32_bf16 v[0:3], v[192:195], v[222:225], v[0:3]
	v_lshl_add_u64 v[132:133], v[132:133], 0, s[46:47]
	s_mov_b32 s1, s36
	s_barrier
	s_cbranch_vccnz .LBB0_810
	v_readlane_b32 s34, v243, 2
	v_readlane_b32 s2, v243, 57
	v_readlane_b32 s3, v243, 58
	v_readlane_b32 s4, v244, 3
	v_readlane_b32 s5, v244, 4
	s_add_i32 s0, s0, s49
	v_and_b32_e32 v172, 15, v146
	v_or_b32_e32 v172, s54, v172
	v_or_b32_e32 v172, s27, v172
	v_lshrrev_b32_e32 v173, 2, v146
	v_and_b32_e32 v174, -4, v173
	v_add_u32_e32 v174, s0, v174
	v_and_b32_e32 v173, -8, v173
	v_and_b32_e32 v175, 16, v146
	v_add3_u32 v173, v173, v175, s0
	v_lshlrev_b32_e32 v175, 13, v172
	v_lshl_add_u32 v134, v174, 1, v175
	v_add_u32_e32 v135, 0x20000, v134
	v_add_u32_e32 v136, 0x100000, v134
	v_add_u32_e32 v137, 0x120000, v134
	v_lshlrev_b32_e32 v175, 12, v172
	v_lshl_add_u32 v138, v174, 1, v175
	v_add_u32_e32 v139, 0x10000, v138
	v_add_u32_e32 v140, 0x80000, v138
	v_add_u32_e32 v141, 0x90000, v138
	global_load_dwordx2 v[210:211], v134, s[2:3] offset:0
	global_load_dwordx2 v[212:213], v134, s[2:3] offset:32
	global_load_dwordx2 v[214:215], v134, s[2:3] offset:64
	global_load_dwordx2 v[216:217], v134, s[2:3] offset:96
	global_load_dwordx2 v[218:219], v135, s[2:3] offset:0
	global_load_dwordx2 v[220:221], v135, s[2:3] offset:32
	global_load_dwordx2 v[222:223], v135, s[2:3] offset:64
	global_load_dwordx2 v[224:225], v135, s[2:3] offset:96
	global_load_dwordx2 v[226:227], v136, s[2:3] offset:0
	global_load_dwordx2 v[228:229], v136, s[2:3] offset:32
	global_load_dwordx2 v[230:231], v136, s[2:3] offset:64
	global_load_dwordx2 v[232:233], v136, s[2:3] offset:96
	global_load_dwordx2 v[234:235], v137, s[2:3] offset:0
	global_load_dwordx2 v[236:237], v137, s[2:3] offset:32
	global_load_dwordx2 v[238:239], v137, s[2:3] offset:64
	global_load_dwordx2 v[240:241], v137, s[2:3] offset:96
	s_andn2_b64 vcc, exec, s[58:59]
	v_readlane_b32 s31, v244, 61
	v_readlane_b32 s35, v243, 3
	s_cbranch_vccnz .LBB0_813
	s_barrier
; __device__ __forceinline__ float bflo(unsigned u) { return __uint_as_float(u << 16); }
; __device__ __forceinline__ float bfhi(unsigned u) { return __uint_as_float(u & 0xffff0000u); }
;     ...
;               } else if (MODE == 2) {
;                 const u16* gate = (const u16*)outp;
;                 uint2 ga = *(const uint2*)(gate + (size_t)tok * 4096 + nc);
;                 uint2 p1; p1.x = pk2(v[0] * bflo(ga.x), v[1] * bfhi(ga.x)); p1.y = pk2(v[2] * bflo(ga.y), v[3] * bfhi(ga.y));
;                 *(uint2*)((u16*)(ws + OFF_YB) + (size_t)tok * DM + nc) = p1;
.LBB0_813:
	s_waitcnt vmcnt(15)
	v_lshlrev_b32_e32 v168, 16, v210
	v_and_b32_e32 v169, 0xffff0000, v210
	v_lshlrev_b32_e32 v170, 16, v211
	v_and_b32_e32 v171, 0xffff0000, v211
	v_pk_mul_f32 v[124:125], v[124:125], v[168:169]
	v_pk_mul_f32 v[126:127], v[126:127], v[170:171]
	global_load_dwordx2 v[210:211], v134, s[2:3] offset:256
	s_waitcnt vmcnt(15)
	v_lshlrev_b32_e32 v168, 16, v212
	v_and_b32_e32 v169, 0xffff0000, v212
	v_lshlrev_b32_e32 v170, 16, v213
	v_and_b32_e32 v171, 0xffff0000, v213
	v_pk_mul_f32 v[116:117], v[116:117], v[168:169]
	v_pk_mul_f32 v[118:119], v[118:119], v[170:171]
	global_load_dwordx2 v[212:213], v134, s[2:3] offset:288
	s_waitcnt vmcnt(15)
	v_lshlrev_b32_e32 v168, 16, v214
	v_and_b32_e32 v169, 0xffff0000, v214
	v_lshlrev_b32_e32 v170, 16, v215
	v_and_b32_e32 v171, 0xffff0000, v215
	v_pk_mul_f32 v[108:109], v[108:109], v[168:169]
	v_pk_mul_f32 v[110:111], v[110:111], v[170:171]
	global_load_dwordx2 v[214:215], v134, s[2:3] offset:320
	s_waitcnt vmcnt(15)
	v_lshlrev_b32_e32 v168, 16, v216
	v_and_b32_e32 v169, 0xffff0000, v216
	v_lshlrev_b32_e32 v170, 16, v217
	v_and_b32_e32 v171, 0xffff0000, v217
	v_pk_mul_f32 v[100:101], v[100:101], v[168:169]
	v_pk_mul_f32 v[102:103], v[102:103], v[170:171]
	global_load_dwordx2 v[216:217], v134, s[2:3] offset:352
	s_nop 0
	v_cvt_pk_bf16_f32 v124, v124, v125
	v_cvt_pk_bf16_f32 v125, v126, v127
	v_cvt_pk_bf16_f32 v116, v116, v117
	v_cvt_pk_bf16_f32 v117, v118, v119
	v_cvt_pk_bf16_f32 v108, v108, v109
	v_cvt_pk_bf16_f32 v109, v110, v111
	v_cvt_pk_bf16_f32 v100, v100, v101
	v_cvt_pk_bf16_f32 v101, v102, v103
	global_store_dwordx2 v138, v[124:125], s[4:5] offset:0
	global_store_dwordx2 v138, v[116:117], s[4:5] offset:32
	global_store_dwordx2 v138, v[108:109], s[4:5] offset:64
	global_store_dwordx2 v138, v[100:101], s[4:5] offset:96
	s_waitcnt vmcnt(19)
	v_lshlrev_b32_e32 v168, 16, v218
	v_and_b32_e32 v169, 0xffff0000, v218
	v_lshlrev_b32_e32 v170, 16, v219
	v_and_b32_e32 v171, 0xffff0000, v219
	v_pk_mul_f32 v[120:121], v[120:121], v[168:169]
	v_pk_mul_f32 v[122:123], v[122:123], v[170:171]
	global_load_dwordx2 v[218:219], v135, s[2:3] offset:256
	s_waitcnt vmcnt(19)
	v_lshlrev_b32_e32 v168, 16, v220
	v_and_b32_e32 v169, 0xffff0000, v220
	v_lshlrev_b32_e32 v170, 16, v221
	v_and_b32_e32 v171, 0xffff0000, v221
	v_pk_mul_f32 v[112:113], v[112:113], v[168:169]
	v_pk_mul_f32 v[114:115], v[114:115], v[170:171]
	global_load_dwordx2 v[220:221], v135, s[2:3] offset:288
	s_waitcnt vmcnt(19)
	v_lshlrev_b32_e32 v168, 16, v222
	v_and_b32_e32 v169, 0xffff0000, v222
	v_lshlrev_b32_e32 v170, 16, v223
	v_and_b32_e32 v171, 0xffff0000, v223
	v_pk_mul_f32 v[104:105], v[104:105], v[168:169]
	v_pk_mul_f32 v[106:107], v[106:107], v[170:171]
	global_load_dwordx2 v[222:223], v135, s[2:3] offset:320
	s_waitcnt vmcnt(19)
	v_lshlrev_b32_e32 v168, 16, v224
	v_and_b32_e32 v169, 0xffff0000, v224
	v_lshlrev_b32_e32 v170, 16, v225
	v_and_b32_e32 v171, 0xffff0000, v225
	v_pk_mul_f32 v[96:97], v[96:97], v[168:169]
	v_pk_mul_f32 v[98:99], v[98:99], v[170:171]
	global_load_dwordx2 v[224:225], v135, s[2:3] offset:352
	s_nop 0
	v_cvt_pk_bf16_f32 v120, v120, v121
	v_cvt_pk_bf16_f32 v121, v122, v123
	v_cvt_pk_bf16_f32 v112, v112, v113
	v_cvt_pk_bf16_f32 v113, v114, v115
	v_cvt_pk_bf16_f32 v104, v104, v105
	v_cvt_pk_bf16_f32 v105, v106, v107
	v_cvt_pk_bf16_f32 v96, v96, v97
	v_cvt_pk_bf16_f32 v97, v98, v99
	global_store_dwordx2 v139, v[120:121], s[4:5] offset:0
	global_store_dwordx2 v139, v[112:113], s[4:5] offset:32
	global_store_dwordx2 v139, v[104:105], s[4:5] offset:64
	global_store_dwordx2 v139, v[96:97], s[4:5] offset:96
	s_waitcnt vmcnt(23)
	v_lshlrev_b32_e32 v168, 16, v226
	v_and_b32_e32 v169, 0xffff0000, v226
	v_lshlrev_b32_e32 v170, 16, v227
	v_and_b32_e32 v171, 0xffff0000, v227
	v_pk_mul_f32 v[92:93], v[92:93], v[168:169]
	v_pk_mul_f32 v[94:95], v[94:95], v[170:171]
	global_load_dwordx2 v[226:227], v136, s[2:3] offset:256
	s_waitcnt vmcnt(23)
	v_lshlrev_b32_e32 v168, 16, v228
	v_and_b32_e32 v169, 0xffff0000, v228
	v_lshlrev_b32_e32 v170, 16, v229
	v_and_b32_e32 v171, 0xffff0000, v229
	v_pk_mul_f32 v[84:85], v[84:85], v[168:169]
	v_pk_mul_f32 v[86:87], v[86:87], v[170:171]
	global_load_dwordx2 v[228:229], v136, s[2:3] offset:288
	s_waitcnt vmcnt(23)
	v_lshlrev_b32_e32 v168, 16, v230
	v_and_b32_e32 v169, 0xffff0000, v230
	v_lshlrev_b32_e32 v170, 16, v231
	v_and_b32_e32 v171, 0xffff0000, v231
	v_pk_mul_f32 v[76:77], v[76:77], v[168:169]
	v_pk_mul_f32 v[78:79], v[78:79], v[170:171]
	global_load_dwordx2 v[230:231], v136, s[2:3] offset:320
	s_waitcnt vmcnt(23)
	v_lshlrev_b32_e32 v168, 16, v232
	v_and_b32_e32 v169, 0xffff0000, v232
	v_lshlrev_b32_e32 v170, 16, v233
	v_and_b32_e32 v171, 0xffff0000, v233
	v_pk_mul_f32 v[68:69], v[68:69], v[168:169]
	v_pk_mul_f32 v[70:71], v[70:71], v[170:171]
	global_load_dwordx2 v[232:233], v136, s[2:3] offset:352
	s_nop 0
	v_cvt_pk_bf16_f32 v92, v92, v93
	v_cvt_pk_bf16_f32 v93, v94, v95
	v_cvt_pk_bf16_f32 v84, v84, v85
	v_cvt_pk_bf16_f32 v85, v86, v87
	v_cvt_pk_bf16_f32 v76, v76, v77
	v_cvt_pk_bf16_f32 v77, v78, v79
	v_cvt_pk_bf16_f32 v68, v68, v69
	v_cvt_pk_bf16_f32 v69, v70, v71
	global_store_dwordx2 v140, v[92:93], s[4:5] offset:0
	global_store_dwordx2 v140, v[84:85], s[4:5] offset:32
	global_store_dwordx2 v140, v[76:77], s[4:5] offset:64
	global_store_dwordx2 v140, v[68:69], s[4:5] offset:96
	s_waitcnt vmcnt(27)
	v_lshlrev_b32_e32 v168, 16, v234
	v_and_b32_e32 v169, 0xffff0000, v234
	v_lshlrev_b32_e32 v170, 16, v235
	v_and_b32_e32 v171, 0xffff0000, v235
	v_pk_mul_f32 v[88:89], v[88:89], v[168:169]
	v_pk_mul_f32 v[90:91], v[90:91], v[170:171]
	global_load_dwordx2 v[234:235], v137, s[2:3] offset:256
	s_waitcnt vmcnt(27)
; __device__ __forceinline__ float bflo(unsigned u) { return __uint_as_float(u << 16); }
; __device__ __forceinline__ float bfhi(unsigned u) { return __uint_as_float(u & 0xffff0000u); }
;     ...
;               } else if (MODE == 2) {
;                 const u16* gate = (const u16*)outp;
;                 uint2 ga = *(const uint2*)(gate + (size_t)tok * 4096 + nc);
;                 uint2 p1; p1.x = pk2(v[0] * bflo(ga.x), v[1] * bfhi(ga.x)); p1.y = pk2(v[2] * bflo(ga.y), v[3] * bfhi(ga.y));
;                 *(uint2*)((u16*)(ws + OFF_YB) + (size_t)tok * DM + nc) = p1;
	v_lshlrev_b32_e32 v168, 16, v236
	v_and_b32_e32 v169, 0xffff0000, v236
	v_lshlrev_b32_e32 v170, 16, v237
	v_and_b32_e32 v171, 0xffff0000, v237
	v_pk_mul_f32 v[80:81], v[80:81], v[168:169]
	v_pk_mul_f32 v[82:83], v[82:83], v[170:171]
	global_load_dwordx2 v[236:237], v137, s[2:3] offset:288
	s_waitcnt vmcnt(27)
	v_lshlrev_b32_e32 v168, 16, v238
	v_and_b32_e32 v169, 0xffff0000, v238
	v_lshlrev_b32_e32 v170, 16, v239
	v_and_b32_e32 v171, 0xffff0000, v239
	v_pk_mul_f32 v[72:73], v[72:73], v[168:169]
	v_pk_mul_f32 v[74:75], v[74:75], v[170:171]
	global_load_dwordx2 v[238:239], v137, s[2:3] offset:320
	s_waitcnt vmcnt(27)
	v_lshlrev_b32_e32 v168, 16, v240
	v_and_b32_e32 v169, 0xffff0000, v240
	v_lshlrev_b32_e32 v170, 16, v241
	v_and_b32_e32 v171, 0xffff0000, v241
	v_pk_mul_f32 v[64:65], v[64:65], v[168:169]
	v_pk_mul_f32 v[66:67], v[66:67], v[170:171]
	global_load_dwordx2 v[240:241], v137, s[2:3] offset:352
	s_nop 0
	v_cvt_pk_bf16_f32 v88, v88, v89
	v_cvt_pk_bf16_f32 v89, v90, v91
	v_cvt_pk_bf16_f32 v80, v80, v81
	v_cvt_pk_bf16_f32 v81, v82, v83
	v_cvt_pk_bf16_f32 v72, v72, v73
	v_cvt_pk_bf16_f32 v73, v74, v75
	v_cvt_pk_bf16_f32 v64, v64, v65
	v_cvt_pk_bf16_f32 v65, v66, v67
	global_store_dwordx2 v141, v[88:89], s[4:5] offset:0
	global_store_dwordx2 v141, v[80:81], s[4:5] offset:32
	global_store_dwordx2 v141, v[72:73], s[4:5] offset:64
	global_store_dwordx2 v141, v[64:65], s[4:5] offset:96
	s_waitcnt vmcnt(31)
	v_lshlrev_b32_e32 v168, 16, v210
	v_and_b32_e32 v169, 0xffff0000, v210
	v_lshlrev_b32_e32 v170, 16, v211
	v_and_b32_e32 v171, 0xffff0000, v211
	v_pk_mul_f32 v[60:61], v[60:61], v[168:169]
	v_pk_mul_f32 v[62:63], v[62:63], v[170:171]
	s_waitcnt vmcnt(30)
	v_lshlrev_b32_e32 v168, 16, v212
	v_and_b32_e32 v169, 0xffff0000, v212
	v_lshlrev_b32_e32 v170, 16, v213
	v_and_b32_e32 v171, 0xffff0000, v213
	v_pk_mul_f32 v[52:53], v[52:53], v[168:169]
	v_pk_mul_f32 v[54:55], v[54:55], v[170:171]
	s_waitcnt vmcnt(29)
	v_lshlrev_b32_e32 v168, 16, v214
	v_and_b32_e32 v169, 0xffff0000, v214
	v_lshlrev_b32_e32 v170, 16, v215
	v_and_b32_e32 v171, 0xffff0000, v215
	v_pk_mul_f32 v[44:45], v[44:45], v[168:169]
	v_pk_mul_f32 v[46:47], v[46:47], v[170:171]
	s_waitcnt vmcnt(28)
	v_lshlrev_b32_e32 v168, 16, v216
	v_and_b32_e32 v169, 0xffff0000, v216
	v_lshlrev_b32_e32 v170, 16, v217
	v_and_b32_e32 v171, 0xffff0000, v217
	v_pk_mul_f32 v[36:37], v[36:37], v[168:169]
	v_pk_mul_f32 v[38:39], v[38:39], v[170:171]
	s_nop 0
	v_cvt_pk_bf16_f32 v60, v60, v61
	v_cvt_pk_bf16_f32 v61, v62, v63
	v_cvt_pk_bf16_f32 v52, v52, v53
	v_cvt_pk_bf16_f32 v53, v54, v55
	v_cvt_pk_bf16_f32 v44, v44, v45
	v_cvt_pk_bf16_f32 v45, v46, v47
	v_cvt_pk_bf16_f32 v36, v36, v37
	v_cvt_pk_bf16_f32 v37, v38, v39
	global_store_dwordx2 v138, v[60:61], s[4:5] offset:256
	global_store_dwordx2 v138, v[52:53], s[4:5] offset:288
	global_store_dwordx2 v138, v[44:45], s[4:5] offset:320
	global_store_dwordx2 v138, v[36:37], s[4:5] offset:352
	s_waitcnt vmcnt(27)
	v_lshlrev_b32_e32 v168, 16, v218
	v_and_b32_e32 v169, 0xffff0000, v218
	v_lshlrev_b32_e32 v170, 16, v219
	v_and_b32_e32 v171, 0xffff0000, v219
	v_pk_mul_f32 v[56:57], v[56:57], v[168:169]
	v_pk_mul_f32 v[58:59], v[58:59], v[170:171]
	s_waitcnt vmcnt(26)
	v_lshlrev_b32_e32 v168, 16, v220
	v_and_b32_e32 v169, 0xffff0000, v220
	v_lshlrev_b32_e32 v170, 16, v221
	v_and_b32_e32 v171, 0xffff0000, v221
	v_pk_mul_f32 v[48:49], v[48:49], v[168:169]
	v_pk_mul_f32 v[50:51], v[50:51], v[170:171]
	s_waitcnt vmcnt(25)
	v_lshlrev_b32_e32 v168, 16, v222
	v_and_b32_e32 v169, 0xffff0000, v222
	v_lshlrev_b32_e32 v170, 16, v223
	v_and_b32_e32 v171, 0xffff0000, v223
	v_pk_mul_f32 v[40:41], v[40:41], v[168:169]
	v_pk_mul_f32 v[42:43], v[42:43], v[170:171]
	s_waitcnt vmcnt(24)
	v_lshlrev_b32_e32 v168, 16, v224
	v_and_b32_e32 v169, 0xffff0000, v224
	v_lshlrev_b32_e32 v170, 16, v225
	v_and_b32_e32 v171, 0xffff0000, v225
	v_pk_mul_f32 v[32:33], v[32:33], v[168:169]
	v_pk_mul_f32 v[34:35], v[34:35], v[170:171]
	s_nop 0
	v_cvt_pk_bf16_f32 v56, v56, v57
	v_cvt_pk_bf16_f32 v57, v58, v59
	v_cvt_pk_bf16_f32 v48, v48, v49
	v_cvt_pk_bf16_f32 v49, v50, v51
	v_cvt_pk_bf16_f32 v40, v40, v41
	v_cvt_pk_bf16_f32 v41, v42, v43
	v_cvt_pk_bf16_f32 v32, v32, v33
	v_cvt_pk_bf16_f32 v33, v34, v35
	global_store_dwordx2 v139, v[56:57], s[4:5] offset:256
	global_store_dwordx2 v139, v[48:49], s[4:5] offset:288
	global_store_dwordx2 v139, v[40:41], s[4:5] offset:320
	global_store_dwordx2 v139, v[32:33], s[4:5] offset:352
	s_waitcnt vmcnt(23)
	v_lshlrev_b32_e32 v168, 16, v226
	v_and_b32_e32 v169, 0xffff0000, v226
	v_lshlrev_b32_e32 v170, 16, v227
	v_and_b32_e32 v171, 0xffff0000, v227
	v_pk_mul_f32 v[28:29], v[28:29], v[168:169]
	v_pk_mul_f32 v[30:31], v[30:31], v[170:171]
	s_waitcnt vmcnt(22)
	v_lshlrev_b32_e32 v168, 16, v228
	v_and_b32_e32 v169, 0xffff0000, v228
	v_lshlrev_b32_e32 v170, 16, v229
	v_and_b32_e32 v171, 0xffff0000, v229
	v_pk_mul_f32 v[20:21], v[20:21], v[168:169]
	v_pk_mul_f32 v[22:23], v[22:23], v[170:171]
	s_waitcnt vmcnt(21)
	v_lshlrev_b32_e32 v168, 16, v230
	v_and_b32_e32 v169, 0xffff0000, v230
	v_lshlrev_b32_e32 v170, 16, v231
	v_and_b32_e32 v171, 0xffff0000, v231
	v_pk_mul_f32 v[12:13], v[12:13], v[168:169]
	v_pk_mul_f32 v[14:15], v[14:15], v[170:171]
	s_waitcnt vmcnt(20)
; __device__ __forceinline__ float bflo(unsigned u) { return __uint_as_float(u << 16); }
; __device__ __forceinline__ float bfhi(unsigned u) { return __uint_as_float(u & 0xffff0000u); }
; #define WIDE_STORE(BASE, LD, COFF, O) do { if ((m & 1) == 0) opend[n] = (O); \
;                 else *(uint4*)((BASE) + (size_t)tok * (LD) + (ncw - (COFF))) = swap_pair(opend[n], (O)); } while (0)
;     ...
; #pragma unroll
;     for (int a = 0; a < 2; ++a)
; #pragma unroll
;       for (int b = 0; b < 2; ++b)
; #pragma unroll
;         for (int m = 0; m < 4; ++m)
; #pragma unroll
;           for (int n = 0; n < 2; ++n) acc[a][b][m][n] = f32x4{0.f, 0.f, 0.f, 0.f};
;     ...
;               } else if (MODE == 2) {
;                 const u16* gate = (const u16*)outp;
;                 uint2 ga = *(const uint2*)(gate + (size_t)tok * 4096 + nc);
;                 uint2 p1; p1.x = pk2(v[0] * bflo(ga.x), v[1] * bfhi(ga.x)); p1.y = pk2(v[2] * bflo(ga.y), v[3] * bfhi(ga.y));
;                 *(uint2*)((u16*)(ws + OFF_YB) + (size_t)tok * DM + nc) = p1;
;               } else if (MODE == 6) {
;                 const u16* gate = (const u16*)outp;
;                 uint2 gb = *(const uint2*)(gate + (size_t)tok * 4096 + 2048 + nc);
;                 const uint2 p1 = *(const uint2*)((const u16*)(ws + OFF_YB) + (size_t)tok * DM + nc);
;                 uint2 o;
;                 o.x = pk2(bflo(p1.x) + v[0] * bflo(gb.x), bfhi(p1.x) + v[1] * bfhi(gb.x));
;                 o.y = pk2(bflo(p1.y) + v[2] * bflo(gb.y), bfhi(p1.y) + v[3] * bfhi(gb.y));
;                 WIDE_STORE((u16*)(ws + OFF_RB + 128 * MiB), DM, 0, o);
;               } else if (MODE == 3) {
;                 float4 r = ldnt4(xin + (size_t)tok * DM + nc);
;                 uint2 hb; hb.x = pk2(r.x + v[0], r.y + v[1]); hb.y = pk2(r.z + v[2], r.w + v[3]);
;                 WIDE_STORE((u16*)(ws + OFF_RB), DM, 0, hb);
;               } else {
;                 uint2* ph = (uint2*)((u16*)(ws + OFF_RB) + (size_t)tok * DM + nc);
;                 const uint2 hb = *ph;
;                 uint2 o; o.x = pk2(bflo(hb.x) + v[0], bfhi(hb.x) + v[1]); o.y = pk2(bflo(hb.y) + v[2], bfhi(hb.y) + v[3]);
;                 WIDE_STORE((u16*)(ws + OFF_RB), DM, 0, o);
;               }
;     ...
;             }
;     }
;     asm volatile("s_waitcnt vmcnt(0)" ::: "memory");
;     if (has_next && wr == 1) __builtin_amdgcn_s_barrier();
	v_lshlrev_b32_e32 v168, 16, v232
	v_and_b32_e32 v169, 0xffff0000, v232
	v_lshlrev_b32_e32 v170, 16, v233
	v_and_b32_e32 v171, 0xffff0000, v233
	v_pk_mul_f32 v[4:5], v[4:5], v[168:169]
	v_pk_mul_f32 v[6:7], v[6:7], v[170:171]
	s_nop 0
	v_cvt_pk_bf16_f32 v28, v28, v29
	v_cvt_pk_bf16_f32 v29, v30, v31
	v_cvt_pk_bf16_f32 v20, v20, v21
	v_cvt_pk_bf16_f32 v21, v22, v23
	v_cvt_pk_bf16_f32 v12, v12, v13
	v_cvt_pk_bf16_f32 v13, v14, v15
	v_cvt_pk_bf16_f32 v4, v4, v5
	v_cvt_pk_bf16_f32 v5, v6, v7
	global_store_dwordx2 v140, v[28:29], s[4:5] offset:256
	global_store_dwordx2 v140, v[20:21], s[4:5] offset:288
	global_store_dwordx2 v140, v[12:13], s[4:5] offset:320
	global_store_dwordx2 v140, v[4:5], s[4:5] offset:352
	s_waitcnt vmcnt(19)
	v_lshlrev_b32_e32 v168, 16, v234
	v_and_b32_e32 v169, 0xffff0000, v234
	v_lshlrev_b32_e32 v170, 16, v235
	v_and_b32_e32 v171, 0xffff0000, v235
	v_pk_mul_f32 v[24:25], v[24:25], v[168:169]
	v_pk_mul_f32 v[26:27], v[26:27], v[170:171]
	s_waitcnt vmcnt(18)
	v_lshlrev_b32_e32 v168, 16, v236
	v_and_b32_e32 v169, 0xffff0000, v236
	v_lshlrev_b32_e32 v170, 16, v237
	v_and_b32_e32 v171, 0xffff0000, v237
	v_pk_mul_f32 v[16:17], v[16:17], v[168:169]
	v_pk_mul_f32 v[18:19], v[18:19], v[170:171]
	s_waitcnt vmcnt(17)
	v_lshlrev_b32_e32 v168, 16, v238
	v_and_b32_e32 v169, 0xffff0000, v238
	v_lshlrev_b32_e32 v170, 16, v239
	v_and_b32_e32 v171, 0xffff0000, v239
	v_pk_mul_f32 v[8:9], v[8:9], v[168:169]
	v_pk_mul_f32 v[10:11], v[10:11], v[170:171]
	s_waitcnt vmcnt(16)
	v_lshlrev_b32_e32 v168, 16, v240
	v_and_b32_e32 v169, 0xffff0000, v240
	v_lshlrev_b32_e32 v170, 16, v241
	v_and_b32_e32 v171, 0xffff0000, v241
	v_pk_mul_f32 v[0:1], v[0:1], v[168:169]
	v_pk_mul_f32 v[2:3], v[2:3], v[170:171]
	s_nop 0
	v_cvt_pk_bf16_f32 v24, v24, v25
	v_cvt_pk_bf16_f32 v25, v26, v27
	v_cvt_pk_bf16_f32 v16, v16, v17
	v_cvt_pk_bf16_f32 v17, v18, v19
	v_cvt_pk_bf16_f32 v8, v8, v9
	v_cvt_pk_bf16_f32 v9, v10, v11
	v_cvt_pk_bf16_f32 v0, v0, v1
	v_cvt_pk_bf16_f32 v1, v2, v3
	global_store_dwordx2 v141, v[24:25], s[4:5] offset:256
	global_store_dwordx2 v141, v[16:17], s[4:5] offset:288
	global_store_dwordx2 v141, v[8:9], s[4:5] offset:320
	global_store_dwordx2 v141, v[0:1], s[4:5] offset:352
	s_and_b64 s[0:1], s[56:57], s[8:9]
	s_andn2_b64 vcc, exec, s[0:1]
	s_nop 1
	v_mov_b32_e32 v0, 0
	v_mov_b32_e32 v1, v0
	v_mov_b32_e32 v2, v0
	v_mov_b32_e32 v3, v0
	v_mov_b32_e32 v4, v0
	v_mov_b32_e32 v5, v0
	v_mov_b32_e32 v6, v0
	v_mov_b32_e32 v7, v0
	v_mov_b32_e32 v8, v0
	v_mov_b32_e32 v9, v0
	v_mov_b32_e32 v10, v0
	v_mov_b32_e32 v11, v0
	v_mov_b32_e32 v12, v0
	v_mov_b32_e32 v13, v0
	v_mov_b32_e32 v14, v0
	v_mov_b32_e32 v15, v0
	v_mov_b32_e32 v16, v0
	v_mov_b32_e32 v17, v0
	v_mov_b32_e32 v18, v0
	v_mov_b32_e32 v19, v0
	v_mov_b32_e32 v20, v0
	v_mov_b32_e32 v21, v0
	v_mov_b32_e32 v22, v0
	v_mov_b32_e32 v23, v0
	v_mov_b32_e32 v24, v0
	v_mov_b32_e32 v25, v0
	v_mov_b32_e32 v26, v0
	v_mov_b32_e32 v27, v0
	v_mov_b32_e32 v28, v0
	v_mov_b32_e32 v29, v0
	v_mov_b32_e32 v30, v0
	v_mov_b32_e32 v31, v0
	v_mov_b32_e32 v32, v0
	v_mov_b32_e32 v33, v0
	v_mov_b32_e32 v34, v0
	v_mov_b32_e32 v35, v0
	v_mov_b32_e32 v36, v0
	v_mov_b32_e32 v37, v0
	v_mov_b32_e32 v38, v0
	v_mov_b32_e32 v39, v0
	v_mov_b32_e32 v40, v0
	v_mov_b32_e32 v41, v0
	v_mov_b32_e32 v42, v0
	v_mov_b32_e32 v43, v0
	v_mov_b32_e32 v44, v0
	v_mov_b32_e32 v45, v0
	v_mov_b32_e32 v46, v0
	v_mov_b32_e32 v47, v0
	v_mov_b32_e32 v48, v0
	v_mov_b32_e32 v49, v0
	v_mov_b32_e32 v50, v0
	v_mov_b32_e32 v51, v0
	v_mov_b32_e32 v52, v0
	v_mov_b32_e32 v53, v0
	v_mov_b32_e32 v54, v0
	v_mov_b32_e32 v55, v0
	v_mov_b32_e32 v56, v0
	v_mov_b32_e32 v57, v0
	v_mov_b32_e32 v58, v0
	v_mov_b32_e32 v59, v0
	v_mov_b32_e32 v60, v0
	v_mov_b32_e32 v61, v0
	v_mov_b32_e32 v62, v0
	v_mov_b32_e32 v63, v0
	v_mov_b32_e32 v64, v0
	v_mov_b32_e32 v65, v0
	v_mov_b32_e32 v66, v0
	v_mov_b32_e32 v67, v0
	v_mov_b32_e32 v68, v0
	v_mov_b32_e32 v69, v0
	v_mov_b32_e32 v70, v0
	v_mov_b32_e32 v71, v0
	v_mov_b32_e32 v72, v0
	v_mov_b32_e32 v73, v0
	v_mov_b32_e32 v74, v0
	v_mov_b32_e32 v75, v0
	v_mov_b32_e32 v76, v0
	v_mov_b32_e32 v77, v0
	v_mov_b32_e32 v78, v0
	v_mov_b32_e32 v79, v0
	v_mov_b32_e32 v80, v0
	v_mov_b32_e32 v81, v0
	v_mov_b32_e32 v82, v0
	v_mov_b32_e32 v83, v0
	v_mov_b32_e32 v84, v0
	v_mov_b32_e32 v85, v0
	v_mov_b32_e32 v86, v0
	v_mov_b32_e32 v87, v0
	v_mov_b32_e32 v88, v0
	v_mov_b32_e32 v89, v0
	v_mov_b32_e32 v90, v0
	v_mov_b32_e32 v91, v0
	v_mov_b32_e32 v92, v0
	v_mov_b32_e32 v93, v0
	v_mov_b32_e32 v94, v0
	v_mov_b32_e32 v95, v0
	v_mov_b32_e32 v96, v0
	v_mov_b32_e32 v97, v0
	v_mov_b32_e32 v98, v0
	v_mov_b32_e32 v99, v0
	v_mov_b32_e32 v100, v0
	v_mov_b32_e32 v101, v0
	v_mov_b32_e32 v102, v0
	v_mov_b32_e32 v103, v0
	v_mov_b32_e32 v104, v0
	v_mov_b32_e32 v105, v0
	v_mov_b32_e32 v106, v0
	v_mov_b32_e32 v107, v0
	v_mov_b32_e32 v108, v0
	v_mov_b32_e32 v109, v0
	v_mov_b32_e32 v110, v0
	v_mov_b32_e32 v111, v0
	v_mov_b32_e32 v112, v0
	v_mov_b32_e32 v113, v0
	v_mov_b32_e32 v114, v0
	v_mov_b32_e32 v115, v0
	v_mov_b32_e32 v116, v0
	v_mov_b32_e32 v117, v0
	v_mov_b32_e32 v118, v0
	v_mov_b32_e32 v119, v0
	v_mov_b32_e32 v120, v0
	v_mov_b32_e32 v121, v0
	v_mov_b32_e32 v122, v0
	v_mov_b32_e32 v123, v0
	v_mov_b32_e32 v124, v0
	v_mov_b32_e32 v125, v0
	v_mov_b32_e32 v126, v0
	v_mov_b32_e32 v127, v0
	s_waitcnt vmcnt(0)
	s_cbranch_vccnz .LBB0_804
	s_barrier
	s_branch .LBB0_804

; #define STAGE(P_, BASE, br, kt) do { const u16* _gb = (BASE) + (long)(br) * K + (long)(kt) * BK; \
;     _Pragma("unroll") for (int _i = 0; _i < 2; ++_i) { \
;       __builtin_amdgcn_global_load_lds((const unsigned*)(_gb + (long)_i * 64 * K + lane_off), \
;         (unsigned*)((char*)(P_) + lds_wbase + _i * 8192), 16, 0, 0); } } while (0)
; #define LDA(dst, b, h) _Pragma("unroll") for (int m = 0; m < 4; ++m) _Pragma("unroll") for (int k = 0; k < 2; ++k) \
;     dst[m][k] = *reinterpret_cast<const bf16x8*>((char*)SA(b, h) + lds_byte(wr * 64 + m * 16 + fr, k * 32 + fq * 8))
; #define LDB(dst, b, h) _Pragma("unroll") for (int n = 0; n < 2; ++n) _Pragma("unroll") for (int k = 0; k < 2; ++k) \
;     dst[n][k] = *reinterpret_cast<const bf16x8*>((char*)SB(b, h) + lds_byte(wc * 32 + n * 16 + fr, k * 32 + fq * 8))
; #define MMA(ai, bj, At_, Bt_) do { __builtin_amdgcn_s_setprio(1); \
;     _Pragma("unroll") for (int m = 0; m < 4; ++m) _Pragma("unroll") for (int n = 0; n < 2; ++n) _Pragma("unroll") for (int k = 0; k < 2; ++k) \
;       acc[ai][bj][m][n] = __builtin_amdgcn_mfma_f32_16x16x32_bf16(At_[m][k], Bt_[n][k], acc[ai][bj][m][n], 0, 0, 0); \
;     __builtin_amdgcn_s_setprio(0); } while (0)
; #define WAIT_V(n) asm volatile("s_waitcnt vmcnt(" #n ")" ::: "memory")
; #define WAIT_L(n) asm volatile("s_waitcnt lgkmcnt(" #n ")" ::: "memory")
; #define BAR __builtin_amdgcn_s_barrier()
; #define SCHED __builtin_amdgcn_sched_barrier(0)
; #define STAGEW(P_, BASE, cur, nxt, kt_) do { const bool _wr = (kt_) >= nt; \
;     STAGE(P_, BASE, (_wr ? (nxt) : (cur)), (_wr ? (kt_) - nt : (kt_))); } while (0)
; template <int PRE> ...
;     ...
;   for (int t = 0; t < nt; t += 2) {
;     LDB(B0, 0, 0); SCHED; LDA(At, 0, 0); STAGE(SA(1, 1), A, brow + HALF, t + 1);
;     WAIT_L(8); BAR; WAIT_L(0); MMA(0, 0, At, B0); BAR; SCHED;
;     LDB(B1, 0, 1); STAGEW(SB(0, 0), Bt, bcol, bcol_n, t + 2);
;     BAR; WAIT_L(0); MMA(0, 1, At, B1); BAR;
;     LDA(At, 0, 1); STAGEW(SA(0, 0), A, brow, brow_n, t + 2);
;     BAR; WAIT_L(0); MMA(1, 0, At, B0); BAR; SCHED;
;     STAGEW(SB(0, 1), Bt, bcol + HALF, bcol_n + HALF, t + 2);
;     WAIT_V(6); BAR; MMA(1, 1, At, B1); BAR;
.LBB0_825:
	v_add_u32_e32 v142, s81, v159
	ds_read_b128 v[134:137], v142
	ds_read_b128 v[138:141], v142 offset:1024
	ds_read_b128 v[146:149], v142 offset:2048
	ds_read_b128 v[150:153], v142 offset:3072
	s_add_i32 m0, s10, 0xc000
	ds_read_b128 v[154:157], v144
	ds_read_b128 v[168:171], v144 offset:1024
	ds_read_b128 v[172:175], v160
	ds_read_b128 v[176:179], v160 offset:1024
	ds_read_b128 v[180:183], v161
	ds_read_b128 v[184:187], v161 offset:1024
	ds_read_b128 v[188:191], v162
	ds_read_b128 v[192:195], v162 offset:1024
	global_load_lds_dwordx4 v[128:129], off
	v_lshl_add_u64 v[142:143], v[128:129], 0, s[86:87]
	s_add_i32 m0, s10, 0xe000
	s_nop 0
	global_load_lds_dwordx4 v[142:143], off
	s_waitcnt lgkmcnt(8)
	s_barrier
	s_waitcnt lgkmcnt(0)
	v_mfma_f32_16x16x32_bf16 v[124:127], v[154:157], v[134:137], v[124:127]
	v_mfma_f32_16x16x32_bf16 v[120:123], v[154:157], v[146:149], v[120:123]
	v_mfma_f32_16x16x32_bf16 v[116:119], v[172:175], v[134:137], v[116:119]
	v_mfma_f32_16x16x32_bf16 v[112:115], v[172:175], v[146:149], v[112:115]
	v_mfma_f32_16x16x32_bf16 v[108:111], v[180:183], v[134:137], v[108:111]
	v_mfma_f32_16x16x32_bf16 v[104:107], v[180:183], v[146:149], v[104:107]
	v_mfma_f32_16x16x32_bf16 v[100:103], v[188:191], v[134:137], v[100:103]
	v_mfma_f32_16x16x32_bf16 v[96:99], v[188:191], v[146:149], v[96:99]
	v_mfma_f32_16x16x32_bf16 v[124:127], v[168:171], v[138:141], v[124:127]
	v_mfma_f32_16x16x32_bf16 v[120:123], v[168:171], v[150:153], v[120:123]
	v_mfma_f32_16x16x32_bf16 v[116:119], v[176:179], v[138:141], v[116:119]
	v_mfma_f32_16x16x32_bf16 v[112:115], v[176:179], v[150:153], v[112:115]
	v_mfma_f32_16x16x32_bf16 v[108:111], v[184:187], v[138:141], v[108:111]
	v_mfma_f32_16x16x32_bf16 v[104:107], v[184:187], v[150:153], v[104:107]
	v_mfma_f32_16x16x32_bf16 v[100:103], v[192:195], v[138:141], v[100:103]
	v_mfma_f32_16x16x32_bf16 v[96:99], v[192:195], v[150:153], v[96:99]
	s_barrier
	s_add_i32 s36, s1, 2
	s_cmp_lt_u32 s1, 30
	s_cselect_b64 s[2:3], -1, 0
	s_and_b64 vcc, s[2:3], exec
	s_cselect_b32 s4, s27, s29
	s_cselect_b32 s3, 0, 0xffffffe0
	s_cselect_b32 s38, s0, s28
	s_cselect_b32 s40, s34, s31
	s_cselect_b32 s2, s30, s35
	s_ashr_i32 s5, s4, 31
	s_lshl_b64 s[4:5], s[4:5], 12
	s_add_u32 s37, s62, s4
	s_addc_u32 s39, s63, s5
	s_add_i32 s18, s36, s3
	s_lshl_b64 s[4:5], s[18:19], 7
	s_add_u32 s42, s37, s4
	v_add_u32_e32 v142, s82, v159
	s_addc_u32 s43, s39, s5
	s_mov_b32 m0, s11
	ds_read_b128 v[210:213], v142
	ds_read_b128 v[214:217], v142 offset:1024
	ds_read_b128 v[218:221], v142 offset:2048
	ds_read_b128 v[222:225], v142 offset:3072
	v_lshl_add_u64 v[142:143], s[42:43], 0, v[130:131]
	global_load_lds_dwordx4 v[142:143], off
	v_lshl_add_u64 v[142:143], v[142:143], 0, s[86:87]
	s_mov_b32 m0, s12
	s_nop 0
	global_load_lds_dwordx4 v[142:143], off
	s_barrier
	s_waitcnt lgkmcnt(0)
	v_mfma_f32_16x16x32_bf16 v[92:95], v[154:157], v[210:213], v[92:95]
	v_mfma_f32_16x16x32_bf16 v[88:91], v[154:157], v[218:221], v[88:91]
	v_mfma_f32_16x16x32_bf16 v[84:87], v[172:175], v[210:213], v[84:87]
	v_mfma_f32_16x16x32_bf16 v[80:83], v[172:175], v[218:221], v[80:83]
	v_mfma_f32_16x16x32_bf16 v[76:79], v[180:183], v[210:213], v[76:79]
	v_mfma_f32_16x16x32_bf16 v[72:75], v[180:183], v[218:221], v[72:75]
	v_mfma_f32_16x16x32_bf16 v[68:71], v[188:191], v[210:213], v[68:71]
	v_mfma_f32_16x16x32_bf16 v[64:67], v[188:191], v[218:221], v[64:67]
	v_mfma_f32_16x16x32_bf16 v[92:95], v[168:171], v[214:217], v[92:95]
	v_mfma_f32_16x16x32_bf16 v[88:91], v[168:171], v[222:225], v[88:91]
	v_mfma_f32_16x16x32_bf16 v[84:87], v[176:179], v[214:217], v[84:87]
	v_mfma_f32_16x16x32_bf16 v[80:83], v[176:179], v[222:225], v[80:83]
	v_mfma_f32_16x16x32_bf16 v[76:79], v[184:187], v[214:217], v[76:79]
	v_mfma_f32_16x16x32_bf16 v[72:75], v[184:187], v[222:225], v[72:75]
	v_mfma_f32_16x16x32_bf16 v[68:71], v[192:195], v[214:217], v[68:71]
	v_mfma_f32_16x16x32_bf16 v[64:67], v[192:195], v[222:225], v[64:67]
	s_ashr_i32 s39, s38, 31
	s_lshl_b64 s[38:39], s[38:39], 12
	s_add_u32 s3, s69, s38
	s_addc_u32 s18, s70, s39
	s_add_u32 s38, s3, s4
	s_addc_u32 s39, s18, s5
	s_mov_b32 m0, s10
	v_lshl_add_u64 v[142:143], s[38:39], 0, v[130:131]
	s_barrier
	ds_read_b128 v[154:157], v144 offset:16384
	ds_read_b128 v[168:171], v144 offset:17408
	ds_read_b128 v[172:175], v160 offset:16384
	ds_read_b128 v[176:179], v160 offset:17408
	ds_read_b128 v[180:183], v161 offset:16384
	ds_read_b128 v[184:187], v161 offset:17408
	ds_read_b128 v[188:191], v162 offset:16384
	ds_read_b128 v[192:195], v162 offset:17408
	global_load_lds_dwordx4 v[142:143], off
	v_lshl_add_u64 v[142:143], v[142:143], 0, s[86:87]
	s_mov_b32 m0, s13
	s_nop 0
	global_load_lds_dwordx4 v[142:143], off
	s_barrier
	s_waitcnt lgkmcnt(0)
	v_mfma_f32_16x16x32_bf16 v[60:63], v[154:157], v[134:137], v[60:63]
	v_mfma_f32_16x16x32_bf16 v[56:59], v[154:157], v[146:149], v[56:59]
	v_mfma_f32_16x16x32_bf16 v[52:55], v[172:175], v[134:137], v[52:55]
	v_mfma_f32_16x16x32_bf16 v[48:51], v[172:175], v[146:149], v[48:51]
	v_mfma_f32_16x16x32_bf16 v[44:47], v[180:183], v[134:137], v[44:47]
	v_mfma_f32_16x16x32_bf16 v[40:43], v[180:183], v[146:149], v[40:43]
	v_mfma_f32_16x16x32_bf16 v[36:39], v[188:191], v[134:137], v[36:39]
	v_mfma_f32_16x16x32_bf16 v[32:35], v[188:191], v[146:149], v[32:35]
	v_mfma_f32_16x16x32_bf16 v[60:63], v[168:171], v[138:141], v[60:63]
	v_mfma_f32_16x16x32_bf16 v[56:59], v[168:171], v[150:153], v[56:59]
	v_mfma_f32_16x16x32_bf16 v[52:55], v[176:179], v[138:141], v[52:55]
	v_mfma_f32_16x16x32_bf16 v[48:51], v[176:179], v[150:153], v[48:51]
	v_mfma_f32_16x16x32_bf16 v[44:47], v[184:187], v[138:141], v[44:47]
	v_mfma_f32_16x16x32_bf16 v[40:43], v[184:187], v[150:153], v[40:43]
	v_mfma_f32_16x16x32_bf16 v[36:39], v[192:195], v[138:141], v[36:39]
	v_mfma_f32_16x16x32_bf16 v[32:35], v[192:195], v[150:153], v[32:35]
	s_barrier
; #define LDA(dst, b, h) _Pragma("unroll") for (int m = 0; m < 4; ++m) _Pragma("unroll") for (int k = 0; k < 2; ++k) \
;     dst[m][k] = *reinterpret_cast<const bf16x8*>((char*)SA(b, h) + lds_byte(wr * 64 + m * 16 + fr, k * 32 + fq * 8))
; #define LDB(dst, b, h) _Pragma("unroll") for (int n = 0; n < 2; ++n) _Pragma("unroll") for (int k = 0; k < 2; ++k) \
;     dst[n][k] = *reinterpret_cast<const bf16x8*>((char*)SB(b, h) + lds_byte(wc * 32 + n * 16 + fr, k * 32 + fq * 8))
; #define MMA(ai, bj, At_, Bt_) do { __builtin_amdgcn_s_setprio(1); \
;     _Pragma("unroll") for (int m = 0; m < 4; ++m) _Pragma("unroll") for (int n = 0; n < 2; ++n) _Pragma("unroll") for (int k = 0; k < 2; ++k) \
;       acc[ai][bj][m][n] = __builtin_amdgcn_mfma_f32_16x16x32_bf16(At_[m][k], Bt_[n][k], acc[ai][bj][m][n], 0, 0, 0); \
;     __builtin_amdgcn_s_setprio(0); } while (0)
; #define WAIT_V(n) asm volatile("s_waitcnt vmcnt(" #n ")" ::: "memory")
; #define WAIT_L(n) asm volatile("s_waitcnt lgkmcnt(" #n ")" ::: "memory")
; #define BAR __builtin_amdgcn_s_barrier()
; #define SCHED __builtin_amdgcn_sched_barrier(0)
; #define STAGEW(P_, BASE, cur, nxt, kt_) do { const bool _wr = (kt_) >= nt; \
;     STAGE(P_, BASE, (_wr ? (nxt) : (cur)), (_wr ? (kt_) - nt : (kt_))); } while (0)
; template <int PRE> ...
;     ...
;     BAR; WAIT_L(0); MMA(1, 0, At, B0); BAR; SCHED;
;     STAGEW(SB(0, 1), Bt, bcol + HALF, bcol_n + HALF, t + 2);
;     WAIT_V(6); BAR; MMA(1, 1, At, B1); BAR;
;     LDB(B0, 1, 0); SCHED; LDA(At, 1, 0); STAGEW(SA(0, 1), A, brow + HALF, brow_n + HALF, t + 2);
;     WAIT_L(8); BAR; WAIT_L(0); MMA(0, 0, At, B0); BAR; SCHED;
;     LDB(B1, 1, 1); STAGEW(SB(1, 0), Bt, bcol, bcol_n, t + 3);
;     BAR; WAIT_L(0); MMA(0, 1, At, B1); BAR;
;     LDA(At, 1, 1); STAGEW(SA(1, 0), A, brow, brow_n, t + 3);
	s_ashr_i32 s41, s40, 31
	s_lshl_b64 s[38:39], s[40:41], 12
	s_add_u32 s3, s62, s38
	s_addc_u32 s18, s63, s39
	s_add_u32 s38, s3, s4
	s_addc_u32 s39, s18, s5
	s_mov_b32 m0, s14
	v_lshl_add_u64 v[134:135], s[38:39], 0, v[130:131]
	global_load_lds_dwordx4 v[134:135], off
	v_lshl_add_u64 v[134:135], v[134:135], 0, s[86:87]
	s_mov_b32 m0, s15
	s_nop 0
	global_load_lds_dwordx4 v[134:135], off
	s_waitcnt vmcnt(6)
	s_barrier
	v_mfma_f32_16x16x32_bf16 v[28:31], v[154:157], v[210:213], v[28:31]
	v_mfma_f32_16x16x32_bf16 v[24:27], v[154:157], v[218:221], v[24:27]
	v_mfma_f32_16x16x32_bf16 v[20:23], v[172:175], v[210:213], v[20:23]
	v_mfma_f32_16x16x32_bf16 v[16:19], v[172:175], v[218:221], v[16:19]
	v_mfma_f32_16x16x32_bf16 v[12:15], v[180:183], v[210:213], v[12:15]
	v_mfma_f32_16x16x32_bf16 v[8:11], v[180:183], v[218:221], v[8:11]
	v_mfma_f32_16x16x32_bf16 v[4:7], v[188:191], v[210:213], v[4:7]
	v_mfma_f32_16x16x32_bf16 v[0:3], v[188:191], v[218:221], v[0:3]
	v_mfma_f32_16x16x32_bf16 v[28:31], v[168:171], v[214:217], v[28:31]
	v_mfma_f32_16x16x32_bf16 v[24:27], v[168:171], v[222:225], v[24:27]
	v_mfma_f32_16x16x32_bf16 v[20:23], v[176:179], v[214:217], v[20:23]
	v_mfma_f32_16x16x32_bf16 v[16:19], v[176:179], v[222:225], v[16:19]
	v_mfma_f32_16x16x32_bf16 v[12:15], v[184:187], v[214:217], v[12:15]
	v_mfma_f32_16x16x32_bf16 v[8:11], v[184:187], v[222:225], v[8:11]
	v_mfma_f32_16x16x32_bf16 v[4:7], v[192:195], v[214:217], v[4:7]
	v_mfma_f32_16x16x32_bf16 v[0:3], v[192:195], v[222:225], v[0:3]
	v_add_u32_e32 v142, s83, v159
	s_barrier
	ds_read_b128 v[134:137], v142
	ds_read_b128 v[138:141], v142 offset:1024
	ds_read_b128 v[146:149], v142 offset:2048
	ds_read_b128 v[150:153], v142 offset:3072
	s_ashr_i32 s3, s2, 31
	s_lshl_b64 s[2:3], s[2:3], 12
	s_add_u32 s2, s69, s2
	s_addc_u32 s3, s70, s3
	s_add_u32 s2, s2, s4
	s_addc_u32 s3, s3, s5
	s_mov_b32 m0, s16
	v_lshl_add_u64 v[142:143], s[2:3], 0, v[130:131]
	ds_read_b128 v[154:157], v144 offset:32768
	ds_read_b128 v[168:171], v144 offset:33792
	ds_read_b128 v[172:175], v160 offset:32768
	ds_read_b128 v[176:179], v160 offset:33792
	ds_read_b128 v[180:183], v161 offset:32768
	ds_read_b128 v[184:187], v161 offset:33792
	ds_read_b128 v[188:191], v162 offset:32768
	ds_read_b128 v[192:195], v162 offset:33792
	global_load_lds_dwordx4 v[142:143], off
	v_lshl_add_u64 v[142:143], v[142:143], 0, s[86:87]
	s_mov_b32 m0, s17
	s_nop 0
	global_load_lds_dwordx4 v[142:143], off
	s_waitcnt lgkmcnt(8)
	s_barrier
	s_waitcnt lgkmcnt(0)
	v_mfma_f32_16x16x32_bf16 v[124:127], v[154:157], v[134:137], v[124:127]
	v_mfma_f32_16x16x32_bf16 v[120:123], v[154:157], v[146:149], v[120:123]
	v_mfma_f32_16x16x32_bf16 v[116:119], v[172:175], v[134:137], v[116:119]
	v_mfma_f32_16x16x32_bf16 v[112:115], v[172:175], v[146:149], v[112:115]
	v_mfma_f32_16x16x32_bf16 v[108:111], v[180:183], v[134:137], v[108:111]
	v_mfma_f32_16x16x32_bf16 v[104:107], v[180:183], v[146:149], v[104:107]
	v_mfma_f32_16x16x32_bf16 v[100:103], v[188:191], v[134:137], v[100:103]
	v_mfma_f32_16x16x32_bf16 v[96:99], v[188:191], v[146:149], v[96:99]
	v_mfma_f32_16x16x32_bf16 v[124:127], v[168:171], v[138:141], v[124:127]
	v_mfma_f32_16x16x32_bf16 v[120:123], v[168:171], v[150:153], v[120:123]
	v_mfma_f32_16x16x32_bf16 v[116:119], v[176:179], v[138:141], v[116:119]
	v_mfma_f32_16x16x32_bf16 v[112:115], v[176:179], v[150:153], v[112:115]
	v_mfma_f32_16x16x32_bf16 v[108:111], v[184:187], v[138:141], v[108:111]
	v_mfma_f32_16x16x32_bf16 v[104:107], v[184:187], v[150:153], v[104:107]
	v_mfma_f32_16x16x32_bf16 v[100:103], v[192:195], v[138:141], v[100:103]
	v_mfma_f32_16x16x32_bf16 v[96:99], v[192:195], v[150:153], v[96:99]
	s_barrier
	s_cmp_lt_u32 s1, 29
	s_cselect_b32 s2, s27, s29
	s_cselect_b32 s5, 0, 0xffffffe0
	s_cselect_b32 s4, s0, s28
	s_cselect_b32 s38, s34, s31
	s_ashr_i32 s3, s2, 31
	s_lshl_b64 s[2:3], s[2:3], 12
	s_add_u32 s37, s62, s2
	s_addc_u32 s39, s63, s3
	s_add_i32 s1, s5, s1
	s_add_i32 s18, s1, 3
	s_lshl_b64 s[2:3], s[18:19], 7
	s_add_u32 s40, s37, s2
	v_add_u32_e32 v142, s84, v159
	s_addc_u32 s41, s39, s3
	s_mov_b32 m0, s20
	ds_read_b128 v[210:213], v142
	ds_read_b128 v[214:217], v142 offset:1024
	ds_read_b128 v[218:221], v142 offset:2048
	ds_read_b128 v[222:225], v142 offset:3072
	v_lshl_add_u64 v[142:143], s[40:41], 0, v[130:131]
	global_load_lds_dwordx4 v[142:143], off
	v_lshl_add_u64 v[142:143], v[142:143], 0, s[86:87]
	s_mov_b32 m0, s21
	s_nop 0
	global_load_lds_dwordx4 v[142:143], off
	s_barrier
	s_waitcnt lgkmcnt(0)
	v_mfma_f32_16x16x32_bf16 v[92:95], v[154:157], v[210:213], v[92:95]
	v_mfma_f32_16x16x32_bf16 v[88:91], v[154:157], v[218:221], v[88:91]
	v_mfma_f32_16x16x32_bf16 v[84:87], v[172:175], v[210:213], v[84:87]
	v_mfma_f32_16x16x32_bf16 v[80:83], v[172:175], v[218:221], v[80:83]
	v_mfma_f32_16x16x32_bf16 v[76:79], v[180:183], v[210:213], v[76:79]
	v_mfma_f32_16x16x32_bf16 v[72:75], v[180:183], v[218:221], v[72:75]
	v_mfma_f32_16x16x32_bf16 v[68:71], v[188:191], v[210:213], v[68:71]
	v_mfma_f32_16x16x32_bf16 v[64:67], v[188:191], v[218:221], v[64:67]
	v_mfma_f32_16x16x32_bf16 v[92:95], v[168:171], v[214:217], v[92:95]
	v_mfma_f32_16x16x32_bf16 v[88:91], v[168:171], v[222:225], v[88:91]
	v_mfma_f32_16x16x32_bf16 v[84:87], v[176:179], v[214:217], v[84:87]
	v_mfma_f32_16x16x32_bf16 v[80:83], v[176:179], v[222:225], v[80:83]
	v_mfma_f32_16x16x32_bf16 v[76:79], v[184:187], v[214:217], v[76:79]
	v_mfma_f32_16x16x32_bf16 v[72:75], v[184:187], v[222:225], v[72:75]
	v_mfma_f32_16x16x32_bf16 v[68:71], v[192:195], v[214:217], v[68:71]
	v_mfma_f32_16x16x32_bf16 v[64:67], v[192:195], v[222:225], v[64:67]
	s_ashr_i32 s5, s4, 31
	s_lshl_b64 s[4:5], s[4:5], 12
	s_add_u32 s1, s69, s4
	s_addc_u32 s5, s70, s5
	s_add_u32 s4, s1, s2
	s_addc_u32 s5, s5, s3
	s_mov_b32 m0, s22
	v_lshl_add_u64 v[142:143], s[4:5], 0, v[130:131]
	s_barrier
; #define WAIT_V(n) asm volatile("s_waitcnt vmcnt(" #n ")" ::: "memory")
; template <int PRE> ...
;     ...
;     LDA(At, 1, 1); STAGEW(SA(1, 0), A, brow, brow_n, t + 3);
;     BAR; WAIT_L(0); MMA(1, 0, At, B0); BAR; SCHED;
;     STAGEW(SB(1, 1), Bt, bcol + HALF, bcol_n + HALF, t + 3);
;     WAIT_V(6); BAR; MMA(1, 1, At, B1); BAR;
;   }
;   if (wr == 0) BAR;
;     ...
;               const int nc = brow + ai * 128 + wr * 64 + m * 16 + fq * 4;
;               const int tok = bcol + bj * 128 + wc * 32 + n * 16 + fr;
;               const int ncw = brow + ai * 128 + wr * 64 + ((m & ~1) + (fq & 1)) * 16 + (fq & ~1) * 4;
;     ...
;               f32x4 v = acc[ai][bj][m][n];
;               if (MODE == 0) {
;                 if (tn == 52) {
;                   if (ai == 0) *(float4*)((float*)(ws + OFF_DTR) + (size_t)tok * 128 + (nc - 13312)) = make_float4(v[0], v[1], v[2], v[3]);
;                 } else {
;                   u16* dst; int ld, c0;
;                   if (tn < 16) { dst = (u16*)(ws + OFF_Z); ld = 4096; c0 = 0; }
;                   else if (tn < 40) { dst = (u16*)(ws + OFF_RA); ld = 6144; c0 = 4096; }
;                   else if (tn < 48) { dst = (u16*)(ws + OFF_Q); ld = 2048; c0 = 10240; }
;                   else if (tn < 50) { dst = (u16*)(ws + OFF_K); ld = 512; c0 = 12288; }
;                   else { dst = (u16*)(ws + OFF_V); ld = 512; c0 = 12800; }
;                   uint2 o; o.x = pk2(v[0], v[1]); o.y = pk2(v[2], v[3]);
;                   WIDE_STORE(dst, ld, c0, o);
;                 }
;               } else if (MODE == 1) {
;                 uint2 o; o.x = pk2(sigmoidf_(v[0]), sigmoidf_(v[1])); o.y = pk2(sigmoidf_(v[2]), sigmoidf_(v[3]));
;                 WIDE_STORE((u16*)outp, 4096, 0, o);
;               } else if (MODE == 2) {
;                 const u16* gate = (const u16*)outp;
;                 uint2 ga = *(const uint2*)(gate + (size_t)tok * 4096 + nc);
;                 uint2 p1; p1.x = pk2(v[0] * bflo(ga.x), v[1] * bfhi(ga.x)); p1.y = pk2(v[2] * bflo(ga.y), v[3] * bfhi(ga.y));
;                 *(uint2*)((u16*)(ws + OFF_YB) + (size_t)tok * DM + nc) = p1;
;               } else if (MODE == 6) {
;                 const u16* gate = (const u16*)outp;
;                 uint2 gb = *(const uint2*)(gate + (size_t)tok * 4096 + 2048 + nc);
;                 const uint2 p1 = *(const uint2*)((const u16*)(ws + OFF_YB) + (size_t)tok * DM + nc);
;                 uint2 o;
	ds_read_b128 v[154:157], v144 offset:49152
	ds_read_b128 v[168:171], v144 offset:50176
	ds_read_b128 v[172:175], v160 offset:49152
	ds_read_b128 v[176:179], v160 offset:50176
	ds_read_b128 v[180:183], v161 offset:49152
	ds_read_b128 v[184:187], v161 offset:50176
	ds_read_b128 v[188:191], v162 offset:49152
	ds_read_b128 v[192:195], v162 offset:50176
	global_load_lds_dwordx4 v[142:143], off
	v_lshl_add_u64 v[142:143], v[142:143], 0, s[86:87]
	s_mov_b32 m0, s23
	s_nop 0
	global_load_lds_dwordx4 v[142:143], off
	s_barrier
	s_waitcnt lgkmcnt(0)
	v_mfma_f32_16x16x32_bf16 v[60:63], v[154:157], v[134:137], v[60:63]
	v_mfma_f32_16x16x32_bf16 v[56:59], v[154:157], v[146:149], v[56:59]
	v_mfma_f32_16x16x32_bf16 v[52:55], v[172:175], v[134:137], v[52:55]
	v_mfma_f32_16x16x32_bf16 v[48:51], v[172:175], v[146:149], v[48:51]
	v_mfma_f32_16x16x32_bf16 v[44:47], v[180:183], v[134:137], v[44:47]
	v_mfma_f32_16x16x32_bf16 v[40:43], v[180:183], v[146:149], v[40:43]
	v_mfma_f32_16x16x32_bf16 v[36:39], v[188:191], v[134:137], v[36:39]
	v_mfma_f32_16x16x32_bf16 v[32:35], v[188:191], v[146:149], v[32:35]
	v_mfma_f32_16x16x32_bf16 v[60:63], v[168:171], v[138:141], v[60:63]
	v_mfma_f32_16x16x32_bf16 v[56:59], v[168:171], v[150:153], v[56:59]
	v_mfma_f32_16x16x32_bf16 v[52:55], v[176:179], v[138:141], v[52:55]
	v_mfma_f32_16x16x32_bf16 v[48:51], v[176:179], v[150:153], v[48:51]
	v_mfma_f32_16x16x32_bf16 v[44:47], v[184:187], v[138:141], v[44:47]
	v_mfma_f32_16x16x32_bf16 v[40:43], v[184:187], v[150:153], v[40:43]
	v_mfma_f32_16x16x32_bf16 v[36:39], v[192:195], v[138:141], v[36:39]
	v_mfma_f32_16x16x32_bf16 v[32:35], v[192:195], v[150:153], v[32:35]
	s_barrier
	s_ashr_i32 s39, s38, 31
	s_lshl_b64 s[4:5], s[38:39], 12
	s_add_u32 s1, s62, s4
	s_addc_u32 s4, s63, s5
	s_add_u32 s2, s1, s2
	s_addc_u32 s3, s4, s3
	s_mov_b32 m0, s24
	v_lshl_add_u64 v[134:135], s[2:3], 0, v[130:131]
	global_load_lds_dwordx4 v[134:135], off
	v_lshl_add_u64 v[134:135], v[134:135], 0, s[86:87]
	s_mov_b32 m0, s25
	s_nop 0
	global_load_lds_dwordx4 v[134:135], off
	s_waitcnt vmcnt(6)
	s_barrier
	v_mfma_f32_16x16x32_bf16 v[28:31], v[154:157], v[210:213], v[28:31]
	v_mfma_f32_16x16x32_bf16 v[24:27], v[154:157], v[218:221], v[24:27]
	v_mfma_f32_16x16x32_bf16 v[20:23], v[172:175], v[210:213], v[20:23]
	v_mfma_f32_16x16x32_bf16 v[16:19], v[172:175], v[218:221], v[16:19]
	v_mfma_f32_16x16x32_bf16 v[12:15], v[180:183], v[210:213], v[12:15]
	v_mfma_f32_16x16x32_bf16 v[8:11], v[180:183], v[218:221], v[8:11]
	v_mfma_f32_16x16x32_bf16 v[4:7], v[188:191], v[210:213], v[4:7]
	v_mfma_f32_16x16x32_bf16 v[0:3], v[188:191], v[218:221], v[0:3]
	v_mfma_f32_16x16x32_bf16 v[28:31], v[168:171], v[214:217], v[28:31]
	v_mfma_f32_16x16x32_bf16 v[24:27], v[168:171], v[222:225], v[24:27]
	v_mfma_f32_16x16x32_bf16 v[20:23], v[176:179], v[214:217], v[20:23]
	v_mfma_f32_16x16x32_bf16 v[16:19], v[176:179], v[222:225], v[16:19]
	v_mfma_f32_16x16x32_bf16 v[12:15], v[184:187], v[214:217], v[12:15]
	v_mfma_f32_16x16x32_bf16 v[8:11], v[184:187], v[222:225], v[8:11]
	v_mfma_f32_16x16x32_bf16 v[4:7], v[192:195], v[214:217], v[4:7]
	v_mfma_f32_16x16x32_bf16 v[0:3], v[192:195], v[222:225], v[0:3]
	v_lshl_add_u64 v[128:129], v[128:129], 0, s[46:47]
	s_mov_b32 s1, s36
	s_barrier
	s_cbranch_vccnz .LBB0_825
	v_readlane_b32 s34, v243, 2
	v_readlane_b32 s28, v243, 57
	v_readlane_b32 s29, v243, 58
	v_readlane_b32 s4, v244, 3
	v_readlane_b32 s5, v244, 4
	s_add_i32 s0, s0, s49
	v_and_b32_e32 v172, 15, v158
	v_or_b32_e32 v172, s54, v172
	v_or_b32_e32 v172, s27, v172
	v_lshrrev_b32_e32 v173, 2, v158
	v_and_b32_e32 v174, -4, v173
	v_add_u32_e32 v174, s0, v174
	v_and_b32_e32 v173, -8, v173
	v_and_b32_e32 v175, 16, v158
	v_add3_u32 v173, v173, v175, s0
	v_lshlrev_b32_e32 v175, 13, v172
	v_lshl_add_u32 v134, v174, 1, v175
	v_add_u32_e32 v134, 0x1000, v134
	v_add_u32_e32 v135, 0x20000, v134
	v_add_u32_e32 v136, 0x100000, v134
	v_add_u32_e32 v137, 0x120000, v134
	v_lshlrev_b32_e32 v175, 12, v172
	v_lshl_add_u32 v138, v174, 1, v175
	v_add_u32_e32 v139, 0x10000, v138
	v_add_u32_e32 v140, 0x80000, v138
	v_add_u32_e32 v141, 0x90000, v138
	v_lshlrev_b32_e32 v175, 12, v172
	v_lshl_add_u32 v190, v173, 1, v175
	v_add_u32_e32 v191, 0x10000, v190
	v_add_u32_e32 v192, 0x80000, v190
	v_add_u32_e32 v193, 0x90000, v190
	global_load_dwordx2 v[210:211], v134, s[28:29] offset:0
	global_load_dwordx2 v[212:213], v138, s[4:5] offset:0
	global_load_dwordx2 v[214:215], v134, s[28:29] offset:32
	global_load_dwordx2 v[216:217], v138, s[4:5] offset:32
	global_load_dwordx2 v[218:219], v134, s[28:29] offset:64
	global_load_dwordx2 v[220:221], v138, s[4:5] offset:64
	global_load_dwordx2 v[222:223], v134, s[28:29] offset:96
	global_load_dwordx2 v[224:225], v138, s[4:5] offset:96
	global_load_dwordx2 v[226:227], v135, s[28:29] offset:0
	global_load_dwordx2 v[228:229], v139, s[4:5] offset:0
	global_load_dwordx2 v[230:231], v135, s[28:29] offset:32
	global_load_dwordx2 v[232:233], v139, s[4:5] offset:32
	global_load_dwordx2 v[234:235], v135, s[28:29] offset:64
	global_load_dwordx2 v[236:237], v139, s[4:5] offset:64
	global_load_dwordx2 v[238:239], v135, s[28:29] offset:96
	global_load_dwordx2 v[240:241], v139, s[4:5] offset:96
	s_andn2_b64 vcc, exec, s[58:59]
	v_readlane_b32 s31, v244, 61
	v_readlane_b32 s35, v243, 3
	s_cbranch_vccnz .LBB0_828
	s_barrier
; __device__ __forceinline__ float bflo(unsigned u) { return __uint_as_float(u << 16); }
; __device__ __forceinline__ float bfhi(unsigned u) { return __uint_as_float(u & 0xffff0000u); }
; #define WIDE_STORE(BASE, LD, COFF, O) do { if ((m & 1) == 0) opend[n] = (O); \
;                 else *(uint4*)((BASE) + (size_t)tok * (LD) + (ncw - (COFF))) = swap_pair(opend[n], (O)); } while (0)
; __device__ __forceinline__ uint4 swap_pair(const uint2 a, const uint2 b) {
;   const auto rx = __builtin_amdgcn_permlane16_swap(a.x, b.x, false, false);
;   const auto ry = __builtin_amdgcn_permlane16_swap(a.y, b.y, false, false);
;   return make_uint4(rx[0], ry[0], rx[1], ry[1]);
; }
;     ...
;               } else if (MODE == 6) {
;                 const u16* gate = (const u16*)outp;
;                 uint2 gb = *(const uint2*)(gate + (size_t)tok * 4096 + 2048 + nc);
;                 const uint2 p1 = *(const uint2*)((const u16*)(ws + OFF_YB) + (size_t)tok * DM + nc);
;                 uint2 o;
;                 o.x = pk2(bflo(p1.x) + v[0] * bflo(gb.x), bfhi(p1.x) + v[1] * bfhi(gb.x));
;                 o.y = pk2(bflo(p1.y) + v[2] * bflo(gb.y), bfhi(p1.y) + v[3] * bfhi(gb.y));
;                 WIDE_STORE((u16*)(ws + OFF_RB + 128 * MiB), DM, 0, o);
.LBB0_828:
	s_waitcnt vmcnt(14)
	v_lshlrev_b32_e32 v168, 16, v210
	v_and_b32_e32 v169, 0xffff0000, v210
	v_lshlrev_b32_e32 v176, 16, v212
	v_and_b32_e32 v177, 0xffff0000, v212
	v_pk_fma_f32 v[124:125], v[124:125], v[168:169], v[176:177]
	v_lshlrev_b32_e32 v170, 16, v211
	v_and_b32_e32 v171, 0xffff0000, v211
	v_lshlrev_b32_e32 v178, 16, v213
	v_and_b32_e32 v179, 0xffff0000, v213
	v_pk_fma_f32 v[126:127], v[126:127], v[170:171], v[178:179]
	global_load_dwordx2 v[210:211], v136, s[28:29] offset:0
	global_load_dwordx2 v[212:213], v140, s[4:5] offset:0
	s_waitcnt vmcnt(14)
	v_lshlrev_b32_e32 v168, 16, v214
	v_and_b32_e32 v169, 0xffff0000, v214
	v_lshlrev_b32_e32 v176, 16, v216
	v_and_b32_e32 v177, 0xffff0000, v216
	v_pk_fma_f32 v[116:117], v[116:117], v[168:169], v[176:177]
	v_lshlrev_b32_e32 v170, 16, v215
	v_and_b32_e32 v171, 0xffff0000, v215
	v_lshlrev_b32_e32 v178, 16, v217
	v_and_b32_e32 v179, 0xffff0000, v217
	v_pk_fma_f32 v[118:119], v[118:119], v[170:171], v[178:179]
	global_load_dwordx2 v[214:215], v136, s[28:29] offset:32
	global_load_dwordx2 v[216:217], v140, s[4:5] offset:32
	s_waitcnt vmcnt(14)
	v_lshlrev_b32_e32 v168, 16, v218
	v_and_b32_e32 v169, 0xffff0000, v218
	v_lshlrev_b32_e32 v176, 16, v220
	v_and_b32_e32 v177, 0xffff0000, v220
	v_pk_fma_f32 v[108:109], v[108:109], v[168:169], v[176:177]
	v_lshlrev_b32_e32 v170, 16, v219
	v_and_b32_e32 v171, 0xffff0000, v219
	v_lshlrev_b32_e32 v178, 16, v221
	v_and_b32_e32 v179, 0xffff0000, v221
	v_pk_fma_f32 v[110:111], v[110:111], v[170:171], v[178:179]
	global_load_dwordx2 v[218:219], v136, s[28:29] offset:64
	global_load_dwordx2 v[220:221], v140, s[4:5] offset:64
	s_waitcnt vmcnt(14)
	v_lshlrev_b32_e32 v168, 16, v222
	v_and_b32_e32 v169, 0xffff0000, v222
	v_lshlrev_b32_e32 v176, 16, v224
	v_and_b32_e32 v177, 0xffff0000, v224
	v_pk_fma_f32 v[100:101], v[100:101], v[168:169], v[176:177]
	v_lshlrev_b32_e32 v170, 16, v223
	v_and_b32_e32 v171, 0xffff0000, v223
	v_lshlrev_b32_e32 v178, 16, v225
	v_and_b32_e32 v179, 0xffff0000, v225
	v_pk_fma_f32 v[102:103], v[102:103], v[170:171], v[178:179]
	global_load_dwordx2 v[222:223], v136, s[28:29] offset:96
	global_load_dwordx2 v[224:225], v140, s[4:5] offset:96
	s_nop 0
	v_cvt_pk_bf16_f32 v124, v124, v125
	v_cvt_pk_bf16_f32 v125, v126, v127
	v_cvt_pk_bf16_f32 v126, v116, v117
	v_cvt_pk_bf16_f32 v127, v118, v119
	v_cvt_pk_bf16_f32 v108, v108, v109
	v_cvt_pk_bf16_f32 v109, v110, v111
	v_cvt_pk_bf16_f32 v110, v100, v101
	v_cvt_pk_bf16_f32 v111, v102, v103
	s_nop 1
	v_permlane16_swap_b32_e32 v124, v126
	v_permlane16_swap_b32_e32 v125, v127
	v_permlane16_swap_b32_e32 v108, v110
	v_permlane16_swap_b32_e32 v109, v111
	global_store_dwordx4 v190, v[124:127], s[72:73] offset:0
	global_store_dwordx4 v190, v[108:111], s[72:73] offset:64
	s_waitcnt vmcnt(16)
	v_lshlrev_b32_e32 v168, 16, v226
	v_and_b32_e32 v169, 0xffff0000, v226
	v_lshlrev_b32_e32 v176, 16, v228
	v_and_b32_e32 v177, 0xffff0000, v228
	v_pk_fma_f32 v[120:121], v[120:121], v[168:169], v[176:177]
	v_lshlrev_b32_e32 v170, 16, v227
	v_and_b32_e32 v171, 0xffff0000, v227
	v_lshlrev_b32_e32 v178, 16, v229
	v_and_b32_e32 v179, 0xffff0000, v229
	v_pk_fma_f32 v[122:123], v[122:123], v[170:171], v[178:179]
	global_load_dwordx2 v[226:227], v137, s[28:29] offset:0
	global_load_dwordx2 v[228:229], v141, s[4:5] offset:0
	s_waitcnt vmcnt(16)
	v_lshlrev_b32_e32 v168, 16, v230
	v_and_b32_e32 v169, 0xffff0000, v230
	v_lshlrev_b32_e32 v176, 16, v232
	v_and_b32_e32 v177, 0xffff0000, v232
	v_pk_fma_f32 v[112:113], v[112:113], v[168:169], v[176:177]
	v_lshlrev_b32_e32 v170, 16, v231
	v_and_b32_e32 v171, 0xffff0000, v231
	v_lshlrev_b32_e32 v178, 16, v233
	v_and_b32_e32 v179, 0xffff0000, v233
	v_pk_fma_f32 v[114:115], v[114:115], v[170:171], v[178:179]
	global_load_dwordx2 v[230:231], v137, s[28:29] offset:32
	global_load_dwordx2 v[232:233], v141, s[4:5] offset:32
	s_waitcnt vmcnt(16)
	v_lshlrev_b32_e32 v168, 16, v234
	v_and_b32_e32 v169, 0xffff0000, v234
	v_lshlrev_b32_e32 v176, 16, v236
	v_and_b32_e32 v177, 0xffff0000, v236
	v_pk_fma_f32 v[104:105], v[104:105], v[168:169], v[176:177]
	v_lshlrev_b32_e32 v170, 16, v235
	v_and_b32_e32 v171, 0xffff0000, v235
	v_lshlrev_b32_e32 v178, 16, v237
	v_and_b32_e32 v179, 0xffff0000, v237
	v_pk_fma_f32 v[106:107], v[106:107], v[170:171], v[178:179]
	global_load_dwordx2 v[234:235], v137, s[28:29] offset:64
	global_load_dwordx2 v[236:237], v141, s[4:5] offset:64
	s_waitcnt vmcnt(16)
	v_lshlrev_b32_e32 v168, 16, v238
	v_and_b32_e32 v169, 0xffff0000, v238
	v_lshlrev_b32_e32 v176, 16, v240
	v_and_b32_e32 v177, 0xffff0000, v240
	v_pk_fma_f32 v[96:97], v[96:97], v[168:169], v[176:177]
	v_lshlrev_b32_e32 v170, 16, v239
	v_and_b32_e32 v171, 0xffff0000, v239
	v_lshlrev_b32_e32 v178, 16, v241
	v_and_b32_e32 v179, 0xffff0000, v241
	v_pk_fma_f32 v[98:99], v[98:99], v[170:171], v[178:179]
	global_load_dwordx2 v[238:239], v137, s[28:29] offset:96
	global_load_dwordx2 v[240:241], v141, s[4:5] offset:96
	s_nop 0
	v_cvt_pk_bf16_f32 v120, v120, v121
	v_cvt_pk_bf16_f32 v121, v122, v123
	v_cvt_pk_bf16_f32 v122, v112, v113
	v_cvt_pk_bf16_f32 v123, v114, v115
	v_cvt_pk_bf16_f32 v104, v104, v105
	v_cvt_pk_bf16_f32 v105, v106, v107
	v_cvt_pk_bf16_f32 v106, v96, v97
	v_cvt_pk_bf16_f32 v107, v98, v99
	s_nop 1
	v_permlane16_swap_b32_e32 v120, v122
	v_permlane16_swap_b32_e32 v121, v123
	v_permlane16_swap_b32_e32 v104, v106
	v_permlane16_swap_b32_e32 v105, v107
	global_store_dwordx4 v191, v[120:123], s[72:73] offset:0
	global_store_dwordx4 v191, v[104:107], s[72:73] offset:64
	s_waitcnt vmcnt(18)
; __device__ __forceinline__ float bflo(unsigned u) { return __uint_as_float(u << 16); }
; __device__ __forceinline__ float bfhi(unsigned u) { return __uint_as_float(u & 0xffff0000u); }
; #define WIDE_STORE(BASE, LD, COFF, O) do { if ((m & 1) == 0) opend[n] = (O); \
;                 else *(uint4*)((BASE) + (size_t)tok * (LD) + (ncw - (COFF))) = swap_pair(opend[n], (O)); } while (0)
; __device__ __forceinline__ uint4 swap_pair(const uint2 a, const uint2 b) {
;   const auto rx = __builtin_amdgcn_permlane16_swap(a.x, b.x, false, false);
;   const auto ry = __builtin_amdgcn_permlane16_swap(a.y, b.y, false, false);
;   return make_uint4(rx[0], ry[0], rx[1], ry[1]);
; }
;     ...
;               } else if (MODE == 6) {
;                 const u16* gate = (const u16*)outp;
;                 uint2 gb = *(const uint2*)(gate + (size_t)tok * 4096 + 2048 + nc);
;                 const uint2 p1 = *(const uint2*)((const u16*)(ws + OFF_YB) + (size_t)tok * DM + nc);
;                 uint2 o;
;                 o.x = pk2(bflo(p1.x) + v[0] * bflo(gb.x), bfhi(p1.x) + v[1] * bfhi(gb.x));
;                 o.y = pk2(bflo(p1.y) + v[2] * bflo(gb.y), bfhi(p1.y) + v[3] * bfhi(gb.y));
;                 WIDE_STORE((u16*)(ws + OFF_RB + 128 * MiB), DM, 0, o);
	v_lshlrev_b32_e32 v168, 16, v210
	v_and_b32_e32 v169, 0xffff0000, v210
	v_lshlrev_b32_e32 v176, 16, v212
	v_and_b32_e32 v177, 0xffff0000, v212
	v_pk_fma_f32 v[92:93], v[92:93], v[168:169], v[176:177]
	v_lshlrev_b32_e32 v170, 16, v211
	v_and_b32_e32 v171, 0xffff0000, v211
	v_lshlrev_b32_e32 v178, 16, v213
	v_and_b32_e32 v179, 0xffff0000, v213
	v_pk_fma_f32 v[94:95], v[94:95], v[170:171], v[178:179]
	global_load_dwordx2 v[210:211], v134, s[28:29] offset:256
	global_load_dwordx2 v[212:213], v138, s[4:5] offset:256
	s_waitcnt vmcnt(18)
	v_lshlrev_b32_e32 v168, 16, v214
	v_and_b32_e32 v169, 0xffff0000, v214
	v_lshlrev_b32_e32 v176, 16, v216
	v_and_b32_e32 v177, 0xffff0000, v216
	v_pk_fma_f32 v[84:85], v[84:85], v[168:169], v[176:177]
	v_lshlrev_b32_e32 v170, 16, v215
	v_and_b32_e32 v171, 0xffff0000, v215
	v_lshlrev_b32_e32 v178, 16, v217
	v_and_b32_e32 v179, 0xffff0000, v217
	v_pk_fma_f32 v[86:87], v[86:87], v[170:171], v[178:179]
	global_load_dwordx2 v[214:215], v134, s[28:29] offset:288
	global_load_dwordx2 v[216:217], v138, s[4:5] offset:288
	s_waitcnt vmcnt(18)
	v_lshlrev_b32_e32 v168, 16, v218
	v_and_b32_e32 v169, 0xffff0000, v218
	v_lshlrev_b32_e32 v176, 16, v220
	v_and_b32_e32 v177, 0xffff0000, v220
	v_pk_fma_f32 v[76:77], v[76:77], v[168:169], v[176:177]
	v_lshlrev_b32_e32 v170, 16, v219
	v_and_b32_e32 v171, 0xffff0000, v219
	v_lshlrev_b32_e32 v178, 16, v221
	v_and_b32_e32 v179, 0xffff0000, v221
	v_pk_fma_f32 v[78:79], v[78:79], v[170:171], v[178:179]
	global_load_dwordx2 v[218:219], v134, s[28:29] offset:320
	global_load_dwordx2 v[220:221], v138, s[4:5] offset:320
	s_waitcnt vmcnt(18)
	v_lshlrev_b32_e32 v168, 16, v222
	v_and_b32_e32 v169, 0xffff0000, v222
	v_lshlrev_b32_e32 v176, 16, v224
	v_and_b32_e32 v177, 0xffff0000, v224
	v_pk_fma_f32 v[68:69], v[68:69], v[168:169], v[176:177]
	v_lshlrev_b32_e32 v170, 16, v223
	v_and_b32_e32 v171, 0xffff0000, v223
	v_lshlrev_b32_e32 v178, 16, v225
	v_and_b32_e32 v179, 0xffff0000, v225
	v_pk_fma_f32 v[70:71], v[70:71], v[170:171], v[178:179]
	global_load_dwordx2 v[222:223], v134, s[28:29] offset:352
	global_load_dwordx2 v[224:225], v138, s[4:5] offset:352
	s_nop 0
	v_cvt_pk_bf16_f32 v92, v92, v93
	v_cvt_pk_bf16_f32 v93, v94, v95
	v_cvt_pk_bf16_f32 v94, v84, v85
	v_cvt_pk_bf16_f32 v95, v86, v87
	v_cvt_pk_bf16_f32 v76, v76, v77
	v_cvt_pk_bf16_f32 v77, v78, v79
	v_cvt_pk_bf16_f32 v78, v68, v69
	v_cvt_pk_bf16_f32 v79, v70, v71
	s_nop 1
	v_permlane16_swap_b32_e32 v92, v94
	v_permlane16_swap_b32_e32 v93, v95
	v_permlane16_swap_b32_e32 v76, v78
	v_permlane16_swap_b32_e32 v77, v79
	global_store_dwordx4 v192, v[92:95], s[72:73] offset:0
	global_store_dwordx4 v192, v[76:79], s[72:73] offset:64
	s_waitcnt vmcnt(18)
	v_lshlrev_b32_e32 v168, 16, v226
	v_and_b32_e32 v169, 0xffff0000, v226
	v_lshlrev_b32_e32 v176, 16, v228
	v_and_b32_e32 v177, 0xffff0000, v228
	v_pk_fma_f32 v[88:89], v[88:89], v[168:169], v[176:177]
	v_lshlrev_b32_e32 v170, 16, v227
	v_and_b32_e32 v171, 0xffff0000, v227
	v_lshlrev_b32_e32 v178, 16, v229
	v_and_b32_e32 v179, 0xffff0000, v229
	v_pk_fma_f32 v[90:91], v[90:91], v[170:171], v[178:179]
	global_load_dwordx2 v[226:227], v135, s[28:29] offset:256
	global_load_dwordx2 v[228:229], v139, s[4:5] offset:256
	s_waitcnt vmcnt(18)
	v_lshlrev_b32_e32 v168, 16, v230
	v_and_b32_e32 v169, 0xffff0000, v230
	v_lshlrev_b32_e32 v176, 16, v232
	v_and_b32_e32 v177, 0xffff0000, v232
	v_pk_fma_f32 v[80:81], v[80:81], v[168:169], v[176:177]
	v_lshlrev_b32_e32 v170, 16, v231
	v_and_b32_e32 v171, 0xffff0000, v231
	v_lshlrev_b32_e32 v178, 16, v233
	v_and_b32_e32 v179, 0xffff0000, v233
	v_pk_fma_f32 v[82:83], v[82:83], v[170:171], v[178:179]
	global_load_dwordx2 v[230:231], v135, s[28:29] offset:288
	global_load_dwordx2 v[232:233], v139, s[4:5] offset:288
	s_waitcnt vmcnt(18)
	v_lshlrev_b32_e32 v168, 16, v234
	v_and_b32_e32 v169, 0xffff0000, v234
	v_lshlrev_b32_e32 v176, 16, v236
	v_and_b32_e32 v177, 0xffff0000, v236
	v_pk_fma_f32 v[72:73], v[72:73], v[168:169], v[176:177]
	v_lshlrev_b32_e32 v170, 16, v235
	v_and_b32_e32 v171, 0xffff0000, v235
	v_lshlrev_b32_e32 v178, 16, v237
	v_and_b32_e32 v179, 0xffff0000, v237
	v_pk_fma_f32 v[74:75], v[74:75], v[170:171], v[178:179]
	global_load_dwordx2 v[234:235], v135, s[28:29] offset:320
	global_load_dwordx2 v[236:237], v139, s[4:5] offset:320
	s_waitcnt vmcnt(18)
	v_lshlrev_b32_e32 v168, 16, v238
	v_and_b32_e32 v169, 0xffff0000, v238
	v_lshlrev_b32_e32 v176, 16, v240
	v_and_b32_e32 v177, 0xffff0000, v240
	v_pk_fma_f32 v[64:65], v[64:65], v[168:169], v[176:177]
	v_lshlrev_b32_e32 v170, 16, v239
	v_and_b32_e32 v171, 0xffff0000, v239
	v_lshlrev_b32_e32 v178, 16, v241
	v_and_b32_e32 v179, 0xffff0000, v241
	v_pk_fma_f32 v[66:67], v[66:67], v[170:171], v[178:179]
	global_load_dwordx2 v[238:239], v135, s[28:29] offset:352
	global_load_dwordx2 v[240:241], v139, s[4:5] offset:352
	s_nop 0
	v_cvt_pk_bf16_f32 v88, v88, v89
	v_cvt_pk_bf16_f32 v89, v90, v91
	v_cvt_pk_bf16_f32 v90, v80, v81
	v_cvt_pk_bf16_f32 v91, v82, v83
	v_cvt_pk_bf16_f32 v72, v72, v73
	v_cvt_pk_bf16_f32 v73, v74, v75
	v_cvt_pk_bf16_f32 v74, v64, v65
	v_cvt_pk_bf16_f32 v75, v66, v67
	s_nop 1
	v_permlane16_swap_b32_e32 v88, v90
	v_permlane16_swap_b32_e32 v89, v91
	v_permlane16_swap_b32_e32 v72, v74
	v_permlane16_swap_b32_e32 v73, v75
	global_store_dwordx4 v193, v[88:91], s[72:73] offset:0
	global_store_dwordx4 v193, v[72:75], s[72:73] offset:64
	s_waitcnt vmcnt(18)
; __device__ __forceinline__ float bflo(unsigned u) { return __uint_as_float(u << 16); }
; __device__ __forceinline__ float bfhi(unsigned u) { return __uint_as_float(u & 0xffff0000u); }
; #define WIDE_STORE(BASE, LD, COFF, O) do { if ((m & 1) == 0) opend[n] = (O); \
;                 else *(uint4*)((BASE) + (size_t)tok * (LD) + (ncw - (COFF))) = swap_pair(opend[n], (O)); } while (0)
; __device__ __forceinline__ uint4 swap_pair(const uint2 a, const uint2 b) {
;   const auto rx = __builtin_amdgcn_permlane16_swap(a.x, b.x, false, false);
;   const auto ry = __builtin_amdgcn_permlane16_swap(a.y, b.y, false, false);
;   return make_uint4(rx[0], ry[0], rx[1], ry[1]);
; }
;     ...
;               } else if (MODE == 6) {
;                 const u16* gate = (const u16*)outp;
;                 uint2 gb = *(const uint2*)(gate + (size_t)tok * 4096 + 2048 + nc);
;                 const uint2 p1 = *(const uint2*)((const u16*)(ws + OFF_YB) + (size_t)tok * DM + nc);
;                 uint2 o;
;                 o.x = pk2(bflo(p1.x) + v[0] * bflo(gb.x), bfhi(p1.x) + v[1] * bfhi(gb.x));
;                 o.y = pk2(bflo(p1.y) + v[2] * bflo(gb.y), bfhi(p1.y) + v[3] * bfhi(gb.y));
;                 WIDE_STORE((u16*)(ws + OFF_RB + 128 * MiB), DM, 0, o);
	v_lshlrev_b32_e32 v168, 16, v210
	v_and_b32_e32 v169, 0xffff0000, v210
	v_lshlrev_b32_e32 v176, 16, v212
	v_and_b32_e32 v177, 0xffff0000, v212
	v_pk_fma_f32 v[60:61], v[60:61], v[168:169], v[176:177]
	v_lshlrev_b32_e32 v170, 16, v211
	v_and_b32_e32 v171, 0xffff0000, v211
	v_lshlrev_b32_e32 v178, 16, v213
	v_and_b32_e32 v179, 0xffff0000, v213
	v_pk_fma_f32 v[62:63], v[62:63], v[170:171], v[178:179]
	global_load_dwordx2 v[210:211], v136, s[28:29] offset:256
	global_load_dwordx2 v[212:213], v140, s[4:5] offset:256
	s_waitcnt vmcnt(18)
	v_lshlrev_b32_e32 v168, 16, v214
	v_and_b32_e32 v169, 0xffff0000, v214
	v_lshlrev_b32_e32 v176, 16, v216
	v_and_b32_e32 v177, 0xffff0000, v216
	v_pk_fma_f32 v[52:53], v[52:53], v[168:169], v[176:177]
	v_lshlrev_b32_e32 v170, 16, v215
	v_and_b32_e32 v171, 0xffff0000, v215
	v_lshlrev_b32_e32 v178, 16, v217
	v_and_b32_e32 v179, 0xffff0000, v217
	v_pk_fma_f32 v[54:55], v[54:55], v[170:171], v[178:179]
	global_load_dwordx2 v[214:215], v136, s[28:29] offset:288
	global_load_dwordx2 v[216:217], v140, s[4:5] offset:288
	s_waitcnt vmcnt(18)
	v_lshlrev_b32_e32 v168, 16, v218
	v_and_b32_e32 v169, 0xffff0000, v218
	v_lshlrev_b32_e32 v176, 16, v220
	v_and_b32_e32 v177, 0xffff0000, v220
	v_pk_fma_f32 v[44:45], v[44:45], v[168:169], v[176:177]
	v_lshlrev_b32_e32 v170, 16, v219
	v_and_b32_e32 v171, 0xffff0000, v219
	v_lshlrev_b32_e32 v178, 16, v221
	v_and_b32_e32 v179, 0xffff0000, v221
	v_pk_fma_f32 v[46:47], v[46:47], v[170:171], v[178:179]
	global_load_dwordx2 v[218:219], v136, s[28:29] offset:320
	global_load_dwordx2 v[220:221], v140, s[4:5] offset:320
	s_waitcnt vmcnt(18)
	v_lshlrev_b32_e32 v168, 16, v222
	v_and_b32_e32 v169, 0xffff0000, v222
	v_lshlrev_b32_e32 v176, 16, v224
	v_and_b32_e32 v177, 0xffff0000, v224
	v_pk_fma_f32 v[36:37], v[36:37], v[168:169], v[176:177]
	v_lshlrev_b32_e32 v170, 16, v223
	v_and_b32_e32 v171, 0xffff0000, v223
	v_lshlrev_b32_e32 v178, 16, v225
	v_and_b32_e32 v179, 0xffff0000, v225
	v_pk_fma_f32 v[38:39], v[38:39], v[170:171], v[178:179]
	global_load_dwordx2 v[222:223], v136, s[28:29] offset:352
	global_load_dwordx2 v[224:225], v140, s[4:5] offset:352
	s_nop 0
	v_cvt_pk_bf16_f32 v60, v60, v61
	v_cvt_pk_bf16_f32 v61, v62, v63
	v_cvt_pk_bf16_f32 v62, v52, v53
	v_cvt_pk_bf16_f32 v63, v54, v55
	v_cvt_pk_bf16_f32 v44, v44, v45
	v_cvt_pk_bf16_f32 v45, v46, v47
	v_cvt_pk_bf16_f32 v46, v36, v37
	v_cvt_pk_bf16_f32 v47, v38, v39
	s_nop 1
	v_permlane16_swap_b32_e32 v60, v62
	v_permlane16_swap_b32_e32 v61, v63
	v_permlane16_swap_b32_e32 v44, v46
	v_permlane16_swap_b32_e32 v45, v47
	global_store_dwordx4 v190, v[60:63], s[72:73] offset:256
	global_store_dwordx4 v190, v[44:47], s[72:73] offset:320
	s_waitcnt vmcnt(18)
	v_lshlrev_b32_e32 v168, 16, v226
	v_and_b32_e32 v169, 0xffff0000, v226
	v_lshlrev_b32_e32 v176, 16, v228
	v_and_b32_e32 v177, 0xffff0000, v228
	v_pk_fma_f32 v[56:57], v[56:57], v[168:169], v[176:177]
	v_lshlrev_b32_e32 v170, 16, v227
	v_and_b32_e32 v171, 0xffff0000, v227
	v_lshlrev_b32_e32 v178, 16, v229
	v_and_b32_e32 v179, 0xffff0000, v229
	v_pk_fma_f32 v[58:59], v[58:59], v[170:171], v[178:179]
	global_load_dwordx2 v[226:227], v137, s[28:29] offset:256
	global_load_dwordx2 v[228:229], v141, s[4:5] offset:256
	s_waitcnt vmcnt(18)
	v_lshlrev_b32_e32 v168, 16, v230
	v_and_b32_e32 v169, 0xffff0000, v230
	v_lshlrev_b32_e32 v176, 16, v232
	v_and_b32_e32 v177, 0xffff0000, v232
	v_pk_fma_f32 v[48:49], v[48:49], v[168:169], v[176:177]
	v_lshlrev_b32_e32 v170, 16, v231
	v_and_b32_e32 v171, 0xffff0000, v231
	v_lshlrev_b32_e32 v178, 16, v233
	v_and_b32_e32 v179, 0xffff0000, v233
	v_pk_fma_f32 v[50:51], v[50:51], v[170:171], v[178:179]
	global_load_dwordx2 v[230:231], v137, s[28:29] offset:288
	global_load_dwordx2 v[232:233], v141, s[4:5] offset:288
	s_waitcnt vmcnt(18)
	v_lshlrev_b32_e32 v168, 16, v234
	v_and_b32_e32 v169, 0xffff0000, v234
	v_lshlrev_b32_e32 v176, 16, v236
	v_and_b32_e32 v177, 0xffff0000, v236
	v_pk_fma_f32 v[40:41], v[40:41], v[168:169], v[176:177]
	v_lshlrev_b32_e32 v170, 16, v235
	v_and_b32_e32 v171, 0xffff0000, v235
	v_lshlrev_b32_e32 v178, 16, v237
	v_and_b32_e32 v179, 0xffff0000, v237
	v_pk_fma_f32 v[42:43], v[42:43], v[170:171], v[178:179]
	global_load_dwordx2 v[234:235], v137, s[28:29] offset:320
	global_load_dwordx2 v[236:237], v141, s[4:5] offset:320
	s_waitcnt vmcnt(18)
	v_lshlrev_b32_e32 v168, 16, v238
	v_and_b32_e32 v169, 0xffff0000, v238
	v_lshlrev_b32_e32 v176, 16, v240
	v_and_b32_e32 v177, 0xffff0000, v240
	v_pk_fma_f32 v[32:33], v[32:33], v[168:169], v[176:177]
	v_lshlrev_b32_e32 v170, 16, v239
	v_and_b32_e32 v171, 0xffff0000, v239
	v_lshlrev_b32_e32 v178, 16, v241
	v_and_b32_e32 v179, 0xffff0000, v241
	v_pk_fma_f32 v[34:35], v[34:35], v[170:171], v[178:179]
	global_load_dwordx2 v[238:239], v137, s[28:29] offset:352
	global_load_dwordx2 v[240:241], v141, s[4:5] offset:352
	s_nop 0
	v_cvt_pk_bf16_f32 v56, v56, v57
	v_cvt_pk_bf16_f32 v57, v58, v59
	v_cvt_pk_bf16_f32 v58, v48, v49
	v_cvt_pk_bf16_f32 v59, v50, v51
	v_cvt_pk_bf16_f32 v40, v40, v41
	v_cvt_pk_bf16_f32 v41, v42, v43
	v_cvt_pk_bf16_f32 v42, v32, v33
	v_cvt_pk_bf16_f32 v43, v34, v35
	s_nop 1
	v_permlane16_swap_b32_e32 v56, v58
	v_permlane16_swap_b32_e32 v57, v59
	v_permlane16_swap_b32_e32 v40, v42
	v_permlane16_swap_b32_e32 v41, v43
	global_store_dwordx4 v191, v[56:59], s[72:73] offset:256
	global_store_dwordx4 v191, v[40:43], s[72:73] offset:320
	s_waitcnt vmcnt(18)
	v_lshlrev_b32_e32 v168, 16, v210
	v_and_b32_e32 v169, 0xffff0000, v210
	v_lshlrev_b32_e32 v176, 16, v212
	v_and_b32_e32 v177, 0xffff0000, v212
	v_pk_fma_f32 v[28:29], v[28:29], v[168:169], v[176:177]
	v_lshlrev_b32_e32 v170, 16, v211
	v_and_b32_e32 v171, 0xffff0000, v211
	v_lshlrev_b32_e32 v178, 16, v213
	v_and_b32_e32 v179, 0xffff0000, v213
	v_pk_fma_f32 v[30:31], v[30:31], v[170:171], v[178:179]
	s_waitcnt vmcnt(16)
; __device__ __forceinline__ float bflo(unsigned u) { return __uint_as_float(u << 16); }
; __device__ __forceinline__ float bfhi(unsigned u) { return __uint_as_float(u & 0xffff0000u); }
; #define WIDE_STORE(BASE, LD, COFF, O) do { if ((m & 1) == 0) opend[n] = (O); \
;                 else *(uint4*)((BASE) + (size_t)tok * (LD) + (ncw - (COFF))) = swap_pair(opend[n], (O)); } while (0)
; __device__ __forceinline__ uint4 swap_pair(const uint2 a, const uint2 b) {
;   const auto rx = __builtin_amdgcn_permlane16_swap(a.x, b.x, false, false);
;   const auto ry = __builtin_amdgcn_permlane16_swap(a.y, b.y, false, false);
;   return make_uint4(rx[0], ry[0], rx[1], ry[1]);
; }
;     ...
;               } else if (MODE == 6) {
;                 const u16* gate = (const u16*)outp;
;                 uint2 gb = *(const uint2*)(gate + (size_t)tok * 4096 + 2048 + nc);
;                 const uint2 p1 = *(const uint2*)((const u16*)(ws + OFF_YB) + (size_t)tok * DM + nc);
;                 uint2 o;
;                 o.x = pk2(bflo(p1.x) + v[0] * bflo(gb.x), bfhi(p1.x) + v[1] * bfhi(gb.x));
;                 o.y = pk2(bflo(p1.y) + v[2] * bflo(gb.y), bfhi(p1.y) + v[3] * bfhi(gb.y));
;                 WIDE_STORE((u16*)(ws + OFF_RB + 128 * MiB), DM, 0, o);
	v_lshlrev_b32_e32 v168, 16, v214
	v_and_b32_e32 v169, 0xffff0000, v214
	v_lshlrev_b32_e32 v176, 16, v216
	v_and_b32_e32 v177, 0xffff0000, v216
	v_pk_fma_f32 v[20:21], v[20:21], v[168:169], v[176:177]
	v_lshlrev_b32_e32 v170, 16, v215
	v_and_b32_e32 v171, 0xffff0000, v215
	v_lshlrev_b32_e32 v178, 16, v217
	v_and_b32_e32 v179, 0xffff0000, v217
	v_pk_fma_f32 v[22:23], v[22:23], v[170:171], v[178:179]
	s_waitcnt vmcnt(14)
	v_lshlrev_b32_e32 v168, 16, v218
	v_and_b32_e32 v169, 0xffff0000, v218
	v_lshlrev_b32_e32 v176, 16, v220
	v_and_b32_e32 v177, 0xffff0000, v220
	v_pk_fma_f32 v[12:13], v[12:13], v[168:169], v[176:177]
	v_lshlrev_b32_e32 v170, 16, v219
	v_and_b32_e32 v171, 0xffff0000, v219
	v_lshlrev_b32_e32 v178, 16, v221
	v_and_b32_e32 v179, 0xffff0000, v221
	v_pk_fma_f32 v[14:15], v[14:15], v[170:171], v[178:179]
	s_waitcnt vmcnt(12)
	v_lshlrev_b32_e32 v168, 16, v222
	v_and_b32_e32 v169, 0xffff0000, v222
	v_lshlrev_b32_e32 v176, 16, v224
	v_and_b32_e32 v177, 0xffff0000, v224
	v_pk_fma_f32 v[4:5], v[4:5], v[168:169], v[176:177]
	v_lshlrev_b32_e32 v170, 16, v223
	v_and_b32_e32 v171, 0xffff0000, v223
	v_lshlrev_b32_e32 v178, 16, v225
	v_and_b32_e32 v179, 0xffff0000, v225
	v_pk_fma_f32 v[6:7], v[6:7], v[170:171], v[178:179]
	s_nop 0
	v_cvt_pk_bf16_f32 v28, v28, v29
	v_cvt_pk_bf16_f32 v29, v30, v31
	v_cvt_pk_bf16_f32 v30, v20, v21
	v_cvt_pk_bf16_f32 v31, v22, v23
	v_cvt_pk_bf16_f32 v12, v12, v13
	v_cvt_pk_bf16_f32 v13, v14, v15
	v_cvt_pk_bf16_f32 v14, v4, v5
	v_cvt_pk_bf16_f32 v15, v6, v7
	s_nop 1
	v_permlane16_swap_b32_e32 v28, v30
	v_permlane16_swap_b32_e32 v29, v31
	v_permlane16_swap_b32_e32 v12, v14
	v_permlane16_swap_b32_e32 v13, v15
	global_store_dwordx4 v192, v[28:31], s[72:73] offset:256
	global_store_dwordx4 v192, v[12:15], s[72:73] offset:320
	s_waitcnt vmcnt(10)
	v_lshlrev_b32_e32 v168, 16, v226
	v_and_b32_e32 v169, 0xffff0000, v226
	v_lshlrev_b32_e32 v176, 16, v228
	v_and_b32_e32 v177, 0xffff0000, v228
	v_pk_fma_f32 v[24:25], v[24:25], v[168:169], v[176:177]
	v_lshlrev_b32_e32 v170, 16, v227
	v_and_b32_e32 v171, 0xffff0000, v227
	v_lshlrev_b32_e32 v178, 16, v229
	v_and_b32_e32 v179, 0xffff0000, v229
	v_pk_fma_f32 v[26:27], v[26:27], v[170:171], v[178:179]
	s_waitcnt vmcnt(8)
	v_lshlrev_b32_e32 v168, 16, v230
	v_and_b32_e32 v169, 0xffff0000, v230
	v_lshlrev_b32_e32 v176, 16, v232
	v_and_b32_e32 v177, 0xffff0000, v232
	v_pk_fma_f32 v[16:17], v[16:17], v[168:169], v[176:177]
	v_lshlrev_b32_e32 v170, 16, v231
	v_and_b32_e32 v171, 0xffff0000, v231
	v_lshlrev_b32_e32 v178, 16, v233
	v_and_b32_e32 v179, 0xffff0000, v233
	v_pk_fma_f32 v[18:19], v[18:19], v[170:171], v[178:179]
	s_waitcnt vmcnt(6)
	v_lshlrev_b32_e32 v168, 16, v234
	v_and_b32_e32 v169, 0xffff0000, v234
	v_lshlrev_b32_e32 v176, 16, v236
	v_and_b32_e32 v177, 0xffff0000, v236
	v_pk_fma_f32 v[8:9], v[8:9], v[168:169], v[176:177]
	v_lshlrev_b32_e32 v170, 16, v235
	v_and_b32_e32 v171, 0xffff0000, v235
	v_lshlrev_b32_e32 v178, 16, v237
	v_and_b32_e32 v179, 0xffff0000, v237
	v_pk_fma_f32 v[10:11], v[10:11], v[170:171], v[178:179]
	s_waitcnt vmcnt(4)
; __device__ __forceinline__ float bflo(unsigned u) { return __uint_as_float(u << 16); }
; __device__ __forceinline__ float bfhi(unsigned u) { return __uint_as_float(u & 0xffff0000u); }
; #define WIDE_STORE(BASE, LD, COFF, O) do { if ((m & 1) == 0) opend[n] = (O); \
;                 else *(uint4*)((BASE) + (size_t)tok * (LD) + (ncw - (COFF))) = swap_pair(opend[n], (O)); } while (0)
;     ...
; #pragma unroll
;     for (int a = 0; a < 2; ++a)
; #pragma unroll
;       for (int b = 0; b < 2; ++b)
; #pragma unroll
;         for (int m = 0; m < 4; ++m)
; #pragma unroll
;           for (int n = 0; n < 2; ++n) acc[a][b][m][n] = f32x4{0.f, 0.f, 0.f, 0.f};
;     ...
;               } else if (MODE == 6) {
;                 const u16* gate = (const u16*)outp;
;                 uint2 gb = *(const uint2*)(gate + (size_t)tok * 4096 + 2048 + nc);
;                 const uint2 p1 = *(const uint2*)((const u16*)(ws + OFF_YB) + (size_t)tok * DM + nc);
;                 uint2 o;
;                 o.x = pk2(bflo(p1.x) + v[0] * bflo(gb.x), bfhi(p1.x) + v[1] * bfhi(gb.x));
;                 o.y = pk2(bflo(p1.y) + v[2] * bflo(gb.y), bfhi(p1.y) + v[3] * bfhi(gb.y));
;                 WIDE_STORE((u16*)(ws + OFF_RB + 128 * MiB), DM, 0, o);
;               } else if (MODE == 3) {
;                 float4 r = ldnt4(xin + (size_t)tok * DM + nc);
;                 uint2 hb; hb.x = pk2(r.x + v[0], r.y + v[1]); hb.y = pk2(r.z + v[2], r.w + v[3]);
;                 WIDE_STORE((u16*)(ws + OFF_RB), DM, 0, hb);
;               } else {
;                 uint2* ph = (uint2*)((u16*)(ws + OFF_RB) + (size_t)tok * DM + nc);
;                 const uint2 hb = *ph;
;                 uint2 o; o.x = pk2(bflo(hb.x) + v[0], bfhi(hb.x) + v[1]); o.y = pk2(bflo(hb.y) + v[2], bfhi(hb.y) + v[3]);
;                 WIDE_STORE((u16*)(ws + OFF_RB), DM, 0, o);
;               }
;     ...
;             }
;     }
;     asm volatile("s_waitcnt vmcnt(0)" ::: "memory");
;     if (has_next && wr == 1) __builtin_amdgcn_s_barrier();
	v_lshlrev_b32_e32 v168, 16, v238
	v_and_b32_e32 v169, 0xffff0000, v238
	v_lshlrev_b32_e32 v176, 16, v240
	v_and_b32_e32 v177, 0xffff0000, v240
	v_pk_fma_f32 v[0:1], v[0:1], v[168:169], v[176:177]
	v_lshlrev_b32_e32 v170, 16, v239
	v_and_b32_e32 v171, 0xffff0000, v239
	v_lshlrev_b32_e32 v178, 16, v241
	v_and_b32_e32 v179, 0xffff0000, v241
	v_pk_fma_f32 v[2:3], v[2:3], v[170:171], v[178:179]
	s_nop 0
	v_cvt_pk_bf16_f32 v24, v24, v25
	v_cvt_pk_bf16_f32 v25, v26, v27
	v_cvt_pk_bf16_f32 v26, v16, v17
	v_cvt_pk_bf16_f32 v27, v18, v19
	v_cvt_pk_bf16_f32 v8, v8, v9
	v_cvt_pk_bf16_f32 v9, v10, v11
	v_cvt_pk_bf16_f32 v10, v0, v1
	v_cvt_pk_bf16_f32 v11, v2, v3
	s_nop 1
	v_permlane16_swap_b32_e32 v24, v26
	v_permlane16_swap_b32_e32 v25, v27
	v_permlane16_swap_b32_e32 v8, v10
	v_permlane16_swap_b32_e32 v9, v11
	global_store_dwordx4 v193, v[24:27], s[72:73] offset:256
	global_store_dwordx4 v193, v[8:11], s[72:73] offset:320
	s_and_b64 s[0:1], s[56:57], s[8:9]
	s_andn2_b64 vcc, exec, s[0:1]
	s_nop 1
	v_mov_b32_e32 v0, 0
	v_mov_b32_e32 v1, v0
	v_mov_b32_e32 v2, v0
	v_mov_b32_e32 v3, v0
	v_mov_b32_e32 v4, v0
	v_mov_b32_e32 v5, v0
	v_mov_b32_e32 v6, v0
	v_mov_b32_e32 v7, v0
	v_mov_b32_e32 v8, v0
	v_mov_b32_e32 v9, v0
	v_mov_b32_e32 v10, v0
	v_mov_b32_e32 v11, v0
	v_mov_b32_e32 v12, v0
	v_mov_b32_e32 v13, v0
	v_mov_b32_e32 v14, v0
	v_mov_b32_e32 v15, v0
	v_mov_b32_e32 v16, v0
	v_mov_b32_e32 v17, v0
	v_mov_b32_e32 v18, v0
	v_mov_b32_e32 v19, v0
	v_mov_b32_e32 v20, v0
	v_mov_b32_e32 v21, v0
	v_mov_b32_e32 v22, v0
	v_mov_b32_e32 v23, v0
	v_mov_b32_e32 v24, v0
	v_mov_b32_e32 v25, v0
	v_mov_b32_e32 v26, v0
	v_mov_b32_e32 v27, v0
	v_mov_b32_e32 v28, v0
	v_mov_b32_e32 v29, v0
	v_mov_b32_e32 v30, v0
	v_mov_b32_e32 v31, v0
	v_mov_b32_e32 v32, v0
	v_mov_b32_e32 v33, v0
	v_mov_b32_e32 v34, v0
	v_mov_b32_e32 v35, v0
	v_mov_b32_e32 v36, v0
	v_mov_b32_e32 v37, v0
	v_mov_b32_e32 v38, v0
	v_mov_b32_e32 v39, v0
	v_mov_b32_e32 v40, v0
	v_mov_b32_e32 v41, v0
	v_mov_b32_e32 v42, v0
	v_mov_b32_e32 v43, v0
	v_mov_b32_e32 v44, v0
	v_mov_b32_e32 v45, v0
	v_mov_b32_e32 v46, v0
	v_mov_b32_e32 v47, v0
	v_mov_b32_e32 v48, v0
	v_mov_b32_e32 v49, v0
	v_mov_b32_e32 v50, v0
	v_mov_b32_e32 v51, v0
	v_mov_b32_e32 v52, v0
	v_mov_b32_e32 v53, v0
	v_mov_b32_e32 v54, v0
	v_mov_b32_e32 v55, v0
	v_mov_b32_e32 v56, v0
	v_mov_b32_e32 v57, v0
	v_mov_b32_e32 v58, v0
	v_mov_b32_e32 v59, v0
	v_mov_b32_e32 v60, v0
	v_mov_b32_e32 v61, v0
	v_mov_b32_e32 v62, v0
	v_mov_b32_e32 v63, v0
	v_mov_b32_e32 v64, v0
	v_mov_b32_e32 v65, v0
	v_mov_b32_e32 v66, v0
	v_mov_b32_e32 v67, v0
	v_mov_b32_e32 v68, v0
	v_mov_b32_e32 v69, v0
	v_mov_b32_e32 v70, v0
	v_mov_b32_e32 v71, v0
	v_mov_b32_e32 v72, v0
	v_mov_b32_e32 v73, v0
	v_mov_b32_e32 v74, v0
	v_mov_b32_e32 v75, v0
	v_mov_b32_e32 v76, v0
	v_mov_b32_e32 v77, v0
	v_mov_b32_e32 v78, v0
	v_mov_b32_e32 v79, v0
	v_mov_b32_e32 v80, v0
	v_mov_b32_e32 v81, v0
	v_mov_b32_e32 v82, v0
	v_mov_b32_e32 v83, v0
	v_mov_b32_e32 v84, v0
	v_mov_b32_e32 v85, v0
	v_mov_b32_e32 v86, v0
	v_mov_b32_e32 v87, v0
	v_mov_b32_e32 v88, v0
	v_mov_b32_e32 v89, v0
	v_mov_b32_e32 v90, v0
	v_mov_b32_e32 v91, v0
	v_mov_b32_e32 v92, v0
	v_mov_b32_e32 v93, v0
	v_mov_b32_e32 v94, v0
	v_mov_b32_e32 v95, v0
	v_mov_b32_e32 v96, v0
	v_mov_b32_e32 v97, v0
	v_mov_b32_e32 v98, v0
	v_mov_b32_e32 v99, v0
	v_mov_b32_e32 v100, v0
	v_mov_b32_e32 v101, v0
	v_mov_b32_e32 v102, v0
	v_mov_b32_e32 v103, v0
	v_mov_b32_e32 v104, v0
	v_mov_b32_e32 v105, v0
	v_mov_b32_e32 v106, v0
	v_mov_b32_e32 v107, v0
	v_mov_b32_e32 v108, v0
	v_mov_b32_e32 v109, v0
	v_mov_b32_e32 v110, v0
	v_mov_b32_e32 v111, v0
	v_mov_b32_e32 v112, v0
	v_mov_b32_e32 v113, v0
	v_mov_b32_e32 v114, v0
	v_mov_b32_e32 v115, v0
	v_mov_b32_e32 v116, v0
	v_mov_b32_e32 v117, v0
	v_mov_b32_e32 v118, v0
	v_mov_b32_e32 v119, v0
	v_mov_b32_e32 v120, v0
	v_mov_b32_e32 v121, v0
	v_mov_b32_e32 v122, v0
	v_mov_b32_e32 v123, v0
	v_mov_b32_e32 v124, v0
	v_mov_b32_e32 v125, v0
	v_mov_b32_e32 v126, v0
	v_mov_b32_e32 v127, v0
	s_waitcnt vmcnt(0)
	s_cbranch_vccnz .LBB0_819
	s_barrier
	s_branch .LBB0_819

; #define STAGE(P_, BASE, br, kt) do { const u16* _gb = (BASE) + (long)(br) * K + (long)(kt) * BK; \
;     _Pragma("unroll") for (int _i = 0; _i < 2; ++_i) { \
;       __builtin_amdgcn_global_load_lds((const unsigned*)(_gb + (long)_i * 64 * K + lane_off), \
;         (unsigned*)((char*)(P_) + lds_wbase + _i * 8192), 16, 0, 0); } } while (0)
; #define LDA(dst, b, h) _Pragma("unroll") for (int m = 0; m < 4; ++m) _Pragma("unroll") for (int k = 0; k < 2; ++k) \
;     dst[m][k] = *reinterpret_cast<const bf16x8*>((char*)SA(b, h) + lds_byte(wr * 64 + m * 16 + fr, k * 32 + fq * 8))
; #define LDB(dst, b, h) _Pragma("unroll") for (int n = 0; n < 2; ++n) _Pragma("unroll") for (int k = 0; k < 2; ++k) \
;     dst[n][k] = *reinterpret_cast<const bf16x8*>((char*)SB(b, h) + lds_byte(wc * 32 + n * 16 + fr, k * 32 + fq * 8))
; #define MMA(ai, bj, At_, Bt_) do { __builtin_amdgcn_s_setprio(1); \
;     _Pragma("unroll") for (int m = 0; m < 4; ++m) _Pragma("unroll") for (int n = 0; n < 2; ++n) _Pragma("unroll") for (int k = 0; k < 2; ++k) \
;       acc[ai][bj][m][n] = __builtin_amdgcn_mfma_f32_16x16x32_bf16(At_[m][k], Bt_[n][k], acc[ai][bj][m][n], 0, 0, 0); \
;     __builtin_amdgcn_s_setprio(0); } while (0)
; #define WAIT_V(n) asm volatile("s_waitcnt vmcnt(" #n ")" ::: "memory")
; #define WAIT_L(n) asm volatile("s_waitcnt lgkmcnt(" #n ")" ::: "memory")
; #define BAR __builtin_amdgcn_s_barrier()
; #define SCHED __builtin_amdgcn_sched_barrier(0)
; #define STAGEW(P_, BASE, cur, nxt, kt_) do { const bool _wr = (kt_) >= nt; \
;     STAGE(P_, BASE, (_wr ? (nxt) : (cur)), (_wr ? (kt_) - nt : (kt_))); } while (0)
; template <int PRE> ...
;     ...
;   for (int t = 0; t < nt; t += 2) {
;     LDB(B0, 0, 0); SCHED; LDA(At, 0, 0); STAGE(SA(1, 1), A, brow + HALF, t + 1);
;     WAIT_L(8); BAR; WAIT_L(0); MMA(0, 0, At, B0); BAR; SCHED;
;     LDB(B1, 0, 1); STAGEW(SB(0, 0), Bt, bcol, bcol_n, t + 2);
;     BAR; WAIT_L(0); MMA(0, 1, At, B1); BAR;
;     LDA(At, 0, 1); STAGEW(SA(0, 0), A, brow, brow_n, t + 2);
;     BAR; WAIT_L(0); MMA(1, 0, At, B0); BAR; SCHED;
;     STAGEW(SB(0, 1), Bt, bcol + HALF, bcol_n + HALF, t + 2);
;     WAIT_V(6); BAR; MMA(1, 1, At, B1); BAR;
.LBB0_892:
	v_add_u32_e32 v142, s81, v147
	ds_read_b128 v[134:137], v142
	ds_read_b128 v[138:141], v142 offset:1024
	ds_read_b128 v[152:155], v142 offset:2048
	ds_read_b128 v[156:159], v142 offset:3072
	s_add_i32 m0, s12, 0xc000
	ds_read_b128 v[160:163], v144
	ds_read_b128 v[168:171], v144 offset:1024
	ds_read_b128 v[172:175], v148
	ds_read_b128 v[176:179], v148 offset:1024
	ds_read_b128 v[180:183], v149
	ds_read_b128 v[184:187], v149 offset:1024
	ds_read_b128 v[188:191], v150
	ds_read_b128 v[192:195], v150 offset:1024
	global_load_lds_dwordx4 v[132:133], off
	v_lshl_add_u64 v[142:143], v[132:133], 0, s[86:87]
	s_add_i32 m0, s12, 0xe000
	s_nop 0
	global_load_lds_dwordx4 v[142:143], off
	s_waitcnt lgkmcnt(8)
	s_barrier
	s_waitcnt lgkmcnt(0)
	v_mfma_f32_16x16x32_bf16 v[124:127], v[160:163], v[134:137], v[124:127]
	v_mfma_f32_16x16x32_bf16 v[120:123], v[160:163], v[152:155], v[120:123]
	v_mfma_f32_16x16x32_bf16 v[116:119], v[172:175], v[134:137], v[116:119]
	v_mfma_f32_16x16x32_bf16 v[112:115], v[172:175], v[152:155], v[112:115]
	v_mfma_f32_16x16x32_bf16 v[108:111], v[180:183], v[134:137], v[108:111]
	v_mfma_f32_16x16x32_bf16 v[104:107], v[180:183], v[152:155], v[104:107]
	v_mfma_f32_16x16x32_bf16 v[100:103], v[188:191], v[134:137], v[100:103]
	v_mfma_f32_16x16x32_bf16 v[96:99], v[188:191], v[152:155], v[96:99]
	v_mfma_f32_16x16x32_bf16 v[124:127], v[168:171], v[138:141], v[124:127]
	v_mfma_f32_16x16x32_bf16 v[120:123], v[168:171], v[156:159], v[120:123]
	v_mfma_f32_16x16x32_bf16 v[116:119], v[176:179], v[138:141], v[116:119]
	v_mfma_f32_16x16x32_bf16 v[112:115], v[176:179], v[156:159], v[112:115]
	v_mfma_f32_16x16x32_bf16 v[108:111], v[184:187], v[138:141], v[108:111]
	v_mfma_f32_16x16x32_bf16 v[104:107], v[184:187], v[156:159], v[104:107]
	v_mfma_f32_16x16x32_bf16 v[100:103], v[192:195], v[138:141], v[100:103]
	v_mfma_f32_16x16x32_bf16 v[96:99], v[192:195], v[156:159], v[96:99]
	s_barrier
	s_add_i32 s38, s1, 2
	s_cmp_lt_u32 s1, 30
	s_cselect_b64 s[2:3], -1, 0
	s_and_b64 vcc, s[2:3], exec
	s_cselect_b32 s4, s29, s31
	s_cselect_b32 s3, 0, 0xffffffe0
	s_cselect_b32 s40, s0, s30
	s_cselect_b32 s42, s36, s35
	s_cselect_b32 s2, s34, s37
	s_ashr_i32 s5, s4, 31
	s_lshl_b64 s[4:5], s[4:5], 12
	s_add_u32 s39, s72, s4
	s_addc_u32 s41, s73, s5
	s_add_i32 s18, s38, s3
	s_lshl_b64 s[4:5], s[18:19], 7
	s_add_u32 s44, s39, s4
	v_add_u32_e32 v142, s82, v147
	s_addc_u32 s45, s41, s5
	s_mov_b32 m0, s13
	ds_read_b128 v[210:213], v142
	ds_read_b128 v[214:217], v142 offset:1024
	ds_read_b128 v[218:221], v142 offset:2048
	ds_read_b128 v[222:225], v142 offset:3072
	v_lshl_add_u64 v[142:143], s[44:45], 0, v[128:129]
	global_load_lds_dwordx4 v[142:143], off
	v_lshl_add_u64 v[142:143], v[142:143], 0, s[86:87]
	s_mov_b32 m0, s14
	s_nop 0
	global_load_lds_dwordx4 v[142:143], off
	s_barrier
	s_waitcnt lgkmcnt(0)
	v_mfma_f32_16x16x32_bf16 v[92:95], v[160:163], v[210:213], v[92:95]
	v_mfma_f32_16x16x32_bf16 v[88:91], v[160:163], v[218:221], v[88:91]
	v_mfma_f32_16x16x32_bf16 v[84:87], v[172:175], v[210:213], v[84:87]
	v_mfma_f32_16x16x32_bf16 v[80:83], v[172:175], v[218:221], v[80:83]
	v_mfma_f32_16x16x32_bf16 v[76:79], v[180:183], v[210:213], v[76:79]
	v_mfma_f32_16x16x32_bf16 v[72:75], v[180:183], v[218:221], v[72:75]
	v_mfma_f32_16x16x32_bf16 v[68:71], v[188:191], v[210:213], v[68:71]
	v_mfma_f32_16x16x32_bf16 v[64:67], v[188:191], v[218:221], v[64:67]
	v_mfma_f32_16x16x32_bf16 v[92:95], v[168:171], v[214:217], v[92:95]
	v_mfma_f32_16x16x32_bf16 v[88:91], v[168:171], v[222:225], v[88:91]
	v_mfma_f32_16x16x32_bf16 v[84:87], v[176:179], v[214:217], v[84:87]
	v_mfma_f32_16x16x32_bf16 v[80:83], v[176:179], v[222:225], v[80:83]
	v_mfma_f32_16x16x32_bf16 v[76:79], v[184:187], v[214:217], v[76:79]
	v_mfma_f32_16x16x32_bf16 v[72:75], v[184:187], v[222:225], v[72:75]
	v_mfma_f32_16x16x32_bf16 v[68:71], v[192:195], v[214:217], v[68:71]
	v_mfma_f32_16x16x32_bf16 v[64:67], v[192:195], v[222:225], v[64:67]
	s_ashr_i32 s41, s40, 31
	s_lshl_b64 s[40:41], s[40:41], 12
	s_add_u32 s3, s71, s40
	s_addc_u32 s18, s74, s41
	s_add_u32 s40, s3, s4
	s_addc_u32 s41, s18, s5
	s_mov_b32 m0, s12
	v_lshl_add_u64 v[142:143], s[40:41], 0, v[128:129]
	s_barrier
	ds_read_b128 v[160:163], v144 offset:16384
	ds_read_b128 v[168:171], v144 offset:17408
	ds_read_b128 v[172:175], v148 offset:16384
	ds_read_b128 v[176:179], v148 offset:17408
	ds_read_b128 v[180:183], v149 offset:16384
	ds_read_b128 v[184:187], v149 offset:17408
	ds_read_b128 v[188:191], v150 offset:16384
	ds_read_b128 v[192:195], v150 offset:17408
	global_load_lds_dwordx4 v[142:143], off
	v_lshl_add_u64 v[142:143], v[142:143], 0, s[86:87]
	s_mov_b32 m0, s15
	s_nop 0
	global_load_lds_dwordx4 v[142:143], off
	s_barrier
	s_waitcnt lgkmcnt(0)
	v_mfma_f32_16x16x32_bf16 v[60:63], v[160:163], v[134:137], v[60:63]
	v_mfma_f32_16x16x32_bf16 v[56:59], v[160:163], v[152:155], v[56:59]
	v_mfma_f32_16x16x32_bf16 v[52:55], v[172:175], v[134:137], v[52:55]
	v_mfma_f32_16x16x32_bf16 v[48:51], v[172:175], v[152:155], v[48:51]
	v_mfma_f32_16x16x32_bf16 v[44:47], v[180:183], v[134:137], v[44:47]
	v_mfma_f32_16x16x32_bf16 v[40:43], v[180:183], v[152:155], v[40:43]
	v_mfma_f32_16x16x32_bf16 v[36:39], v[188:191], v[134:137], v[36:39]
	v_mfma_f32_16x16x32_bf16 v[32:35], v[188:191], v[152:155], v[32:35]
	v_mfma_f32_16x16x32_bf16 v[60:63], v[168:171], v[138:141], v[60:63]
	v_mfma_f32_16x16x32_bf16 v[56:59], v[168:171], v[156:159], v[56:59]
	v_mfma_f32_16x16x32_bf16 v[52:55], v[176:179], v[138:141], v[52:55]
	v_mfma_f32_16x16x32_bf16 v[48:51], v[176:179], v[156:159], v[48:51]
	v_mfma_f32_16x16x32_bf16 v[44:47], v[184:187], v[138:141], v[44:47]
	v_mfma_f32_16x16x32_bf16 v[40:43], v[184:187], v[156:159], v[40:43]
	v_mfma_f32_16x16x32_bf16 v[36:39], v[192:195], v[138:141], v[36:39]
	v_mfma_f32_16x16x32_bf16 v[32:35], v[192:195], v[156:159], v[32:35]
	s_barrier
; #define LDA(dst, b, h) _Pragma("unroll") for (int m = 0; m < 4; ++m) _Pragma("unroll") for (int k = 0; k < 2; ++k) \
;     dst[m][k] = *reinterpret_cast<const bf16x8*>((char*)SA(b, h) + lds_byte(wr * 64 + m * 16 + fr, k * 32 + fq * 8))
; #define LDB(dst, b, h) _Pragma("unroll") for (int n = 0; n < 2; ++n) _Pragma("unroll") for (int k = 0; k < 2; ++k) \
;     dst[n][k] = *reinterpret_cast<const bf16x8*>((char*)SB(b, h) + lds_byte(wc * 32 + n * 16 + fr, k * 32 + fq * 8))
; #define MMA(ai, bj, At_, Bt_) do { __builtin_amdgcn_s_setprio(1); \
;     _Pragma("unroll") for (int m = 0; m < 4; ++m) _Pragma("unroll") for (int n = 0; n < 2; ++n) _Pragma("unroll") for (int k = 0; k < 2; ++k) \
;       acc[ai][bj][m][n] = __builtin_amdgcn_mfma_f32_16x16x32_bf16(At_[m][k], Bt_[n][k], acc[ai][bj][m][n], 0, 0, 0); \
;     __builtin_amdgcn_s_setprio(0); } while (0)
; #define WAIT_V(n) asm volatile("s_waitcnt vmcnt(" #n ")" ::: "memory")
; #define WAIT_L(n) asm volatile("s_waitcnt lgkmcnt(" #n ")" ::: "memory")
; #define BAR __builtin_amdgcn_s_barrier()
; #define SCHED __builtin_amdgcn_sched_barrier(0)
; #define STAGEW(P_, BASE, cur, nxt, kt_) do { const bool _wr = (kt_) >= nt; \
;     STAGE(P_, BASE, (_wr ? (nxt) : (cur)), (_wr ? (kt_) - nt : (kt_))); } while (0)
; template <int PRE> ...
;     ...
;     BAR; WAIT_L(0); MMA(1, 0, At, B0); BAR; SCHED;
;     STAGEW(SB(0, 1), Bt, bcol + HALF, bcol_n + HALF, t + 2);
;     WAIT_V(6); BAR; MMA(1, 1, At, B1); BAR;
;     LDB(B0, 1, 0); SCHED; LDA(At, 1, 0); STAGEW(SA(0, 1), A, brow + HALF, brow_n + HALF, t + 2);
;     WAIT_L(8); BAR; WAIT_L(0); MMA(0, 0, At, B0); BAR; SCHED;
;     LDB(B1, 1, 1); STAGEW(SB(1, 0), Bt, bcol, bcol_n, t + 3);
;     BAR; WAIT_L(0); MMA(0, 1, At, B1); BAR;
;     LDA(At, 1, 1); STAGEW(SA(1, 0), A, brow, brow_n, t + 3);
	s_ashr_i32 s43, s42, 31
	s_lshl_b64 s[40:41], s[42:43], 12
	s_add_u32 s3, s72, s40
	s_addc_u32 s18, s73, s41
	s_add_u32 s40, s3, s4
	s_addc_u32 s41, s18, s5
	s_mov_b32 m0, s16
	v_lshl_add_u64 v[134:135], s[40:41], 0, v[128:129]
	global_load_lds_dwordx4 v[134:135], off
	v_lshl_add_u64 v[134:135], v[134:135], 0, s[86:87]
	s_mov_b32 m0, s17
	s_nop 0
	global_load_lds_dwordx4 v[134:135], off
	s_waitcnt vmcnt(6)
	s_barrier
	v_mfma_f32_16x16x32_bf16 v[28:31], v[160:163], v[210:213], v[28:31]
	v_mfma_f32_16x16x32_bf16 v[24:27], v[160:163], v[218:221], v[24:27]
	v_mfma_f32_16x16x32_bf16 v[20:23], v[172:175], v[210:213], v[20:23]
	v_mfma_f32_16x16x32_bf16 v[16:19], v[172:175], v[218:221], v[16:19]
	v_mfma_f32_16x16x32_bf16 v[12:15], v[180:183], v[210:213], v[12:15]
	v_mfma_f32_16x16x32_bf16 v[8:11], v[180:183], v[218:221], v[8:11]
	v_mfma_f32_16x16x32_bf16 v[4:7], v[188:191], v[210:213], v[4:7]
	v_mfma_f32_16x16x32_bf16 v[0:3], v[188:191], v[218:221], v[0:3]
	v_mfma_f32_16x16x32_bf16 v[28:31], v[168:171], v[214:217], v[28:31]
	v_mfma_f32_16x16x32_bf16 v[24:27], v[168:171], v[222:225], v[24:27]
	v_mfma_f32_16x16x32_bf16 v[20:23], v[176:179], v[214:217], v[20:23]
	v_mfma_f32_16x16x32_bf16 v[16:19], v[176:179], v[222:225], v[16:19]
	v_mfma_f32_16x16x32_bf16 v[12:15], v[184:187], v[214:217], v[12:15]
	v_mfma_f32_16x16x32_bf16 v[8:11], v[184:187], v[222:225], v[8:11]
	v_mfma_f32_16x16x32_bf16 v[4:7], v[192:195], v[214:217], v[4:7]
	v_mfma_f32_16x16x32_bf16 v[0:3], v[192:195], v[222:225], v[0:3]
	v_add_u32_e32 v142, s83, v147
	s_barrier
	ds_read_b128 v[134:137], v142
	ds_read_b128 v[138:141], v142 offset:1024
	ds_read_b128 v[152:155], v142 offset:2048
	ds_read_b128 v[156:159], v142 offset:3072
	s_ashr_i32 s3, s2, 31
	s_lshl_b64 s[2:3], s[2:3], 12
	s_add_u32 s2, s71, s2
	s_addc_u32 s3, s74, s3
	s_add_u32 s2, s2, s4
	s_addc_u32 s3, s3, s5
	s_mov_b32 m0, s20
	v_lshl_add_u64 v[142:143], s[2:3], 0, v[128:129]
	ds_read_b128 v[160:163], v144 offset:32768
	ds_read_b128 v[168:171], v144 offset:33792
	ds_read_b128 v[172:175], v148 offset:32768
	ds_read_b128 v[176:179], v148 offset:33792
	ds_read_b128 v[180:183], v149 offset:32768
	ds_read_b128 v[184:187], v149 offset:33792
	ds_read_b128 v[188:191], v150 offset:32768
	ds_read_b128 v[192:195], v150 offset:33792
	global_load_lds_dwordx4 v[142:143], off
	v_lshl_add_u64 v[142:143], v[142:143], 0, s[86:87]
	s_mov_b32 m0, s21
	s_nop 0
	global_load_lds_dwordx4 v[142:143], off
	s_waitcnt lgkmcnt(8)
	s_barrier
	s_waitcnt lgkmcnt(0)
	v_mfma_f32_16x16x32_bf16 v[124:127], v[160:163], v[134:137], v[124:127]
	v_mfma_f32_16x16x32_bf16 v[120:123], v[160:163], v[152:155], v[120:123]
	v_mfma_f32_16x16x32_bf16 v[116:119], v[172:175], v[134:137], v[116:119]
	v_mfma_f32_16x16x32_bf16 v[112:115], v[172:175], v[152:155], v[112:115]
	v_mfma_f32_16x16x32_bf16 v[108:111], v[180:183], v[134:137], v[108:111]
	v_mfma_f32_16x16x32_bf16 v[104:107], v[180:183], v[152:155], v[104:107]
	v_mfma_f32_16x16x32_bf16 v[100:103], v[188:191], v[134:137], v[100:103]
	v_mfma_f32_16x16x32_bf16 v[96:99], v[188:191], v[152:155], v[96:99]
	v_mfma_f32_16x16x32_bf16 v[124:127], v[168:171], v[138:141], v[124:127]
	v_mfma_f32_16x16x32_bf16 v[120:123], v[168:171], v[156:159], v[120:123]
	v_mfma_f32_16x16x32_bf16 v[116:119], v[176:179], v[138:141], v[116:119]
	v_mfma_f32_16x16x32_bf16 v[112:115], v[176:179], v[156:159], v[112:115]
	v_mfma_f32_16x16x32_bf16 v[108:111], v[184:187], v[138:141], v[108:111]
	v_mfma_f32_16x16x32_bf16 v[104:107], v[184:187], v[156:159], v[104:107]
	v_mfma_f32_16x16x32_bf16 v[100:103], v[192:195], v[138:141], v[100:103]
	v_mfma_f32_16x16x32_bf16 v[96:99], v[192:195], v[156:159], v[96:99]
	s_barrier
	s_cmp_lt_u32 s1, 29
	s_cselect_b32 s2, s29, s31
	s_cselect_b32 s5, 0, 0xffffffe0
	s_cselect_b32 s4, s0, s30
	s_cselect_b32 s40, s36, s35
	s_ashr_i32 s3, s2, 31
	s_lshl_b64 s[2:3], s[2:3], 12
	s_add_u32 s39, s72, s2
	s_addc_u32 s41, s73, s3
	s_add_i32 s1, s5, s1
	s_add_i32 s18, s1, 3
	s_lshl_b64 s[2:3], s[18:19], 7
	s_add_u32 s42, s39, s2
	v_add_u32_e32 v142, s84, v147
	s_addc_u32 s43, s41, s3
	s_mov_b32 m0, s22
	ds_read_b128 v[210:213], v142
	ds_read_b128 v[214:217], v142 offset:1024
	ds_read_b128 v[218:221], v142 offset:2048
	ds_read_b128 v[222:225], v142 offset:3072
	v_lshl_add_u64 v[142:143], s[42:43], 0, v[128:129]
	global_load_lds_dwordx4 v[142:143], off
	v_lshl_add_u64 v[142:143], v[142:143], 0, s[86:87]
	s_mov_b32 m0, s23
	s_nop 0
	global_load_lds_dwordx4 v[142:143], off
	s_barrier
	s_waitcnt lgkmcnt(0)
	v_mfma_f32_16x16x32_bf16 v[92:95], v[160:163], v[210:213], v[92:95]
	v_mfma_f32_16x16x32_bf16 v[88:91], v[160:163], v[218:221], v[88:91]
	v_mfma_f32_16x16x32_bf16 v[84:87], v[172:175], v[210:213], v[84:87]
	v_mfma_f32_16x16x32_bf16 v[80:83], v[172:175], v[218:221], v[80:83]
	v_mfma_f32_16x16x32_bf16 v[76:79], v[180:183], v[210:213], v[76:79]
	v_mfma_f32_16x16x32_bf16 v[72:75], v[180:183], v[218:221], v[72:75]
	v_mfma_f32_16x16x32_bf16 v[68:71], v[188:191], v[210:213], v[68:71]
	v_mfma_f32_16x16x32_bf16 v[64:67], v[188:191], v[218:221], v[64:67]
	v_mfma_f32_16x16x32_bf16 v[92:95], v[168:171], v[214:217], v[92:95]
	v_mfma_f32_16x16x32_bf16 v[88:91], v[168:171], v[222:225], v[88:91]
	v_mfma_f32_16x16x32_bf16 v[84:87], v[176:179], v[214:217], v[84:87]
	v_mfma_f32_16x16x32_bf16 v[80:83], v[176:179], v[222:225], v[80:83]
	v_mfma_f32_16x16x32_bf16 v[76:79], v[184:187], v[214:217], v[76:79]
	v_mfma_f32_16x16x32_bf16 v[72:75], v[184:187], v[222:225], v[72:75]
	v_mfma_f32_16x16x32_bf16 v[68:71], v[192:195], v[214:217], v[68:71]
	v_mfma_f32_16x16x32_bf16 v[64:67], v[192:195], v[222:225], v[64:67]
	s_ashr_i32 s5, s4, 31
	s_lshl_b64 s[4:5], s[4:5], 12
	s_add_u32 s1, s71, s4
	s_addc_u32 s5, s74, s5
	s_add_u32 s4, s1, s2
	s_addc_u32 s5, s5, s3
	s_mov_b32 m0, s24
	v_lshl_add_u64 v[142:143], s[4:5], 0, v[128:129]
	s_barrier
; #define LDA(dst, b, h) _Pragma("unroll") for (int m = 0; m < 4; ++m) _Pragma("unroll") for (int k = 0; k < 2; ++k) \
;     dst[m][k] = *reinterpret_cast<const bf16x8*>((char*)SA(b, h) + lds_byte(wr * 64 + m * 16 + fr, k * 32 + fq * 8))
; #define MMA(ai, bj, At_, Bt_) do { __builtin_amdgcn_s_setprio(1); \
;     _Pragma("unroll") for (int m = 0; m < 4; ++m) _Pragma("unroll") for (int n = 0; n < 2; ++n) _Pragma("unroll") for (int k = 0; k < 2; ++k) \
;       acc[ai][bj][m][n] = __builtin_amdgcn_mfma_f32_16x16x32_bf16(At_[m][k], Bt_[n][k], acc[ai][bj][m][n], 0, 0, 0); \
;     __builtin_amdgcn_s_setprio(0); } while (0)
; #define WAIT_V(n) asm volatile("s_waitcnt vmcnt(" #n ")" ::: "memory")
; #define WAIT_L(n) asm volatile("s_waitcnt lgkmcnt(" #n ")" ::: "memory")
; #define BAR __builtin_amdgcn_s_barrier()
; #define SCHED __builtin_amdgcn_sched_barrier(0)
; #define STAGEW(P_, BASE, cur, nxt, kt_) do { const bool _wr = (kt_) >= nt; \
;     STAGE(P_, BASE, (_wr ? (nxt) : (cur)), (_wr ? (kt_) - nt : (kt_))); } while (0)
; #define WIDE_STORE(BASE, LD, COFF, O) do { if ((m & 1) == 0) opend[n] = (O); \
;                 else *(uint4*)((BASE) + (size_t)tok * (LD) + (ncw - (COFF))) = swap_pair(opend[n], (O)); } while (0)
; template <int PRE> ...
;     ...
;     LDA(At, 1, 1); STAGEW(SA(1, 0), A, brow, brow_n, t + 3);
;     BAR; WAIT_L(0); MMA(1, 0, At, B0); BAR; SCHED;
;     STAGEW(SB(1, 1), Bt, bcol + HALF, bcol_n + HALF, t + 3);
;     WAIT_V(6); BAR; MMA(1, 1, At, B1); BAR;
;   }
;   if (wr == 0) BAR;
;     ...
;               } else if (MODE == 3) {
;                 float4 r = ldnt4(xin + (size_t)tok * DM + nc);
;                 uint2 hb; hb.x = pk2(r.x + v[0], r.y + v[1]); hb.y = pk2(r.z + v[2], r.w + v[3]);
;                 WIDE_STORE((u16*)(ws + OFF_RB), DM, 0, hb);
	ds_read_b128 v[160:163], v144 offset:49152
	ds_read_b128 v[168:171], v144 offset:50176
	ds_read_b128 v[172:175], v148 offset:49152
	ds_read_b128 v[176:179], v148 offset:50176
	ds_read_b128 v[180:183], v149 offset:49152
	ds_read_b128 v[184:187], v149 offset:50176
	ds_read_b128 v[188:191], v150 offset:49152
	ds_read_b128 v[192:195], v150 offset:50176
	global_load_lds_dwordx4 v[142:143], off
	v_lshl_add_u64 v[142:143], v[142:143], 0, s[86:87]
	s_mov_b32 m0, s25
	s_nop 0
	global_load_lds_dwordx4 v[142:143], off
	s_barrier
	s_waitcnt lgkmcnt(0)
	v_mfma_f32_16x16x32_bf16 v[60:63], v[160:163], v[134:137], v[60:63]
	v_mfma_f32_16x16x32_bf16 v[56:59], v[160:163], v[152:155], v[56:59]
	v_mfma_f32_16x16x32_bf16 v[52:55], v[172:175], v[134:137], v[52:55]
	v_mfma_f32_16x16x32_bf16 v[48:51], v[172:175], v[152:155], v[48:51]
	v_mfma_f32_16x16x32_bf16 v[44:47], v[180:183], v[134:137], v[44:47]
	v_mfma_f32_16x16x32_bf16 v[40:43], v[180:183], v[152:155], v[40:43]
	v_mfma_f32_16x16x32_bf16 v[36:39], v[188:191], v[134:137], v[36:39]
	v_mfma_f32_16x16x32_bf16 v[32:35], v[188:191], v[152:155], v[32:35]
	v_mfma_f32_16x16x32_bf16 v[60:63], v[168:171], v[138:141], v[60:63]
	v_mfma_f32_16x16x32_bf16 v[56:59], v[168:171], v[156:159], v[56:59]
	v_mfma_f32_16x16x32_bf16 v[52:55], v[176:179], v[138:141], v[52:55]
	v_mfma_f32_16x16x32_bf16 v[48:51], v[176:179], v[156:159], v[48:51]
	v_mfma_f32_16x16x32_bf16 v[44:47], v[184:187], v[138:141], v[44:47]
	v_mfma_f32_16x16x32_bf16 v[40:43], v[184:187], v[156:159], v[40:43]
	v_mfma_f32_16x16x32_bf16 v[36:39], v[192:195], v[138:141], v[36:39]
	v_mfma_f32_16x16x32_bf16 v[32:35], v[192:195], v[156:159], v[32:35]
	s_barrier
	s_ashr_i32 s41, s40, 31
	s_lshl_b64 s[4:5], s[40:41], 12
	s_add_u32 s1, s72, s4
	s_addc_u32 s4, s73, s5
	s_add_u32 s2, s1, s2
	s_addc_u32 s3, s4, s3
	s_mov_b32 m0, s26
	v_lshl_add_u64 v[134:135], s[2:3], 0, v[128:129]
	global_load_lds_dwordx4 v[134:135], off
	v_lshl_add_u64 v[134:135], v[134:135], 0, s[86:87]
	s_mov_b32 m0, s27
	s_nop 0
	global_load_lds_dwordx4 v[134:135], off
	s_waitcnt vmcnt(6)
	s_barrier
	v_mfma_f32_16x16x32_bf16 v[28:31], v[160:163], v[210:213], v[28:31]
	v_mfma_f32_16x16x32_bf16 v[24:27], v[160:163], v[218:221], v[24:27]
	v_mfma_f32_16x16x32_bf16 v[20:23], v[172:175], v[210:213], v[20:23]
	v_mfma_f32_16x16x32_bf16 v[16:19], v[172:175], v[218:221], v[16:19]
	v_mfma_f32_16x16x32_bf16 v[12:15], v[180:183], v[210:213], v[12:15]
	v_mfma_f32_16x16x32_bf16 v[8:11], v[180:183], v[218:221], v[8:11]
	v_mfma_f32_16x16x32_bf16 v[4:7], v[188:191], v[210:213], v[4:7]
	v_mfma_f32_16x16x32_bf16 v[0:3], v[188:191], v[218:221], v[0:3]
	v_mfma_f32_16x16x32_bf16 v[28:31], v[168:171], v[214:217], v[28:31]
	v_mfma_f32_16x16x32_bf16 v[24:27], v[168:171], v[222:225], v[24:27]
	v_mfma_f32_16x16x32_bf16 v[20:23], v[176:179], v[214:217], v[20:23]
	v_mfma_f32_16x16x32_bf16 v[16:19], v[176:179], v[222:225], v[16:19]
	v_mfma_f32_16x16x32_bf16 v[12:15], v[184:187], v[214:217], v[12:15]
	v_mfma_f32_16x16x32_bf16 v[8:11], v[184:187], v[222:225], v[8:11]
	v_mfma_f32_16x16x32_bf16 v[4:7], v[192:195], v[214:217], v[4:7]
	v_mfma_f32_16x16x32_bf16 v[0:3], v[192:195], v[222:225], v[0:3]
	v_lshl_add_u64 v[132:133], v[132:133], 0, s[46:47]
	s_mov_b32 s1, s38
	s_barrier
	s_cbranch_vccnz .LBB0_892
	v_readlane_b32 s34, v243, 2
	v_readlane_b32 s2, v245, 25
	v_readlane_b32 s3, v245, 26
	s_add_i32 s0, s0, s49
	v_and_b32_e32 v192, 15, v146
	v_or_b32_e32 v192, s54, v192
	v_or_b32_e32 v192, s29, v192
	v_lshrrev_b32_e32 v193, 2, v146
	v_and_b32_e32 v194, -4, v193
	v_add_u32_e32 v194, s0, v194
	v_and_b32_e32 v193, -8, v193
	v_and_b32_e32 v195, 16, v146
	v_add3_u32 v193, v193, v195, s0
	v_lshlrev_b32_e32 v195, 13, v192
	v_lshl_add_u32 v138, v194, 2, v195
	v_add_u32_e32 v139, 0x20000, v138
	v_add_u32_e32 v140, 0x100000, v138
	v_add_u32_e32 v141, 0x120000, v138
	v_lshlrev_b32_e32 v195, 12, v192
	v_lshl_add_u32 v142, v193, 1, v195
	v_add_u32_e32 v143, 0x10000, v142
	v_add_u32_e32 v190, 0x80000, v142
	v_add_u32_e32 v191, 0x90000, v142
	global_load_dwordx4 v[210:213], v138, s[6:7] offset:0 nt
	global_load_dwordx4 v[214:217], v138, s[6:7] offset:64 nt
	global_load_dwordx4 v[218:221], v138, s[6:7] offset:128 nt
	global_load_dwordx4 v[222:225], v138, s[6:7] offset:192 nt
	global_load_dwordx4 v[226:229], v139, s[6:7] offset:0 nt
	global_load_dwordx4 v[230:233], v139, s[6:7] offset:64 nt
	global_load_dwordx4 v[234:237], v139, s[6:7] offset:128 nt
	global_load_dwordx4 v[238:241], v139, s[6:7] offset:192 nt
	global_load_dwordx4 v[168:171], v140, s[6:7] offset:0 nt
	global_load_dwordx4 v[172:175], v140, s[6:7] offset:64 nt
	global_load_dwordx4 v[176:179], v140, s[6:7] offset:128 nt
	global_load_dwordx4 v[180:183], v140, s[6:7] offset:192 nt
	global_load_dwordx4 v[152:155], v141, s[6:7] offset:0 nt
	global_load_dwordx4 v[156:159], v141, s[6:7] offset:64 nt
	global_load_dwordx4 v[160:163], v141, s[6:7] offset:128 nt
	global_load_dwordx4 v[134:137], v141, s[6:7] offset:192 nt
	s_andn2_b64 vcc, exec, s[58:59]
	v_readlane_b32 s31, v244, 61
	v_readlane_b32 s35, v243, 3
	s_cbranch_vccnz .LBB0_895
	s_barrier
; #define WIDE_STORE(BASE, LD, COFF, O) do { if ((m & 1) == 0) opend[n] = (O); \
;                 else *(uint4*)((BASE) + (size_t)tok * (LD) + (ncw - (COFF))) = swap_pair(opend[n], (O)); } while (0)
; __device__ __forceinline__ uint4 swap_pair(const uint2 a, const uint2 b) {
;   const auto rx = __builtin_amdgcn_permlane16_swap(a.x, b.x, false, false);
;   const auto ry = __builtin_amdgcn_permlane16_swap(a.y, b.y, false, false);
;   return make_uint4(rx[0], ry[0], rx[1], ry[1]);
; }
;     ...
;               } else if (MODE == 3) {
;                 float4 r = ldnt4(xin + (size_t)tok * DM + nc);
;                 uint2 hb; hb.x = pk2(r.x + v[0], r.y + v[1]); hb.y = pk2(r.z + v[2], r.w + v[3]);
;                 WIDE_STORE((u16*)(ws + OFF_RB), DM, 0, hb);
.LBB0_895:
	s_waitcnt vmcnt(15)
	v_pk_add_f32 v[124:125], v[124:125], v[210:211]
	v_pk_add_f32 v[126:127], v[126:127], v[212:213]
	global_load_dwordx4 v[210:213], v138, s[6:7] offset:512 nt
	s_waitcnt vmcnt(15)
	v_pk_add_f32 v[116:117], v[116:117], v[214:215]
	v_pk_add_f32 v[118:119], v[118:119], v[216:217]
	global_load_dwordx4 v[214:217], v138, s[6:7] offset:576 nt
	s_waitcnt vmcnt(15)
	v_pk_add_f32 v[108:109], v[108:109], v[218:219]
	v_pk_add_f32 v[110:111], v[110:111], v[220:221]
	global_load_dwordx4 v[218:221], v138, s[6:7] offset:640 nt
	s_waitcnt vmcnt(15)
	v_pk_add_f32 v[100:101], v[100:101], v[222:223]
	v_pk_add_f32 v[102:103], v[102:103], v[224:225]
	global_load_dwordx4 v[222:225], v138, s[6:7] offset:704 nt
	s_waitcnt vmcnt(15)
	v_pk_add_f32 v[120:121], v[120:121], v[226:227]
	v_pk_add_f32 v[122:123], v[122:123], v[228:229]
	global_load_dwordx4 v[226:229], v139, s[6:7] offset:512 nt
	s_waitcnt vmcnt(15)
	v_pk_add_f32 v[112:113], v[112:113], v[230:231]
	v_pk_add_f32 v[114:115], v[114:115], v[232:233]
	global_load_dwordx4 v[230:233], v139, s[6:7] offset:576 nt
	s_waitcnt vmcnt(15)
	v_pk_add_f32 v[104:105], v[104:105], v[234:235]
	v_pk_add_f32 v[106:107], v[106:107], v[236:237]
	global_load_dwordx4 v[234:237], v139, s[6:7] offset:640 nt
	s_waitcnt vmcnt(15)
	v_pk_add_f32 v[96:97], v[96:97], v[238:239]
	v_pk_add_f32 v[98:99], v[98:99], v[240:241]
	global_load_dwordx4 v[238:241], v139, s[6:7] offset:704 nt
	s_waitcnt vmcnt(15)
	v_pk_add_f32 v[92:93], v[92:93], v[168:169]
	v_pk_add_f32 v[94:95], v[94:95], v[170:171]
	global_load_dwordx4 v[168:171], v140, s[6:7] offset:512 nt
	s_waitcnt vmcnt(15)
	v_pk_add_f32 v[84:85], v[84:85], v[172:173]
	v_pk_add_f32 v[86:87], v[86:87], v[174:175]
	global_load_dwordx4 v[172:175], v140, s[6:7] offset:576 nt
	s_waitcnt vmcnt(15)
	v_pk_add_f32 v[76:77], v[76:77], v[176:177]
	v_pk_add_f32 v[78:79], v[78:79], v[178:179]
	global_load_dwordx4 v[176:179], v140, s[6:7] offset:640 nt
	s_waitcnt vmcnt(15)
	v_pk_add_f32 v[68:69], v[68:69], v[180:181]
	v_pk_add_f32 v[70:71], v[70:71], v[182:183]
	global_load_dwordx4 v[180:183], v140, s[6:7] offset:704 nt
	s_waitcnt vmcnt(15)
	v_pk_add_f32 v[88:89], v[88:89], v[152:153]
	v_pk_add_f32 v[90:91], v[90:91], v[154:155]
	global_load_dwordx4 v[152:155], v141, s[6:7] offset:512 nt
	s_waitcnt vmcnt(15)
	v_pk_add_f32 v[80:81], v[80:81], v[156:157]
	v_pk_add_f32 v[82:83], v[82:83], v[158:159]
	global_load_dwordx4 v[156:159], v141, s[6:7] offset:576 nt
	s_waitcnt vmcnt(15)
	v_pk_add_f32 v[72:73], v[72:73], v[160:161]
	v_pk_add_f32 v[74:75], v[74:75], v[162:163]
	global_load_dwordx4 v[160:163], v141, s[6:7] offset:640 nt
	s_waitcnt vmcnt(15)
	v_pk_add_f32 v[64:65], v[64:65], v[134:135]
	v_pk_add_f32 v[66:67], v[66:67], v[136:137]
	global_load_dwordx4 v[134:137], v141, s[6:7] offset:704 nt
	v_cvt_pk_bf16_f32 v124, v124, v125
	v_cvt_pk_bf16_f32 v125, v126, v127
	v_cvt_pk_bf16_f32 v126, v116, v117
	v_cvt_pk_bf16_f32 v127, v118, v119
	v_cvt_pk_bf16_f32 v108, v108, v109
	v_cvt_pk_bf16_f32 v109, v110, v111
	v_cvt_pk_bf16_f32 v110, v100, v101
	v_cvt_pk_bf16_f32 v111, v102, v103
	s_nop 1
	v_permlane16_swap_b32_e32 v124, v126
	v_permlane16_swap_b32_e32 v125, v127
	v_permlane16_swap_b32_e32 v108, v110
	v_permlane16_swap_b32_e32 v109, v111
	global_store_dwordx4 v142, v[124:127], s[2:3] offset:0
	global_store_dwordx4 v142, v[108:111], s[2:3] offset:64
	v_cvt_pk_bf16_f32 v120, v120, v121
	v_cvt_pk_bf16_f32 v121, v122, v123
	v_cvt_pk_bf16_f32 v122, v112, v113
	v_cvt_pk_bf16_f32 v123, v114, v115
	v_cvt_pk_bf16_f32 v104, v104, v105
	v_cvt_pk_bf16_f32 v105, v106, v107
	v_cvt_pk_bf16_f32 v106, v96, v97
	v_cvt_pk_bf16_f32 v107, v98, v99
	s_nop 1
	v_permlane16_swap_b32_e32 v120, v122
	v_permlane16_swap_b32_e32 v121, v123
	v_permlane16_swap_b32_e32 v104, v106
	v_permlane16_swap_b32_e32 v105, v107
	global_store_dwordx4 v143, v[120:123], s[2:3] offset:0
	global_store_dwordx4 v143, v[104:107], s[2:3] offset:64
	v_cvt_pk_bf16_f32 v92, v92, v93
	v_cvt_pk_bf16_f32 v93, v94, v95
	v_cvt_pk_bf16_f32 v94, v84, v85
	v_cvt_pk_bf16_f32 v95, v86, v87
	v_cvt_pk_bf16_f32 v76, v76, v77
	v_cvt_pk_bf16_f32 v77, v78, v79
	v_cvt_pk_bf16_f32 v78, v68, v69
	v_cvt_pk_bf16_f32 v79, v70, v71
	s_nop 1
	v_permlane16_swap_b32_e32 v92, v94
	v_permlane16_swap_b32_e32 v93, v95
	v_permlane16_swap_b32_e32 v76, v78
	v_permlane16_swap_b32_e32 v77, v79
	global_store_dwordx4 v190, v[92:95], s[2:3] offset:0
	global_store_dwordx4 v190, v[76:79], s[2:3] offset:64
	v_cvt_pk_bf16_f32 v88, v88, v89
	v_cvt_pk_bf16_f32 v89, v90, v91
	v_cvt_pk_bf16_f32 v90, v80, v81
	v_cvt_pk_bf16_f32 v91, v82, v83
	v_cvt_pk_bf16_f32 v72, v72, v73
	v_cvt_pk_bf16_f32 v73, v74, v75
	v_cvt_pk_bf16_f32 v74, v64, v65
	v_cvt_pk_bf16_f32 v75, v66, v67
	s_nop 1
	v_permlane16_swap_b32_e32 v88, v90
	v_permlane16_swap_b32_e32 v89, v91
	v_permlane16_swap_b32_e32 v72, v74
	v_permlane16_swap_b32_e32 v73, v75
	global_store_dwordx4 v191, v[88:91], s[2:3] offset:0
	global_store_dwordx4 v191, v[72:75], s[2:3] offset:64
	s_waitcnt vmcnt(23)
	v_pk_add_f32 v[60:61], v[60:61], v[210:211]
	v_pk_add_f32 v[62:63], v[62:63], v[212:213]
	s_waitcnt vmcnt(22)
	v_pk_add_f32 v[52:53], v[52:53], v[214:215]
	v_pk_add_f32 v[54:55], v[54:55], v[216:217]
	s_waitcnt vmcnt(21)
	v_pk_add_f32 v[44:45], v[44:45], v[218:219]
	v_pk_add_f32 v[46:47], v[46:47], v[220:221]
	s_waitcnt vmcnt(20)
	v_pk_add_f32 v[36:37], v[36:37], v[222:223]
	v_pk_add_f32 v[38:39], v[38:39], v[224:225]
	s_waitcnt vmcnt(19)
	v_pk_add_f32 v[56:57], v[56:57], v[226:227]
	v_pk_add_f32 v[58:59], v[58:59], v[228:229]
	s_waitcnt vmcnt(18)
	v_pk_add_f32 v[48:49], v[48:49], v[230:231]
	v_pk_add_f32 v[50:51], v[50:51], v[232:233]
	s_waitcnt vmcnt(17)
; __device__ __forceinline__ float bflo(unsigned u) { return __uint_as_float(u << 16); }
; __device__ __forceinline__ float bfhi(unsigned u) { return __uint_as_float(u & 0xffff0000u); }
; #define WIDE_STORE(BASE, LD, COFF, O) do { if ((m & 1) == 0) opend[n] = (O); \
;                 else *(uint4*)((BASE) + (size_t)tok * (LD) + (ncw - (COFF))) = swap_pair(opend[n], (O)); } while (0)
;     ...
; #pragma unroll
;     for (int a = 0; a < 2; ++a)
; #pragma unroll
;       for (int b = 0; b < 2; ++b)
; #pragma unroll
;         for (int m = 0; m < 4; ++m)
; #pragma unroll
;           for (int n = 0; n < 2; ++n) acc[a][b][m][n] = f32x4{0.f, 0.f, 0.f, 0.f};
;     ...
;               } else if (MODE == 3) {
;                 float4 r = ldnt4(xin + (size_t)tok * DM + nc);
;                 uint2 hb; hb.x = pk2(r.x + v[0], r.y + v[1]); hb.y = pk2(r.z + v[2], r.w + v[3]);
;                 WIDE_STORE((u16*)(ws + OFF_RB), DM, 0, hb);
;               } else {
;                 uint2* ph = (uint2*)((u16*)(ws + OFF_RB) + (size_t)tok * DM + nc);
;                 const uint2 hb = *ph;
;                 uint2 o; o.x = pk2(bflo(hb.x) + v[0], bfhi(hb.x) + v[1]); o.y = pk2(bflo(hb.y) + v[2], bfhi(hb.y) + v[3]);
;                 WIDE_STORE((u16*)(ws + OFF_RB), DM, 0, o);
;               }
;     ...
;             }
;     }
;     asm volatile("s_waitcnt vmcnt(0)" ::: "memory");
;     if (has_next && wr == 1) __builtin_amdgcn_s_barrier();
	v_pk_add_f32 v[40:41], v[40:41], v[234:235]
	v_pk_add_f32 v[42:43], v[42:43], v[236:237]
	s_waitcnt vmcnt(16)
	v_pk_add_f32 v[32:33], v[32:33], v[238:239]
	v_pk_add_f32 v[34:35], v[34:35], v[240:241]
	s_waitcnt vmcnt(15)
	v_pk_add_f32 v[28:29], v[28:29], v[168:169]
	v_pk_add_f32 v[30:31], v[30:31], v[170:171]
	s_waitcnt vmcnt(14)
	v_pk_add_f32 v[20:21], v[20:21], v[172:173]
	v_pk_add_f32 v[22:23], v[22:23], v[174:175]
	s_waitcnt vmcnt(13)
	v_pk_add_f32 v[12:13], v[12:13], v[176:177]
	v_pk_add_f32 v[14:15], v[14:15], v[178:179]
	s_waitcnt vmcnt(12)
	v_pk_add_f32 v[4:5], v[4:5], v[180:181]
	v_pk_add_f32 v[6:7], v[6:7], v[182:183]
	s_waitcnt vmcnt(11)
	v_pk_add_f32 v[24:25], v[24:25], v[152:153]
	v_pk_add_f32 v[26:27], v[26:27], v[154:155]
	s_waitcnt vmcnt(10)
	v_pk_add_f32 v[16:17], v[16:17], v[156:157]
	v_pk_add_f32 v[18:19], v[18:19], v[158:159]
	s_waitcnt vmcnt(9)
	v_pk_add_f32 v[8:9], v[8:9], v[160:161]
	v_pk_add_f32 v[10:11], v[10:11], v[162:163]
	s_waitcnt vmcnt(8)
	v_pk_add_f32 v[0:1], v[0:1], v[134:135]
	v_pk_add_f32 v[2:3], v[2:3], v[136:137]
	v_cvt_pk_bf16_f32 v60, v60, v61
	v_cvt_pk_bf16_f32 v61, v62, v63
	v_cvt_pk_bf16_f32 v62, v52, v53
	v_cvt_pk_bf16_f32 v63, v54, v55
	v_cvt_pk_bf16_f32 v44, v44, v45
	v_cvt_pk_bf16_f32 v45, v46, v47
	v_cvt_pk_bf16_f32 v46, v36, v37
	v_cvt_pk_bf16_f32 v47, v38, v39
	s_nop 1
	v_permlane16_swap_b32_e32 v60, v62
	v_permlane16_swap_b32_e32 v61, v63
	v_permlane16_swap_b32_e32 v44, v46
	v_permlane16_swap_b32_e32 v45, v47
	global_store_dwordx4 v142, v[60:63], s[2:3] offset:256
	global_store_dwordx4 v142, v[44:47], s[2:3] offset:320
	v_cvt_pk_bf16_f32 v56, v56, v57
	v_cvt_pk_bf16_f32 v57, v58, v59
	v_cvt_pk_bf16_f32 v58, v48, v49
	v_cvt_pk_bf16_f32 v59, v50, v51
	v_cvt_pk_bf16_f32 v40, v40, v41
	v_cvt_pk_bf16_f32 v41, v42, v43
	v_cvt_pk_bf16_f32 v42, v32, v33
	v_cvt_pk_bf16_f32 v43, v34, v35
	s_nop 1
	v_permlane16_swap_b32_e32 v56, v58
	v_permlane16_swap_b32_e32 v57, v59
	v_permlane16_swap_b32_e32 v40, v42
	v_permlane16_swap_b32_e32 v41, v43
	global_store_dwordx4 v143, v[56:59], s[2:3] offset:256
	global_store_dwordx4 v143, v[40:43], s[2:3] offset:320
	v_cvt_pk_bf16_f32 v28, v28, v29
	v_cvt_pk_bf16_f32 v29, v30, v31
	v_cvt_pk_bf16_f32 v30, v20, v21
	v_cvt_pk_bf16_f32 v31, v22, v23
	v_cvt_pk_bf16_f32 v12, v12, v13
	v_cvt_pk_bf16_f32 v13, v14, v15
	v_cvt_pk_bf16_f32 v14, v4, v5
	v_cvt_pk_bf16_f32 v15, v6, v7
	s_nop 1
	v_permlane16_swap_b32_e32 v28, v30
	v_permlane16_swap_b32_e32 v29, v31
	v_permlane16_swap_b32_e32 v12, v14
	v_permlane16_swap_b32_e32 v13, v15
	global_store_dwordx4 v190, v[28:31], s[2:3] offset:256
	global_store_dwordx4 v190, v[12:15], s[2:3] offset:320
	v_cvt_pk_bf16_f32 v24, v24, v25
	v_cvt_pk_bf16_f32 v25, v26, v27
	v_cvt_pk_bf16_f32 v26, v16, v17
	v_cvt_pk_bf16_f32 v27, v18, v19
	v_cvt_pk_bf16_f32 v8, v8, v9
	v_cvt_pk_bf16_f32 v9, v10, v11
	v_cvt_pk_bf16_f32 v10, v0, v1
	v_cvt_pk_bf16_f32 v11, v2, v3
	s_nop 1
	v_permlane16_swap_b32_e32 v24, v26
	v_permlane16_swap_b32_e32 v25, v27
	v_permlane16_swap_b32_e32 v8, v10
	v_permlane16_swap_b32_e32 v9, v11
	global_store_dwordx4 v191, v[24:27], s[2:3] offset:256
	global_store_dwordx4 v191, v[8:11], s[2:3] offset:320
	s_and_b64 s[0:1], s[56:57], s[10:11]
	s_andn2_b64 vcc, exec, s[0:1]
	s_nop 1
	v_mov_b32_e32 v0, 0
	v_mov_b32_e32 v1, v0
	v_mov_b32_e32 v2, v0
	v_mov_b32_e32 v3, v0
	v_mov_b32_e32 v4, v0
	v_mov_b32_e32 v5, v0
	v_mov_b32_e32 v6, v0
	v_mov_b32_e32 v7, v0
	v_mov_b32_e32 v8, v0
	v_mov_b32_e32 v9, v0
	v_mov_b32_e32 v10, v0
	v_mov_b32_e32 v11, v0
	v_mov_b32_e32 v12, v0
	v_mov_b32_e32 v13, v0
	v_mov_b32_e32 v14, v0
	v_mov_b32_e32 v15, v0
	v_mov_b32_e32 v16, v0
	v_mov_b32_e32 v17, v0
	v_mov_b32_e32 v18, v0
	v_mov_b32_e32 v19, v0
	v_mov_b32_e32 v20, v0
	v_mov_b32_e32 v21, v0
	v_mov_b32_e32 v22, v0
	v_mov_b32_e32 v23, v0
	v_mov_b32_e32 v24, v0
	v_mov_b32_e32 v25, v0
	v_mov_b32_e32 v26, v0
	v_mov_b32_e32 v27, v0
	v_mov_b32_e32 v28, v0
	v_mov_b32_e32 v29, v0
	v_mov_b32_e32 v30, v0
	v_mov_b32_e32 v31, v0
	v_mov_b32_e32 v32, v0
	v_mov_b32_e32 v33, v0
	v_mov_b32_e32 v34, v0
	v_mov_b32_e32 v35, v0
	v_mov_b32_e32 v36, v0
	v_mov_b32_e32 v37, v0
	v_mov_b32_e32 v38, v0
	v_mov_b32_e32 v39, v0
	v_mov_b32_e32 v40, v0
	v_mov_b32_e32 v41, v0
	v_mov_b32_e32 v42, v0
	v_mov_b32_e32 v43, v0
	v_mov_b32_e32 v44, v0
	v_mov_b32_e32 v45, v0
	v_mov_b32_e32 v46, v0
	v_mov_b32_e32 v47, v0
	v_mov_b32_e32 v48, v0
	v_mov_b32_e32 v49, v0
	v_mov_b32_e32 v50, v0
	v_mov_b32_e32 v51, v0
	v_mov_b32_e32 v52, v0
	v_mov_b32_e32 v53, v0
	v_mov_b32_e32 v54, v0
	v_mov_b32_e32 v55, v0
	v_mov_b32_e32 v56, v0
	v_mov_b32_e32 v57, v0
	v_mov_b32_e32 v58, v0
	v_mov_b32_e32 v59, v0
	v_mov_b32_e32 v60, v0
	v_mov_b32_e32 v61, v0
	v_mov_b32_e32 v62, v0
	v_mov_b32_e32 v63, v0
	v_mov_b32_e32 v64, v0
	v_mov_b32_e32 v65, v0
	v_mov_b32_e32 v66, v0
	v_mov_b32_e32 v67, v0
	v_mov_b32_e32 v68, v0
	v_mov_b32_e32 v69, v0
	v_mov_b32_e32 v70, v0
	v_mov_b32_e32 v71, v0
	v_mov_b32_e32 v72, v0
	v_mov_b32_e32 v73, v0
	v_mov_b32_e32 v74, v0
	v_mov_b32_e32 v75, v0
	v_mov_b32_e32 v76, v0
	v_mov_b32_e32 v77, v0
	v_mov_b32_e32 v78, v0
	v_mov_b32_e32 v79, v0
	v_mov_b32_e32 v80, v0
	v_mov_b32_e32 v81, v0
	v_mov_b32_e32 v82, v0
	v_mov_b32_e32 v83, v0
	v_mov_b32_e32 v84, v0
	v_mov_b32_e32 v85, v0
	v_mov_b32_e32 v86, v0
	v_mov_b32_e32 v87, v0
	v_mov_b32_e32 v88, v0
	v_mov_b32_e32 v89, v0
	v_mov_b32_e32 v90, v0
	v_mov_b32_e32 v91, v0
	v_mov_b32_e32 v92, v0
	v_mov_b32_e32 v93, v0
	v_mov_b32_e32 v94, v0
	v_mov_b32_e32 v95, v0
	v_mov_b32_e32 v96, v0
	v_mov_b32_e32 v97, v0
	v_mov_b32_e32 v98, v0
	v_mov_b32_e32 v99, v0
	v_mov_b32_e32 v100, v0
	v_mov_b32_e32 v101, v0
	v_mov_b32_e32 v102, v0
	v_mov_b32_e32 v103, v0
	v_mov_b32_e32 v104, v0
	v_mov_b32_e32 v105, v0
	v_mov_b32_e32 v106, v0
	v_mov_b32_e32 v107, v0
	v_mov_b32_e32 v108, v0
	v_mov_b32_e32 v109, v0
	v_mov_b32_e32 v110, v0
	v_mov_b32_e32 v111, v0
	v_mov_b32_e32 v112, v0
	v_mov_b32_e32 v113, v0
	v_mov_b32_e32 v114, v0
	v_mov_b32_e32 v115, v0
	v_mov_b32_e32 v116, v0
	v_mov_b32_e32 v117, v0
	v_mov_b32_e32 v118, v0
	v_mov_b32_e32 v119, v0
	v_mov_b32_e32 v120, v0
	v_mov_b32_e32 v121, v0
	v_mov_b32_e32 v122, v0
	v_mov_b32_e32 v123, v0
	v_mov_b32_e32 v124, v0
	v_mov_b32_e32 v125, v0
	v_mov_b32_e32 v126, v0
	v_mov_b32_e32 v127, v0
	s_waitcnt vmcnt(0)
	s_cbranch_vccnz .LBB0_886
	s_barrier
	s_branch .LBB0_886

; #define STAGE(P_, BASE, br, kt) do { const u16* _gb = (BASE) + (long)(br) * K + (long)(kt) * BK; \
;     _Pragma("unroll") for (int _i = 0; _i < 2; ++_i) { \
;       __builtin_amdgcn_global_load_lds((const unsigned*)(_gb + (long)_i * 64 * K + lane_off), \
;         (unsigned*)((char*)(P_) + lds_wbase + _i * 8192), 16, 0, 0); } } while (0)
; #define LDA(dst, b, h) _Pragma("unroll") for (int m = 0; m < 4; ++m) _Pragma("unroll") for (int k = 0; k < 2; ++k) \
;     dst[m][k] = *reinterpret_cast<const bf16x8*>((char*)SA(b, h) + lds_byte(wr * 64 + m * 16 + fr, k * 32 + fq * 8))
; #define LDB(dst, b, h) _Pragma("unroll") for (int n = 0; n < 2; ++n) _Pragma("unroll") for (int k = 0; k < 2; ++k) \
;     dst[n][k] = *reinterpret_cast<const bf16x8*>((char*)SB(b, h) + lds_byte(wc * 32 + n * 16 + fr, k * 32 + fq * 8))
; #define MMA(ai, bj, At_, Bt_) do { __builtin_amdgcn_s_setprio(1); \
;     _Pragma("unroll") for (int m = 0; m < 4; ++m) _Pragma("unroll") for (int n = 0; n < 2; ++n) _Pragma("unroll") for (int k = 0; k < 2; ++k) \
;       acc[ai][bj][m][n] = __builtin_amdgcn_mfma_f32_16x16x32_bf16(At_[m][k], Bt_[n][k], acc[ai][bj][m][n], 0, 0, 0); \
;     __builtin_amdgcn_s_setprio(0); } while (0)
; #define WAIT_V(n) asm volatile("s_waitcnt vmcnt(" #n ")" ::: "memory")
; #define WAIT_L(n) asm volatile("s_waitcnt lgkmcnt(" #n ")" ::: "memory")
; #define BAR __builtin_amdgcn_s_barrier()
; #define SCHED __builtin_amdgcn_sched_barrier(0)
; #define STAGEW(P_, BASE, cur, nxt, kt_) do { const bool _wr = (kt_) >= nt; \
;     STAGE(P_, BASE, (_wr ? (nxt) : (cur)), (_wr ? (kt_) - nt : (kt_))); } while (0)
; template <int PRE> ...
;     ...
;   for (int t = 0; t < nt; t += 2) {
;     LDB(B0, 0, 0); SCHED; LDA(At, 0, 0); STAGE(SA(1, 1), A, brow + HALF, t + 1);
;     WAIT_L(8); BAR; WAIT_L(0); MMA(0, 0, At, B0); BAR; SCHED;
;     LDB(B1, 0, 1); STAGEW(SB(0, 0), Bt, bcol, bcol_n, t + 2);
;     BAR; WAIT_L(0); MMA(0, 1, At, B1); BAR;
;     LDA(At, 0, 1); STAGEW(SA(0, 0), A, brow, brow_n, t + 2);
;     BAR; WAIT_L(0); MMA(1, 0, At, B0); BAR; SCHED;
;     STAGEW(SB(0, 1), Bt, bcol + HALF, bcol_n + HALF, t + 2);
;     WAIT_V(6); BAR; MMA(1, 1, At, B1); BAR;
.LBB0_1083:
	v_add_u32_e32 v142, s81, v151
	ds_read_b128 v[134:137], v142
	ds_read_b128 v[138:141], v142 offset:1024
	ds_read_b128 v[146:149], v142 offset:2048
	ds_read_b128 v[156:159], v142 offset:3072
	s_add_i32 m0, s2, 0xc000
	ds_read_b128 v[160:163], v144
	ds_read_b128 v[168:171], v144 offset:1024
	ds_read_b128 v[172:175], v152
	ds_read_b128 v[176:179], v152 offset:1024
	ds_read_b128 v[180:183], v153
	ds_read_b128 v[184:187], v153 offset:1024
	ds_read_b128 v[188:191], v154
	ds_read_b128 v[192:195], v154 offset:1024
	global_load_lds_dwordx4 v[128:129], off
	v_lshl_add_u64 v[142:143], v[128:129], 0, s[40:41]
	s_add_i32 m0, s2, 0xe000
	s_nop 0
	global_load_lds_dwordx4 v[142:143], off
	s_waitcnt lgkmcnt(8)
	s_barrier
	s_waitcnt lgkmcnt(0)
	v_mfma_f32_16x16x32_bf16 v[124:127], v[160:163], v[134:137], v[124:127]
	v_mfma_f32_16x16x32_bf16 v[120:123], v[160:163], v[146:149], v[120:123]
	v_mfma_f32_16x16x32_bf16 v[116:119], v[172:175], v[134:137], v[116:119]
	v_mfma_f32_16x16x32_bf16 v[112:115], v[172:175], v[146:149], v[112:115]
	v_mfma_f32_16x16x32_bf16 v[108:111], v[180:183], v[134:137], v[108:111]
	v_mfma_f32_16x16x32_bf16 v[104:107], v[180:183], v[146:149], v[104:107]
	v_mfma_f32_16x16x32_bf16 v[100:103], v[188:191], v[134:137], v[100:103]
	v_mfma_f32_16x16x32_bf16 v[96:99], v[188:191], v[146:149], v[96:99]
	v_mfma_f32_16x16x32_bf16 v[124:127], v[168:171], v[138:141], v[124:127]
	v_mfma_f32_16x16x32_bf16 v[120:123], v[168:171], v[156:159], v[120:123]
	v_mfma_f32_16x16x32_bf16 v[116:119], v[176:179], v[138:141], v[116:119]
	v_mfma_f32_16x16x32_bf16 v[112:115], v[176:179], v[156:159], v[112:115]
	v_mfma_f32_16x16x32_bf16 v[108:111], v[184:187], v[138:141], v[108:111]
	v_mfma_f32_16x16x32_bf16 v[104:107], v[184:187], v[156:159], v[104:107]
	v_mfma_f32_16x16x32_bf16 v[100:103], v[192:195], v[138:141], v[100:103]
	v_mfma_f32_16x16x32_bf16 v[96:99], v[192:195], v[156:159], v[96:99]
	s_barrier
	s_add_i32 s34, s31, 2
	s_cmpk_lt_u32 s31, 0x56
	s_cselect_b64 s[0:1], -1, 0
	s_and_b64 vcc, s[0:1], exec
	s_cselect_b32 s0, s24, s26
	s_mulk_i32 s0, 0x1600
	s_cselect_b32 s18, 0, 0xffffffa8
	s_cselect_b32 s35, s23, s25
	s_cselect_b32 s38, s29, s28
	s_cselect_b32 s39, s27, s30
	s_ashr_i32 s1, s0, 31
	s_lshl_b64 s[0:1], s[0:1], 1
	s_add_u32 s36, s66, s0
	s_addc_u32 s37, s67, s1
	s_add_i32 s18, s34, s18
	s_lshl_b64 s[0:1], s[18:19], 7
	s_add_u32 s36, s36, s0
	v_add_u32_e32 v142, s82, v151
	s_addc_u32 s37, s37, s1
	s_mov_b32 m0, s3
	ds_read_b128 v[210:213], v142
	ds_read_b128 v[214:217], v142 offset:1024
	ds_read_b128 v[218:221], v142 offset:2048
	ds_read_b128 v[222:225], v142 offset:3072
	v_lshl_add_u64 v[142:143], s[36:37], 0, v[130:131]
	global_load_lds_dwordx4 v[142:143], off
	v_lshl_add_u64 v[142:143], v[142:143], 0, s[40:41]
	s_mov_b32 m0, s4
	s_nop 0
	global_load_lds_dwordx4 v[142:143], off
	s_barrier
	s_waitcnt lgkmcnt(0)
	v_mfma_f32_16x16x32_bf16 v[92:95], v[160:163], v[210:213], v[92:95]
	v_mfma_f32_16x16x32_bf16 v[88:91], v[160:163], v[218:221], v[88:91]
	v_mfma_f32_16x16x32_bf16 v[84:87], v[172:175], v[210:213], v[84:87]
	v_mfma_f32_16x16x32_bf16 v[80:83], v[172:175], v[218:221], v[80:83]
	v_mfma_f32_16x16x32_bf16 v[76:79], v[180:183], v[210:213], v[76:79]
	v_mfma_f32_16x16x32_bf16 v[72:75], v[180:183], v[218:221], v[72:75]
	v_mfma_f32_16x16x32_bf16 v[68:71], v[188:191], v[210:213], v[68:71]
	v_mfma_f32_16x16x32_bf16 v[64:67], v[188:191], v[218:221], v[64:67]
	v_mfma_f32_16x16x32_bf16 v[92:95], v[168:171], v[214:217], v[92:95]
	v_mfma_f32_16x16x32_bf16 v[88:91], v[168:171], v[222:225], v[88:91]
	v_mfma_f32_16x16x32_bf16 v[84:87], v[176:179], v[214:217], v[84:87]
	v_mfma_f32_16x16x32_bf16 v[80:83], v[176:179], v[222:225], v[80:83]
	v_mfma_f32_16x16x32_bf16 v[76:79], v[184:187], v[214:217], v[76:79]
	v_mfma_f32_16x16x32_bf16 v[72:75], v[184:187], v[222:225], v[72:75]
	v_mfma_f32_16x16x32_bf16 v[68:71], v[192:195], v[214:217], v[68:71]
	v_mfma_f32_16x16x32_bf16 v[64:67], v[192:195], v[222:225], v[64:67]
	s_mul_hi_i32 s18, s35, 0x2c00
	s_mulk_i32 s35, 0x2c00
	s_add_u32 s35, s79, s35
	s_addc_u32 s18, s80, s18
	s_add_u32 s36, s35, s0
	s_addc_u32 s37, s18, s1
	s_mov_b32 m0, s2
	v_lshl_add_u64 v[142:143], s[36:37], 0, v[130:131]
	s_barrier
	ds_read_b128 v[160:163], v144 offset:16384
	ds_read_b128 v[168:171], v144 offset:17408
	ds_read_b128 v[172:175], v152 offset:16384
	ds_read_b128 v[176:179], v152 offset:17408
	ds_read_b128 v[180:183], v153 offset:16384
	ds_read_b128 v[184:187], v153 offset:17408
	ds_read_b128 v[188:191], v154 offset:16384
	ds_read_b128 v[192:195], v154 offset:17408
	global_load_lds_dwordx4 v[142:143], off
	v_lshl_add_u64 v[142:143], v[142:143], 0, s[40:41]
	s_mov_b32 m0, s5
	s_nop 0
	global_load_lds_dwordx4 v[142:143], off
	s_barrier
	s_waitcnt lgkmcnt(0)
	v_mfma_f32_16x16x32_bf16 v[60:63], v[160:163], v[134:137], v[60:63]
	v_mfma_f32_16x16x32_bf16 v[56:59], v[160:163], v[146:149], v[56:59]
	v_mfma_f32_16x16x32_bf16 v[52:55], v[172:175], v[134:137], v[52:55]
	v_mfma_f32_16x16x32_bf16 v[48:51], v[172:175], v[146:149], v[48:51]
	v_mfma_f32_16x16x32_bf16 v[44:47], v[180:183], v[134:137], v[44:47]
	v_mfma_f32_16x16x32_bf16 v[40:43], v[180:183], v[146:149], v[40:43]
	v_mfma_f32_16x16x32_bf16 v[36:39], v[188:191], v[134:137], v[36:39]
	v_mfma_f32_16x16x32_bf16 v[32:35], v[188:191], v[146:149], v[32:35]
	v_mfma_f32_16x16x32_bf16 v[60:63], v[168:171], v[138:141], v[60:63]
	v_mfma_f32_16x16x32_bf16 v[56:59], v[168:171], v[156:159], v[56:59]
	v_mfma_f32_16x16x32_bf16 v[52:55], v[176:179], v[138:141], v[52:55]
	v_mfma_f32_16x16x32_bf16 v[48:51], v[176:179], v[156:159], v[48:51]
	v_mfma_f32_16x16x32_bf16 v[44:47], v[184:187], v[138:141], v[44:47]
	v_mfma_f32_16x16x32_bf16 v[40:43], v[184:187], v[156:159], v[40:43]
	v_mfma_f32_16x16x32_bf16 v[36:39], v[192:195], v[138:141], v[36:39]
	v_mfma_f32_16x16x32_bf16 v[32:35], v[192:195], v[156:159], v[32:35]
	s_barrier
; #define STAGE(P_, BASE, br, kt) do { const u16* _gb = (BASE) + (long)(br) * K + (long)(kt) * BK; \
;     _Pragma("unroll") for (int _i = 0; _i < 2; ++_i) { \
;       __builtin_amdgcn_global_load_lds((const unsigned*)(_gb + (long)_i * 64 * K + lane_off), \
;         (unsigned*)((char*)(P_) + lds_wbase + _i * 8192), 16, 0, 0); } } while (0)
; #define LDA(dst, b, h) _Pragma("unroll") for (int m = 0; m < 4; ++m) _Pragma("unroll") for (int k = 0; k < 2; ++k) \
;     dst[m][k] = *reinterpret_cast<const bf16x8*>((char*)SA(b, h) + lds_byte(wr * 64 + m * 16 + fr, k * 32 + fq * 8))
; #define LDB(dst, b, h) _Pragma("unroll") for (int n = 0; n < 2; ++n) _Pragma("unroll") for (int k = 0; k < 2; ++k) \
;     dst[n][k] = *reinterpret_cast<const bf16x8*>((char*)SB(b, h) + lds_byte(wc * 32 + n * 16 + fr, k * 32 + fq * 8))
; #define MMA(ai, bj, At_, Bt_) do { __builtin_amdgcn_s_setprio(1); \
;     _Pragma("unroll") for (int m = 0; m < 4; ++m) _Pragma("unroll") for (int n = 0; n < 2; ++n) _Pragma("unroll") for (int k = 0; k < 2; ++k) \
;       acc[ai][bj][m][n] = __builtin_amdgcn_mfma_f32_16x16x32_bf16(At_[m][k], Bt_[n][k], acc[ai][bj][m][n], 0, 0, 0); \
;     __builtin_amdgcn_s_setprio(0); } while (0)
; #define WAIT_V(n) asm volatile("s_waitcnt vmcnt(" #n ")" ::: "memory")
; #define BAR __builtin_amdgcn_s_barrier()
; template <int PRE> ...
;     ...
;   for (int t = 0; t < nt; t += 2) {
;     LDB(B0, 0, 0); SCHED; LDA(At, 0, 0); STAGE(SA(1, 1), A, brow + HALF, t + 1);
;     WAIT_L(8); BAR; WAIT_L(0); MMA(0, 0, At, B0); BAR; SCHED;
;     LDB(B1, 0, 1); STAGEW(SB(0, 0), Bt, bcol, bcol_n, t + 2);
;     BAR; WAIT_L(0); MMA(0, 1, At, B1); BAR;
;     LDA(At, 0, 1); STAGEW(SA(0, 0), A, brow, brow_n, t + 2);
;     BAR; WAIT_L(0); MMA(1, 0, At, B0); BAR; SCHED;
;     STAGEW(SB(0, 1), Bt, bcol + HALF, bcol_n + HALF, t + 2);
;     WAIT_V(6); BAR; MMA(1, 1, At, B1); BAR;
;     LDB(B0, 1, 0); SCHED; LDA(At, 1, 0); STAGEW(SA(0, 1), A, brow + HALF, brow_n + HALF, t + 2);
;     WAIT_L(8); BAR; WAIT_L(0); MMA(0, 0, At, B0); BAR; SCHED;
;     LDB(B1, 1, 1); STAGEW(SB(1, 0), Bt, bcol, bcol_n, t + 3);
;     BAR; WAIT_L(0); MMA(0, 1, At, B1); BAR;
;     LDA(At, 1, 1); STAGEW(SA(1, 0), A, brow, brow_n, t + 3);
;     BAR; WAIT_L(0); MMA(1, 0, At, B0); BAR; SCHED;
;     STAGEW(SB(1, 1), Bt, bcol + HALF, bcol_n + HALF, t + 3);
;     WAIT_V(6); BAR; MMA(1, 1, At, B1); BAR;
;   }
	s_mul_i32 s36, s38, 0x1600
	s_ashr_i32 s37, s36, 31
	s_lshl_b64 s[36:37], s[36:37], 1
	s_add_u32 s18, s66, s36
	s_addc_u32 s35, s67, s37
	s_add_u32 s36, s18, s0
	s_addc_u32 s37, s35, s1
	s_mov_b32 m0, s10
	v_lshl_add_u64 v[134:135], s[36:37], 0, v[130:131]
	global_load_lds_dwordx4 v[134:135], off
	v_lshl_add_u64 v[134:135], v[134:135], 0, s[40:41]
	s_mov_b32 m0, s11
	s_nop 0
	global_load_lds_dwordx4 v[134:135], off
	s_waitcnt vmcnt(6)
	s_barrier
	v_mfma_f32_16x16x32_bf16 v[28:31], v[160:163], v[210:213], v[28:31]
	v_mfma_f32_16x16x32_bf16 v[24:27], v[160:163], v[218:221], v[24:27]
	v_mfma_f32_16x16x32_bf16 v[20:23], v[172:175], v[210:213], v[20:23]
	v_mfma_f32_16x16x32_bf16 v[16:19], v[172:175], v[218:221], v[16:19]
	v_mfma_f32_16x16x32_bf16 v[12:15], v[180:183], v[210:213], v[12:15]
	v_mfma_f32_16x16x32_bf16 v[8:11], v[180:183], v[218:221], v[8:11]
	v_mfma_f32_16x16x32_bf16 v[4:7], v[188:191], v[210:213], v[4:7]
	v_mfma_f32_16x16x32_bf16 v[0:3], v[188:191], v[218:221], v[0:3]
	v_mfma_f32_16x16x32_bf16 v[28:31], v[168:171], v[214:217], v[28:31]
	v_mfma_f32_16x16x32_bf16 v[24:27], v[168:171], v[222:225], v[24:27]
	v_mfma_f32_16x16x32_bf16 v[20:23], v[176:179], v[214:217], v[20:23]
	v_mfma_f32_16x16x32_bf16 v[16:19], v[176:179], v[222:225], v[16:19]
	v_mfma_f32_16x16x32_bf16 v[12:15], v[184:187], v[214:217], v[12:15]
	v_mfma_f32_16x16x32_bf16 v[8:11], v[184:187], v[222:225], v[8:11]
	v_mfma_f32_16x16x32_bf16 v[4:7], v[192:195], v[214:217], v[4:7]
	v_mfma_f32_16x16x32_bf16 v[0:3], v[192:195], v[222:225], v[0:3]
	v_add_u32_e32 v142, s83, v151
	s_barrier
	ds_read_b128 v[134:137], v142
	ds_read_b128 v[138:141], v142 offset:1024
	ds_read_b128 v[146:149], v142 offset:2048
	ds_read_b128 v[156:159], v142 offset:3072
	s_mul_hi_i32 s18, s39, 0x2c00
	s_mulk_i32 s39, 0x2c00
	s_add_u32 s35, s79, s39
	s_addc_u32 s18, s80, s18
	s_add_u32 s0, s35, s0
	s_addc_u32 s1, s18, s1
	s_mov_b32 m0, s12
	v_lshl_add_u64 v[142:143], s[0:1], 0, v[130:131]
	ds_read_b128 v[160:163], v144 offset:32768
	ds_read_b128 v[168:171], v144 offset:33792
	ds_read_b128 v[172:175], v152 offset:32768
	ds_read_b128 v[176:179], v152 offset:33792
	ds_read_b128 v[180:183], v153 offset:32768
	ds_read_b128 v[184:187], v153 offset:33792
	ds_read_b128 v[188:191], v154 offset:32768
	ds_read_b128 v[192:195], v154 offset:33792
	global_load_lds_dwordx4 v[142:143], off
	v_lshl_add_u64 v[142:143], v[142:143], 0, s[40:41]
	s_mov_b32 m0, s13
	s_nop 0
	global_load_lds_dwordx4 v[142:143], off
	s_waitcnt lgkmcnt(8)
	s_barrier
	s_waitcnt lgkmcnt(0)
	v_mfma_f32_16x16x32_bf16 v[124:127], v[160:163], v[134:137], v[124:127]
	v_mfma_f32_16x16x32_bf16 v[120:123], v[160:163], v[146:149], v[120:123]
	v_mfma_f32_16x16x32_bf16 v[116:119], v[172:175], v[134:137], v[116:119]
	v_mfma_f32_16x16x32_bf16 v[112:115], v[172:175], v[146:149], v[112:115]
	v_mfma_f32_16x16x32_bf16 v[108:111], v[180:183], v[134:137], v[108:111]
	v_mfma_f32_16x16x32_bf16 v[104:107], v[180:183], v[146:149], v[104:107]
	v_mfma_f32_16x16x32_bf16 v[100:103], v[188:191], v[134:137], v[100:103]
	v_mfma_f32_16x16x32_bf16 v[96:99], v[188:191], v[146:149], v[96:99]
	v_mfma_f32_16x16x32_bf16 v[124:127], v[168:171], v[138:141], v[124:127]
	v_mfma_f32_16x16x32_bf16 v[120:123], v[168:171], v[156:159], v[120:123]
	v_mfma_f32_16x16x32_bf16 v[116:119], v[176:179], v[138:141], v[116:119]
	v_mfma_f32_16x16x32_bf16 v[112:115], v[176:179], v[156:159], v[112:115]
	v_mfma_f32_16x16x32_bf16 v[108:111], v[184:187], v[138:141], v[108:111]
	v_mfma_f32_16x16x32_bf16 v[104:107], v[184:187], v[156:159], v[104:107]
	v_mfma_f32_16x16x32_bf16 v[100:103], v[192:195], v[138:141], v[100:103]
	v_mfma_f32_16x16x32_bf16 v[96:99], v[192:195], v[156:159], v[96:99]
	s_barrier
	s_cmpk_lt_u32 s31, 0x55
	s_cselect_b32 s0, s24, s26
	s_mulk_i32 s0, 0x1600
	s_cselect_b32 s18, 0, 0xffffffa8
	s_cselect_b32 s35, s23, s25
	s_cselect_b32 s38, s29, s28
	s_ashr_i32 s1, s0, 31
	s_lshl_b64 s[0:1], s[0:1], 1
	s_add_u32 s36, s66, s0
	s_addc_u32 s37, s67, s1
	s_add_i32 s0, s18, s31
	s_add_i32 s18, s0, 3
	s_lshl_b64 s[0:1], s[18:19], 7
	s_add_u32 s36, s36, s0
	v_add_u32_e32 v142, s84, v151
	s_addc_u32 s37, s37, s1
	s_mov_b32 m0, s14
	ds_read_b128 v[210:213], v142
	ds_read_b128 v[214:217], v142 offset:1024
	ds_read_b128 v[218:221], v142 offset:2048
	ds_read_b128 v[222:225], v142 offset:3072
	v_lshl_add_u64 v[142:143], s[36:37], 0, v[130:131]
	global_load_lds_dwordx4 v[142:143], off
	v_lshl_add_u64 v[142:143], v[142:143], 0, s[40:41]
	s_mov_b32 m0, s15
	s_nop 0
	global_load_lds_dwordx4 v[142:143], off
	s_barrier
	s_waitcnt lgkmcnt(0)
	v_mfma_f32_16x16x32_bf16 v[92:95], v[160:163], v[210:213], v[92:95]
	v_mfma_f32_16x16x32_bf16 v[88:91], v[160:163], v[218:221], v[88:91]
	v_mfma_f32_16x16x32_bf16 v[84:87], v[172:175], v[210:213], v[84:87]
	v_mfma_f32_16x16x32_bf16 v[80:83], v[172:175], v[218:221], v[80:83]
	v_mfma_f32_16x16x32_bf16 v[76:79], v[180:183], v[210:213], v[76:79]
	v_mfma_f32_16x16x32_bf16 v[72:75], v[180:183], v[218:221], v[72:75]
	v_mfma_f32_16x16x32_bf16 v[68:71], v[188:191], v[210:213], v[68:71]
	v_mfma_f32_16x16x32_bf16 v[64:67], v[188:191], v[218:221], v[64:67]
	v_mfma_f32_16x16x32_bf16 v[92:95], v[168:171], v[214:217], v[92:95]
	v_mfma_f32_16x16x32_bf16 v[88:91], v[168:171], v[222:225], v[88:91]
	v_mfma_f32_16x16x32_bf16 v[84:87], v[176:179], v[214:217], v[84:87]
	v_mfma_f32_16x16x32_bf16 v[80:83], v[176:179], v[222:225], v[80:83]
	v_mfma_f32_16x16x32_bf16 v[76:79], v[184:187], v[214:217], v[76:79]
	v_mfma_f32_16x16x32_bf16 v[72:75], v[184:187], v[222:225], v[72:75]
	v_mfma_f32_16x16x32_bf16 v[68:71], v[192:195], v[214:217], v[68:71]
	v_mfma_f32_16x16x32_bf16 v[64:67], v[192:195], v[222:225], v[64:67]
	s_mul_hi_i32 s18, s35, 0x2c00
	s_mulk_i32 s35, 0x2c00
	s_add_u32 s31, s79, s35
	s_addc_u32 s18, s80, s18
	s_add_u32 s36, s31, s0
	s_addc_u32 s37, s18, s1
	s_mov_b32 m0, s16
	v_lshl_add_u64 v[142:143], s[36:37], 0, v[130:131]
	s_barrier
; __device__ __forceinline__ float bflo(unsigned u) { return __uint_as_float(u << 16); }
; __device__ __forceinline__ float bfhi(unsigned u) { return __uint_as_float(u & 0xffff0000u); }
; #define LDA(dst, b, h) _Pragma("unroll") for (int m = 0; m < 4; ++m) _Pragma("unroll") for (int k = 0; k < 2; ++k) \
;     dst[m][k] = *reinterpret_cast<const bf16x8*>((char*)SA(b, h) + lds_byte(wr * 64 + m * 16 + fr, k * 32 + fq * 8))
; #define LDB(dst, b, h) _Pragma("unroll") for (int n = 0; n < 2; ++n) _Pragma("unroll") for (int k = 0; k < 2; ++k) \
;     dst[n][k] = *reinterpret_cast<const bf16x8*>((char*)SB(b, h) + lds_byte(wc * 32 + n * 16 + fr, k * 32 + fq * 8))
; #define MMA(ai, bj, At_, Bt_) do { __builtin_amdgcn_s_setprio(1); \
;     _Pragma("unroll") for (int m = 0; m < 4; ++m) _Pragma("unroll") for (int n = 0; n < 2; ++n) _Pragma("unroll") for (int k = 0; k < 2; ++k) \
;       acc[ai][bj][m][n] = __builtin_amdgcn_mfma_f32_16x16x32_bf16(At_[m][k], Bt_[n][k], acc[ai][bj][m][n], 0, 0, 0); \
;     __builtin_amdgcn_s_setprio(0); } while (0)
; #define WAIT_V(n) asm volatile("s_waitcnt vmcnt(" #n ")" ::: "memory")
; #define WAIT_L(n) asm volatile("s_waitcnt lgkmcnt(" #n ")" ::: "memory")
; #define BAR __builtin_amdgcn_s_barrier()
; #define SCHED __builtin_amdgcn_sched_barrier(0)
; #define STAGEW(P_, BASE, cur, nxt, kt_) do { const bool _wr = (kt_) >= nt; \
;     STAGE(P_, BASE, (_wr ? (nxt) : (cur)), (_wr ? (kt_) - nt : (kt_))); } while (0)
; #define WIDE_STORE(BASE, LD, COFF, O) do { if ((m & 1) == 0) opend[n] = (O); \
;                 else *(uint4*)((BASE) + (size_t)tok * (LD) + (ncw - (COFF))) = swap_pair(opend[n], (O)); } while (0)
; template <int PRE> ...
;     ...
;     LDB(B1, 1, 1); STAGEW(SB(1, 0), Bt, bcol, bcol_n, t + 3);
;     BAR; WAIT_L(0); MMA(0, 1, At, B1); BAR;
;     LDA(At, 1, 1); STAGEW(SA(1, 0), A, brow, brow_n, t + 3);
;     BAR; WAIT_L(0); MMA(1, 0, At, B0); BAR; SCHED;
;     STAGEW(SB(1, 1), Bt, bcol + HALF, bcol_n + HALF, t + 3);
;     WAIT_V(6); BAR; MMA(1, 1, At, B1); BAR;
;   }
;   if (wr == 0) BAR;
;     ...
;               } else {
;                 uint2* ph = (uint2*)((u16*)(ws + OFF_RB) + (size_t)tok * DM + nc);
;                 const uint2 hb = *ph;
;                 uint2 o; o.x = pk2(bflo(hb.x) + v[0], bfhi(hb.x) + v[1]); o.y = pk2(bflo(hb.y) + v[2], bfhi(hb.y) + v[3]);
;                 WIDE_STORE((u16*)(ws + OFF_RB), DM, 0, o);
	ds_read_b128 v[160:163], v144 offset:49152
	ds_read_b128 v[168:171], v144 offset:50176
	ds_read_b128 v[172:175], v152 offset:49152
	ds_read_b128 v[176:179], v152 offset:50176
	ds_read_b128 v[180:183], v153 offset:49152
	ds_read_b128 v[184:187], v153 offset:50176
	ds_read_b128 v[188:191], v154 offset:49152
	ds_read_b128 v[192:195], v154 offset:50176
	global_load_lds_dwordx4 v[142:143], off
	v_lshl_add_u64 v[142:143], v[142:143], 0, s[40:41]
	s_mov_b32 m0, s17
	s_nop 0
	global_load_lds_dwordx4 v[142:143], off
	s_barrier
	s_waitcnt lgkmcnt(0)
	v_mfma_f32_16x16x32_bf16 v[60:63], v[160:163], v[134:137], v[60:63]
	v_mfma_f32_16x16x32_bf16 v[56:59], v[160:163], v[146:149], v[56:59]
	v_mfma_f32_16x16x32_bf16 v[52:55], v[172:175], v[134:137], v[52:55]
	v_mfma_f32_16x16x32_bf16 v[48:51], v[172:175], v[146:149], v[48:51]
	v_mfma_f32_16x16x32_bf16 v[44:47], v[180:183], v[134:137], v[44:47]
	v_mfma_f32_16x16x32_bf16 v[40:43], v[180:183], v[146:149], v[40:43]
	v_mfma_f32_16x16x32_bf16 v[36:39], v[188:191], v[134:137], v[36:39]
	v_mfma_f32_16x16x32_bf16 v[32:35], v[188:191], v[146:149], v[32:35]
	v_mfma_f32_16x16x32_bf16 v[60:63], v[168:171], v[138:141], v[60:63]
	v_mfma_f32_16x16x32_bf16 v[56:59], v[168:171], v[156:159], v[56:59]
	v_mfma_f32_16x16x32_bf16 v[52:55], v[176:179], v[138:141], v[52:55]
	v_mfma_f32_16x16x32_bf16 v[48:51], v[176:179], v[156:159], v[48:51]
	v_mfma_f32_16x16x32_bf16 v[44:47], v[184:187], v[138:141], v[44:47]
	v_mfma_f32_16x16x32_bf16 v[40:43], v[184:187], v[156:159], v[40:43]
	v_mfma_f32_16x16x32_bf16 v[36:39], v[192:195], v[138:141], v[36:39]
	v_mfma_f32_16x16x32_bf16 v[32:35], v[192:195], v[156:159], v[32:35]
	s_barrier
	s_mul_i32 s36, s38, 0x1600
	s_ashr_i32 s37, s36, 31
	s_lshl_b64 s[36:37], s[36:37], 1
	s_add_u32 s18, s66, s36
	s_addc_u32 s31, s67, s37
	s_add_u32 s0, s18, s0
	s_addc_u32 s1, s31, s1
	s_mov_b32 m0, s20
	v_lshl_add_u64 v[134:135], s[0:1], 0, v[130:131]
	global_load_lds_dwordx4 v[134:135], off
	v_lshl_add_u64 v[134:135], v[134:135], 0, s[40:41]
	s_mov_b32 m0, s21
	s_nop 0
	global_load_lds_dwordx4 v[134:135], off
	s_waitcnt vmcnt(6)
	s_barrier
	v_mfma_f32_16x16x32_bf16 v[28:31], v[160:163], v[210:213], v[28:31]
	v_mfma_f32_16x16x32_bf16 v[24:27], v[160:163], v[218:221], v[24:27]
	v_mfma_f32_16x16x32_bf16 v[20:23], v[172:175], v[210:213], v[20:23]
	v_mfma_f32_16x16x32_bf16 v[16:19], v[172:175], v[218:221], v[16:19]
	v_mfma_f32_16x16x32_bf16 v[12:15], v[180:183], v[210:213], v[12:15]
	v_mfma_f32_16x16x32_bf16 v[8:11], v[180:183], v[218:221], v[8:11]
	v_mfma_f32_16x16x32_bf16 v[4:7], v[188:191], v[210:213], v[4:7]
	v_mfma_f32_16x16x32_bf16 v[0:3], v[188:191], v[218:221], v[0:3]
	v_mfma_f32_16x16x32_bf16 v[28:31], v[168:171], v[214:217], v[28:31]
	v_mfma_f32_16x16x32_bf16 v[24:27], v[168:171], v[222:225], v[24:27]
	v_mfma_f32_16x16x32_bf16 v[20:23], v[176:179], v[214:217], v[20:23]
	v_mfma_f32_16x16x32_bf16 v[16:19], v[176:179], v[222:225], v[16:19]
	v_mfma_f32_16x16x32_bf16 v[12:15], v[184:187], v[214:217], v[12:15]
	v_mfma_f32_16x16x32_bf16 v[8:11], v[184:187], v[222:225], v[8:11]
	v_mfma_f32_16x16x32_bf16 v[4:7], v[192:195], v[214:217], v[4:7]
	v_mfma_f32_16x16x32_bf16 v[0:3], v[192:195], v[222:225], v[0:3]
	v_lshl_add_u64 v[128:129], v[128:129], 0, s[46:47]
	s_mov_b32 s31, s34
	s_barrier
	s_cbranch_vccnz .LBB0_1083
	v_readlane_b32 s26, v245, 25
	v_readlane_b32 s27, v245, 26
	v_readlane_b32 s34, v243, 2
	v_readlane_b32 s31, v244, 61
	v_readlane_b32 s35, v243, 3
	s_add_i32 s0, s23, s49
	v_and_b32_e32 v172, 15, v150
	v_or_b32_e32 v172, s54, v172
	v_or_b32_e32 v172, s24, v172
	v_lshrrev_b32_e32 v173, 2, v150
	v_and_b32_e32 v174, -4, v173
	v_add_u32_e32 v174, s0, v174
	v_and_b32_e32 v173, -8, v173
	v_and_b32_e32 v175, 16, v150
	v_add3_u32 v173, v173, v175, s0
	v_lshlrev_b32_e32 v175, 12, v172
	v_lshl_add_u32 v134, v174, 1, v175
	v_add_u32_e32 v135, 0x10000, v134
	v_add_u32_e32 v136, 0x80000, v134
	v_add_u32_e32 v137, 0x90000, v134
	v_lshlrev_b32_e32 v175, 12, v172
	v_lshl_add_u32 v138, v173, 1, v175
	v_add_u32_e32 v139, 0x10000, v138
	v_add_u32_e32 v140, 0x80000, v138
	v_add_u32_e32 v141, 0x90000, v138
	global_load_dwordx2 v[210:211], v134, s[26:27] offset:0
	global_load_dwordx2 v[212:213], v134, s[26:27] offset:32
	global_load_dwordx2 v[214:215], v134, s[26:27] offset:64
	global_load_dwordx2 v[216:217], v134, s[26:27] offset:96
	global_load_dwordx2 v[218:219], v135, s[26:27] offset:0
	global_load_dwordx2 v[220:221], v135, s[26:27] offset:32
	global_load_dwordx2 v[222:223], v135, s[26:27] offset:64
	global_load_dwordx2 v[224:225], v135, s[26:27] offset:96
	global_load_dwordx2 v[226:227], v136, s[26:27] offset:0
	global_load_dwordx2 v[228:229], v136, s[26:27] offset:32
	global_load_dwordx2 v[230:231], v136, s[26:27] offset:64
	global_load_dwordx2 v[232:233], v136, s[26:27] offset:96
	global_load_dwordx2 v[234:235], v137, s[26:27] offset:0
	global_load_dwordx2 v[236:237], v137, s[26:27] offset:32
	global_load_dwordx2 v[238:239], v137, s[26:27] offset:64
	global_load_dwordx2 v[240:241], v137, s[26:27] offset:96
	s_andn2_b64 vcc, exec, s[58:59]
	s_cbranch_vccnz .LBB0_1086
	s_barrier
; __device__ __forceinline__ float bflo(unsigned u) { return __uint_as_float(u << 16); }
; __device__ __forceinline__ float bfhi(unsigned u) { return __uint_as_float(u & 0xffff0000u); }
; #define WIDE_STORE(BASE, LD, COFF, O) do { if ((m & 1) == 0) opend[n] = (O); \
;                 else *(uint4*)((BASE) + (size_t)tok * (LD) + (ncw - (COFF))) = swap_pair(opend[n], (O)); } while (0)
;     ...
;               const int nc = brow + ai * 128 + wr * 64 + m * 16 + fq * 4;
;               const int tok = bcol + bj * 128 + wc * 32 + n * 16 + fr;
;               const int ncw = brow + ai * 128 + wr * 64 + ((m & ~1) + (fq & 1)) * 16 + (fq & ~1) * 4;
;     ...
;               } else {
;                 uint2* ph = (uint2*)((u16*)(ws + OFF_RB) + (size_t)tok * DM + nc);
;                 const uint2 hb = *ph;
;                 uint2 o; o.x = pk2(bflo(hb.x) + v[0], bfhi(hb.x) + v[1]); o.y = pk2(bflo(hb.y) + v[2], bfhi(hb.y) + v[3]);
;                 WIDE_STORE((u16*)(ws + OFF_RB), DM, 0, o);
.LBB0_1086:
	s_waitcnt vmcnt(15)
	v_lshlrev_b32_e32 v168, 16, v210
	v_and_b32_e32 v169, 0xffff0000, v210
	v_lshlrev_b32_e32 v170, 16, v211
	v_and_b32_e32 v171, 0xffff0000, v211
	v_pk_add_f32 v[124:125], v[124:125], v[168:169]
	v_pk_add_f32 v[126:127], v[126:127], v[170:171]
	global_load_dwordx2 v[210:211], v134, s[26:27] offset:256
	s_waitcnt vmcnt(15)
	v_lshlrev_b32_e32 v168, 16, v212
	v_and_b32_e32 v169, 0xffff0000, v212
	v_lshlrev_b32_e32 v170, 16, v213
	v_and_b32_e32 v171, 0xffff0000, v213
	v_pk_add_f32 v[116:117], v[116:117], v[168:169]
	v_pk_add_f32 v[118:119], v[118:119], v[170:171]
	global_load_dwordx2 v[212:213], v134, s[26:27] offset:288
	s_waitcnt vmcnt(15)
	v_lshlrev_b32_e32 v168, 16, v214
	v_and_b32_e32 v169, 0xffff0000, v214
	v_lshlrev_b32_e32 v170, 16, v215
	v_and_b32_e32 v171, 0xffff0000, v215
	v_pk_add_f32 v[108:109], v[108:109], v[168:169]
	v_pk_add_f32 v[110:111], v[110:111], v[170:171]
	global_load_dwordx2 v[214:215], v134, s[26:27] offset:320
	s_waitcnt vmcnt(15)
	v_lshlrev_b32_e32 v168, 16, v216
	v_and_b32_e32 v169, 0xffff0000, v216
	v_lshlrev_b32_e32 v170, 16, v217
	v_and_b32_e32 v171, 0xffff0000, v217
	v_pk_add_f32 v[100:101], v[100:101], v[168:169]
	v_pk_add_f32 v[102:103], v[102:103], v[170:171]
	global_load_dwordx2 v[216:217], v134, s[26:27] offset:352
	s_nop 0
	v_cvt_pk_bf16_f32 v124, v124, v125
	v_cvt_pk_bf16_f32 v125, v126, v127
	v_cvt_pk_bf16_f32 v126, v116, v117
	v_cvt_pk_bf16_f32 v127, v118, v119
	v_cvt_pk_bf16_f32 v108, v108, v109
	v_cvt_pk_bf16_f32 v109, v110, v111
	v_cvt_pk_bf16_f32 v110, v100, v101
	v_cvt_pk_bf16_f32 v111, v102, v103
	s_nop 1
	v_permlane16_swap_b32_e32 v124, v126
	v_permlane16_swap_b32_e32 v125, v127
	v_permlane16_swap_b32_e32 v108, v110
	v_permlane16_swap_b32_e32 v109, v111
	global_store_dwordx4 v138, v[124:127], s[26:27] offset:0
	global_store_dwordx4 v138, v[108:111], s[26:27] offset:64
	s_waitcnt vmcnt(17)
	v_lshlrev_b32_e32 v168, 16, v218
	v_and_b32_e32 v169, 0xffff0000, v218
	v_lshlrev_b32_e32 v170, 16, v219
	v_and_b32_e32 v171, 0xffff0000, v219
	v_pk_add_f32 v[120:121], v[120:121], v[168:169]
	v_pk_add_f32 v[122:123], v[122:123], v[170:171]
	global_load_dwordx2 v[218:219], v135, s[26:27] offset:256
	s_waitcnt vmcnt(17)
	v_lshlrev_b32_e32 v168, 16, v220
	v_and_b32_e32 v169, 0xffff0000, v220
	v_lshlrev_b32_e32 v170, 16, v221
	v_and_b32_e32 v171, 0xffff0000, v221
	v_pk_add_f32 v[112:113], v[112:113], v[168:169]
	v_pk_add_f32 v[114:115], v[114:115], v[170:171]
	global_load_dwordx2 v[220:221], v135, s[26:27] offset:288
	s_waitcnt vmcnt(17)
	v_lshlrev_b32_e32 v168, 16, v222
	v_and_b32_e32 v169, 0xffff0000, v222
	v_lshlrev_b32_e32 v170, 16, v223
	v_and_b32_e32 v171, 0xffff0000, v223
	v_pk_add_f32 v[104:105], v[104:105], v[168:169]
	v_pk_add_f32 v[106:107], v[106:107], v[170:171]
	global_load_dwordx2 v[222:223], v135, s[26:27] offset:320
	s_waitcnt vmcnt(17)
	v_lshlrev_b32_e32 v168, 16, v224
	v_and_b32_e32 v169, 0xffff0000, v224
	v_lshlrev_b32_e32 v170, 16, v225
	v_and_b32_e32 v171, 0xffff0000, v225
	v_pk_add_f32 v[96:97], v[96:97], v[168:169]
	v_pk_add_f32 v[98:99], v[98:99], v[170:171]
	global_load_dwordx2 v[224:225], v135, s[26:27] offset:352
	s_nop 0
	v_cvt_pk_bf16_f32 v120, v120, v121
	v_cvt_pk_bf16_f32 v121, v122, v123
	v_cvt_pk_bf16_f32 v122, v112, v113
	v_cvt_pk_bf16_f32 v123, v114, v115
	v_cvt_pk_bf16_f32 v104, v104, v105
	v_cvt_pk_bf16_f32 v105, v106, v107
	v_cvt_pk_bf16_f32 v106, v96, v97
	v_cvt_pk_bf16_f32 v107, v98, v99
	s_nop 1
	v_permlane16_swap_b32_e32 v120, v122
	v_permlane16_swap_b32_e32 v121, v123
	v_permlane16_swap_b32_e32 v104, v106
	v_permlane16_swap_b32_e32 v105, v107
	global_store_dwordx4 v139, v[120:123], s[26:27] offset:0
	global_store_dwordx4 v139, v[104:107], s[26:27] offset:64
	s_waitcnt vmcnt(19)
	v_lshlrev_b32_e32 v168, 16, v226
	v_and_b32_e32 v169, 0xffff0000, v226
	v_lshlrev_b32_e32 v170, 16, v227
	v_and_b32_e32 v171, 0xffff0000, v227
	v_pk_add_f32 v[92:93], v[92:93], v[168:169]
	v_pk_add_f32 v[94:95], v[94:95], v[170:171]
	global_load_dwordx2 v[226:227], v136, s[26:27] offset:256
	s_waitcnt vmcnt(19)
	v_lshlrev_b32_e32 v168, 16, v228
	v_and_b32_e32 v169, 0xffff0000, v228
	v_lshlrev_b32_e32 v170, 16, v229
	v_and_b32_e32 v171, 0xffff0000, v229
	v_pk_add_f32 v[84:85], v[84:85], v[168:169]
	v_pk_add_f32 v[86:87], v[86:87], v[170:171]
	global_load_dwordx2 v[228:229], v136, s[26:27] offset:288
	s_waitcnt vmcnt(19)
	v_lshlrev_b32_e32 v168, 16, v230
	v_and_b32_e32 v169, 0xffff0000, v230
	v_lshlrev_b32_e32 v170, 16, v231
	v_and_b32_e32 v171, 0xffff0000, v231
	v_pk_add_f32 v[76:77], v[76:77], v[168:169]
	v_pk_add_f32 v[78:79], v[78:79], v[170:171]
	global_load_dwordx2 v[230:231], v136, s[26:27] offset:320
	s_waitcnt vmcnt(19)
	v_lshlrev_b32_e32 v168, 16, v232
	v_and_b32_e32 v169, 0xffff0000, v232
	v_lshlrev_b32_e32 v170, 16, v233
	v_and_b32_e32 v171, 0xffff0000, v233
	v_pk_add_f32 v[68:69], v[68:69], v[168:169]
	v_pk_add_f32 v[70:71], v[70:71], v[170:171]
	global_load_dwordx2 v[232:233], v136, s[26:27] offset:352
	s_nop 0
	v_cvt_pk_bf16_f32 v92, v92, v93
	v_cvt_pk_bf16_f32 v93, v94, v95
	v_cvt_pk_bf16_f32 v94, v84, v85
	v_cvt_pk_bf16_f32 v95, v86, v87
	v_cvt_pk_bf16_f32 v76, v76, v77
	v_cvt_pk_bf16_f32 v77, v78, v79
	v_cvt_pk_bf16_f32 v78, v68, v69
	v_cvt_pk_bf16_f32 v79, v70, v71
	s_nop 1
	v_permlane16_swap_b32_e32 v92, v94
	v_permlane16_swap_b32_e32 v93, v95
	v_permlane16_swap_b32_e32 v76, v78
	v_permlane16_swap_b32_e32 v77, v79
	global_store_dwordx4 v140, v[92:95], s[26:27] offset:0
	global_store_dwordx4 v140, v[76:79], s[26:27] offset:64
	s_waitcnt vmcnt(21)
; __device__ __forceinline__ float bflo(unsigned u) { return __uint_as_float(u << 16); }
; __device__ __forceinline__ float bfhi(unsigned u) { return __uint_as_float(u & 0xffff0000u); }
; #define WIDE_STORE(BASE, LD, COFF, O) do { if ((m & 1) == 0) opend[n] = (O); \
;                 else *(uint4*)((BASE) + (size_t)tok * (LD) + (ncw - (COFF))) = swap_pair(opend[n], (O)); } while (0)
;     ...
;               const int nc = brow + ai * 128 + wr * 64 + m * 16 + fq * 4;
;               const int tok = bcol + bj * 128 + wc * 32 + n * 16 + fr;
;               const int ncw = brow + ai * 128 + wr * 64 + ((m & ~1) + (fq & 1)) * 16 + (fq & ~1) * 4;
;     ...
;               } else {
;                 uint2* ph = (uint2*)((u16*)(ws + OFF_RB) + (size_t)tok * DM + nc);
;                 const uint2 hb = *ph;
;                 uint2 o; o.x = pk2(bflo(hb.x) + v[0], bfhi(hb.x) + v[1]); o.y = pk2(bflo(hb.y) + v[2], bfhi(hb.y) + v[3]);
;                 WIDE_STORE((u16*)(ws + OFF_RB), DM, 0, o);
	v_lshlrev_b32_e32 v168, 16, v234
	v_and_b32_e32 v169, 0xffff0000, v234
	v_lshlrev_b32_e32 v170, 16, v235
	v_and_b32_e32 v171, 0xffff0000, v235
	v_pk_add_f32 v[88:89], v[88:89], v[168:169]
	v_pk_add_f32 v[90:91], v[90:91], v[170:171]
	global_load_dwordx2 v[234:235], v137, s[26:27] offset:256
	s_waitcnt vmcnt(21)
	v_lshlrev_b32_e32 v168, 16, v236
	v_and_b32_e32 v169, 0xffff0000, v236
	v_lshlrev_b32_e32 v170, 16, v237
	v_and_b32_e32 v171, 0xffff0000, v237
	v_pk_add_f32 v[80:81], v[80:81], v[168:169]
	v_pk_add_f32 v[82:83], v[82:83], v[170:171]
	global_load_dwordx2 v[236:237], v137, s[26:27] offset:288
	s_waitcnt vmcnt(21)
	v_lshlrev_b32_e32 v168, 16, v238
	v_and_b32_e32 v169, 0xffff0000, v238
	v_lshlrev_b32_e32 v170, 16, v239
	v_and_b32_e32 v171, 0xffff0000, v239
	v_pk_add_f32 v[72:73], v[72:73], v[168:169]
	v_pk_add_f32 v[74:75], v[74:75], v[170:171]
	global_load_dwordx2 v[238:239], v137, s[26:27] offset:320
	s_waitcnt vmcnt(21)
	v_lshlrev_b32_e32 v168, 16, v240
	v_and_b32_e32 v169, 0xffff0000, v240
	v_lshlrev_b32_e32 v170, 16, v241
	v_and_b32_e32 v171, 0xffff0000, v241
	v_pk_add_f32 v[64:65], v[64:65], v[168:169]
	v_pk_add_f32 v[66:67], v[66:67], v[170:171]
	global_load_dwordx2 v[240:241], v137, s[26:27] offset:352
	s_nop 0
	v_cvt_pk_bf16_f32 v88, v88, v89
	v_cvt_pk_bf16_f32 v89, v90, v91
	v_cvt_pk_bf16_f32 v90, v80, v81
	v_cvt_pk_bf16_f32 v91, v82, v83
	v_cvt_pk_bf16_f32 v72, v72, v73
	v_cvt_pk_bf16_f32 v73, v74, v75
	v_cvt_pk_bf16_f32 v74, v64, v65
	v_cvt_pk_bf16_f32 v75, v66, v67
	s_nop 1
	v_permlane16_swap_b32_e32 v88, v90
	v_permlane16_swap_b32_e32 v89, v91
	v_permlane16_swap_b32_e32 v72, v74
	v_permlane16_swap_b32_e32 v73, v75
	global_store_dwordx4 v141, v[88:91], s[26:27] offset:0
	global_store_dwordx4 v141, v[72:75], s[26:27] offset:64
	s_waitcnt vmcnt(23)
	v_lshlrev_b32_e32 v168, 16, v210
	v_and_b32_e32 v169, 0xffff0000, v210
	v_lshlrev_b32_e32 v170, 16, v211
	v_and_b32_e32 v171, 0xffff0000, v211
	v_pk_add_f32 v[60:61], v[60:61], v[168:169]
	v_pk_add_f32 v[62:63], v[62:63], v[170:171]
	s_waitcnt vmcnt(22)
	v_lshlrev_b32_e32 v168, 16, v212
	v_and_b32_e32 v169, 0xffff0000, v212
	v_lshlrev_b32_e32 v170, 16, v213
	v_and_b32_e32 v171, 0xffff0000, v213
	v_pk_add_f32 v[52:53], v[52:53], v[168:169]
	v_pk_add_f32 v[54:55], v[54:55], v[170:171]
	s_waitcnt vmcnt(21)
	v_lshlrev_b32_e32 v168, 16, v214
	v_and_b32_e32 v169, 0xffff0000, v214
	v_lshlrev_b32_e32 v170, 16, v215
	v_and_b32_e32 v171, 0xffff0000, v215
	v_pk_add_f32 v[44:45], v[44:45], v[168:169]
	v_pk_add_f32 v[46:47], v[46:47], v[170:171]
	s_waitcnt vmcnt(20)
	v_lshlrev_b32_e32 v168, 16, v216
	v_and_b32_e32 v169, 0xffff0000, v216
	v_lshlrev_b32_e32 v170, 16, v217
	v_and_b32_e32 v171, 0xffff0000, v217
	v_pk_add_f32 v[36:37], v[36:37], v[168:169]
	v_pk_add_f32 v[38:39], v[38:39], v[170:171]
	s_nop 0
	v_cvt_pk_bf16_f32 v60, v60, v61
	v_cvt_pk_bf16_f32 v61, v62, v63
	v_cvt_pk_bf16_f32 v62, v52, v53
	v_cvt_pk_bf16_f32 v63, v54, v55
	v_cvt_pk_bf16_f32 v44, v44, v45
	v_cvt_pk_bf16_f32 v45, v46, v47
	v_cvt_pk_bf16_f32 v46, v36, v37
	v_cvt_pk_bf16_f32 v47, v38, v39
	s_nop 1
	v_permlane16_swap_b32_e32 v60, v62
	v_permlane16_swap_b32_e32 v61, v63
	v_permlane16_swap_b32_e32 v44, v46
	v_permlane16_swap_b32_e32 v45, v47
	global_store_dwordx4 v138, v[60:63], s[26:27] offset:256
	global_store_dwordx4 v138, v[44:47], s[26:27] offset:320
	s_waitcnt vmcnt(19)
	v_lshlrev_b32_e32 v168, 16, v218
	v_and_b32_e32 v169, 0xffff0000, v218
	v_lshlrev_b32_e32 v170, 16, v219
	v_and_b32_e32 v171, 0xffff0000, v219
	v_pk_add_f32 v[56:57], v[56:57], v[168:169]
	v_pk_add_f32 v[58:59], v[58:59], v[170:171]
	s_waitcnt vmcnt(18)
	v_lshlrev_b32_e32 v168, 16, v220
	v_and_b32_e32 v169, 0xffff0000, v220
	v_lshlrev_b32_e32 v170, 16, v221
	v_and_b32_e32 v171, 0xffff0000, v221
	v_pk_add_f32 v[48:49], v[48:49], v[168:169]
	v_pk_add_f32 v[50:51], v[50:51], v[170:171]
	s_waitcnt vmcnt(17)
	v_lshlrev_b32_e32 v168, 16, v222
	v_and_b32_e32 v169, 0xffff0000, v222
	v_lshlrev_b32_e32 v170, 16, v223
	v_and_b32_e32 v171, 0xffff0000, v223
	v_pk_add_f32 v[40:41], v[40:41], v[168:169]
	v_pk_add_f32 v[42:43], v[42:43], v[170:171]
	s_waitcnt vmcnt(16)
	v_lshlrev_b32_e32 v168, 16, v224
	v_and_b32_e32 v169, 0xffff0000, v224
	v_lshlrev_b32_e32 v170, 16, v225
	v_and_b32_e32 v171, 0xffff0000, v225
	v_pk_add_f32 v[32:33], v[32:33], v[168:169]
	v_pk_add_f32 v[34:35], v[34:35], v[170:171]
	s_nop 0
	v_cvt_pk_bf16_f32 v56, v56, v57
	v_cvt_pk_bf16_f32 v57, v58, v59
	v_cvt_pk_bf16_f32 v58, v48, v49
	v_cvt_pk_bf16_f32 v59, v50, v51
	v_cvt_pk_bf16_f32 v40, v40, v41
	v_cvt_pk_bf16_f32 v41, v42, v43
	v_cvt_pk_bf16_f32 v42, v32, v33
	v_cvt_pk_bf16_f32 v43, v34, v35
	s_nop 1
	v_permlane16_swap_b32_e32 v56, v58
	v_permlane16_swap_b32_e32 v57, v59
	v_permlane16_swap_b32_e32 v40, v42
	v_permlane16_swap_b32_e32 v41, v43
	global_store_dwordx4 v139, v[56:59], s[26:27] offset:256
	global_store_dwordx4 v139, v[40:43], s[26:27] offset:320
	s_waitcnt vmcnt(15)
	v_lshlrev_b32_e32 v168, 16, v226
	v_and_b32_e32 v169, 0xffff0000, v226
	v_lshlrev_b32_e32 v170, 16, v227
	v_and_b32_e32 v171, 0xffff0000, v227
	v_pk_add_f32 v[28:29], v[28:29], v[168:169]
	v_pk_add_f32 v[30:31], v[30:31], v[170:171]
	s_waitcnt vmcnt(14)
	v_lshlrev_b32_e32 v168, 16, v228
	v_and_b32_e32 v169, 0xffff0000, v228
	v_lshlrev_b32_e32 v170, 16, v229
	v_and_b32_e32 v171, 0xffff0000, v229
	v_pk_add_f32 v[20:21], v[20:21], v[168:169]
	v_pk_add_f32 v[22:23], v[22:23], v[170:171]
	s_waitcnt vmcnt(13)
; __device__ __forceinline__ float bflo(unsigned u) { return __uint_as_float(u << 16); }
; __device__ __forceinline__ float bfhi(unsigned u) { return __uint_as_float(u & 0xffff0000u); }
; #define WIDE_STORE(BASE, LD, COFF, O) do { if ((m & 1) == 0) opend[n] = (O); \
;                 else *(uint4*)((BASE) + (size_t)tok * (LD) + (ncw - (COFF))) = swap_pair(opend[n], (O)); } while (0)
;     ...
; #pragma unroll
;     for (int a = 0; a < 2; ++a)
; #pragma unroll
;       for (int b = 0; b < 2; ++b)
; #pragma unroll
;         for (int m = 0; m < 4; ++m)
; #pragma unroll
;           for (int n = 0; n < 2; ++n) acc[a][b][m][n] = f32x4{0.f, 0.f, 0.f, 0.f};
;     ...
;               } else {
;                 uint2* ph = (uint2*)((u16*)(ws + OFF_RB) + (size_t)tok * DM + nc);
;                 const uint2 hb = *ph;
;                 uint2 o; o.x = pk2(bflo(hb.x) + v[0], bfhi(hb.x) + v[1]); o.y = pk2(bflo(hb.y) + v[2], bfhi(hb.y) + v[3]);
;                 WIDE_STORE((u16*)(ws + OFF_RB), DM, 0, o);
;               }
;     ...
;             }
;     }
;     asm volatile("s_waitcnt vmcnt(0)" ::: "memory");
;     if (has_next && wr == 1) __builtin_amdgcn_s_barrier();
	v_lshlrev_b32_e32 v168, 16, v230
	v_and_b32_e32 v169, 0xffff0000, v230
	v_lshlrev_b32_e32 v170, 16, v231
	v_and_b32_e32 v171, 0xffff0000, v231
	v_pk_add_f32 v[12:13], v[12:13], v[168:169]
	v_pk_add_f32 v[14:15], v[14:15], v[170:171]
	s_waitcnt vmcnt(12)
	v_lshlrev_b32_e32 v168, 16, v232
	v_and_b32_e32 v169, 0xffff0000, v232
	v_lshlrev_b32_e32 v170, 16, v233
	v_and_b32_e32 v171, 0xffff0000, v233
	v_pk_add_f32 v[4:5], v[4:5], v[168:169]
	v_pk_add_f32 v[6:7], v[6:7], v[170:171]
	s_nop 0
	v_cvt_pk_bf16_f32 v28, v28, v29
	v_cvt_pk_bf16_f32 v29, v30, v31
	v_cvt_pk_bf16_f32 v30, v20, v21
	v_cvt_pk_bf16_f32 v31, v22, v23
	v_cvt_pk_bf16_f32 v12, v12, v13
	v_cvt_pk_bf16_f32 v13, v14, v15
	v_cvt_pk_bf16_f32 v14, v4, v5
	v_cvt_pk_bf16_f32 v15, v6, v7
	s_nop 1
	v_permlane16_swap_b32_e32 v28, v30
	v_permlane16_swap_b32_e32 v29, v31
	v_permlane16_swap_b32_e32 v12, v14
	v_permlane16_swap_b32_e32 v13, v15
	global_store_dwordx4 v140, v[28:31], s[26:27] offset:256
	global_store_dwordx4 v140, v[12:15], s[26:27] offset:320
	s_waitcnt vmcnt(11)
	v_lshlrev_b32_e32 v168, 16, v234
	v_and_b32_e32 v169, 0xffff0000, v234
	v_lshlrev_b32_e32 v170, 16, v235
	v_and_b32_e32 v171, 0xffff0000, v235
	v_pk_add_f32 v[24:25], v[24:25], v[168:169]
	v_pk_add_f32 v[26:27], v[26:27], v[170:171]
	s_waitcnt vmcnt(10)
	v_lshlrev_b32_e32 v168, 16, v236
	v_and_b32_e32 v169, 0xffff0000, v236
	v_lshlrev_b32_e32 v170, 16, v237
	v_and_b32_e32 v171, 0xffff0000, v237
	v_pk_add_f32 v[16:17], v[16:17], v[168:169]
	v_pk_add_f32 v[18:19], v[18:19], v[170:171]
	s_waitcnt vmcnt(9)
	v_lshlrev_b32_e32 v168, 16, v238
	v_and_b32_e32 v169, 0xffff0000, v238
	v_lshlrev_b32_e32 v170, 16, v239
	v_and_b32_e32 v171, 0xffff0000, v239
	v_pk_add_f32 v[8:9], v[8:9], v[168:169]
	v_pk_add_f32 v[10:11], v[10:11], v[170:171]
	s_waitcnt vmcnt(8)
	v_lshlrev_b32_e32 v168, 16, v240
	v_and_b32_e32 v169, 0xffff0000, v240
	v_lshlrev_b32_e32 v170, 16, v241
	v_and_b32_e32 v171, 0xffff0000, v241
	v_pk_add_f32 v[0:1], v[0:1], v[168:169]
	v_pk_add_f32 v[2:3], v[2:3], v[170:171]
	s_nop 0
	v_cvt_pk_bf16_f32 v24, v24, v25
	v_cvt_pk_bf16_f32 v25, v26, v27
	v_cvt_pk_bf16_f32 v26, v16, v17
	v_cvt_pk_bf16_f32 v27, v18, v19
	v_cvt_pk_bf16_f32 v8, v8, v9
	v_cvt_pk_bf16_f32 v9, v10, v11
	v_cvt_pk_bf16_f32 v10, v0, v1
	v_cvt_pk_bf16_f32 v11, v2, v3
	s_nop 1
	v_permlane16_swap_b32_e32 v24, v26
	v_permlane16_swap_b32_e32 v25, v27
	v_permlane16_swap_b32_e32 v8, v10
	v_permlane16_swap_b32_e32 v9, v11
	global_store_dwordx4 v141, v[24:27], s[26:27] offset:256
	global_store_dwordx4 v141, v[8:11], s[26:27] offset:320
	s_and_b64 s[0:1], s[56:57], s[8:9]
	s_andn2_b64 vcc, exec, s[0:1]
	s_nop 1
	v_mov_b32_e32 v0, 0
	v_mov_b32_e32 v1, v0
	v_mov_b32_e32 v2, v0
	v_mov_b32_e32 v3, v0
	v_mov_b32_e32 v4, v0
	v_mov_b32_e32 v5, v0
	v_mov_b32_e32 v6, v0
	v_mov_b32_e32 v7, v0
	v_mov_b32_e32 v8, v0
	v_mov_b32_e32 v9, v0
	v_mov_b32_e32 v10, v0
	v_mov_b32_e32 v11, v0
	v_mov_b32_e32 v12, v0
	v_mov_b32_e32 v13, v0
	v_mov_b32_e32 v14, v0
	v_mov_b32_e32 v15, v0
	v_mov_b32_e32 v16, v0
	v_mov_b32_e32 v17, v0
	v_mov_b32_e32 v18, v0
	v_mov_b32_e32 v19, v0
	v_mov_b32_e32 v20, v0
	v_mov_b32_e32 v21, v0
	v_mov_b32_e32 v22, v0
	v_mov_b32_e32 v23, v0
	v_mov_b32_e32 v24, v0
	v_mov_b32_e32 v25, v0
	v_mov_b32_e32 v26, v0
	v_mov_b32_e32 v27, v0
	v_mov_b32_e32 v28, v0
	v_mov_b32_e32 v29, v0
	v_mov_b32_e32 v30, v0
	v_mov_b32_e32 v31, v0
	v_mov_b32_e32 v32, v0
	v_mov_b32_e32 v33, v0
	v_mov_b32_e32 v34, v0
	v_mov_b32_e32 v35, v0
	v_mov_b32_e32 v36, v0
	v_mov_b32_e32 v37, v0
	v_mov_b32_e32 v38, v0
	v_mov_b32_e32 v39, v0
	v_mov_b32_e32 v40, v0
	v_mov_b32_e32 v41, v0
	v_mov_b32_e32 v42, v0
	v_mov_b32_e32 v43, v0
	v_mov_b32_e32 v44, v0
	v_mov_b32_e32 v45, v0
	v_mov_b32_e32 v46, v0
	v_mov_b32_e32 v47, v0
	v_mov_b32_e32 v48, v0
	v_mov_b32_e32 v49, v0
	v_mov_b32_e32 v50, v0
	v_mov_b32_e32 v51, v0
	v_mov_b32_e32 v52, v0
	v_mov_b32_e32 v53, v0
	v_mov_b32_e32 v54, v0
	v_mov_b32_e32 v55, v0
	v_mov_b32_e32 v56, v0
	v_mov_b32_e32 v57, v0
	v_mov_b32_e32 v58, v0
	v_mov_b32_e32 v59, v0
	v_mov_b32_e32 v60, v0
	v_mov_b32_e32 v61, v0
	v_mov_b32_e32 v62, v0
	v_mov_b32_e32 v63, v0
	v_mov_b32_e32 v64, v0
	v_mov_b32_e32 v65, v0
	v_mov_b32_e32 v66, v0
	v_mov_b32_e32 v67, v0
	v_mov_b32_e32 v68, v0
	v_mov_b32_e32 v69, v0
	v_mov_b32_e32 v70, v0
	v_mov_b32_e32 v71, v0
	v_mov_b32_e32 v72, v0
	v_mov_b32_e32 v73, v0
	v_mov_b32_e32 v74, v0
	v_mov_b32_e32 v75, v0
	v_mov_b32_e32 v76, v0
	v_mov_b32_e32 v77, v0
	v_mov_b32_e32 v78, v0
	v_mov_b32_e32 v79, v0
	v_mov_b32_e32 v80, v0
	v_mov_b32_e32 v81, v0
	v_mov_b32_e32 v82, v0
	v_mov_b32_e32 v83, v0
	v_mov_b32_e32 v84, v0
	v_mov_b32_e32 v85, v0
	v_mov_b32_e32 v86, v0
	v_mov_b32_e32 v87, v0
	v_mov_b32_e32 v88, v0
	v_mov_b32_e32 v89, v0
	v_mov_b32_e32 v90, v0
	v_mov_b32_e32 v91, v0
	v_mov_b32_e32 v92, v0
	v_mov_b32_e32 v93, v0
	v_mov_b32_e32 v94, v0
	v_mov_b32_e32 v95, v0
	v_mov_b32_e32 v96, v0
	v_mov_b32_e32 v97, v0
	v_mov_b32_e32 v98, v0
	v_mov_b32_e32 v99, v0
	v_mov_b32_e32 v100, v0
	v_mov_b32_e32 v101, v0
	v_mov_b32_e32 v102, v0
	v_mov_b32_e32 v103, v0
	v_mov_b32_e32 v104, v0
	v_mov_b32_e32 v105, v0
	v_mov_b32_e32 v106, v0
	v_mov_b32_e32 v107, v0
	v_mov_b32_e32 v108, v0
	v_mov_b32_e32 v109, v0
	v_mov_b32_e32 v110, v0
	v_mov_b32_e32 v111, v0
	v_mov_b32_e32 v112, v0
	v_mov_b32_e32 v113, v0
	v_mov_b32_e32 v114, v0
	v_mov_b32_e32 v115, v0
	v_mov_b32_e32 v116, v0
	v_mov_b32_e32 v117, v0
	v_mov_b32_e32 v118, v0
	v_mov_b32_e32 v119, v0
	v_mov_b32_e32 v120, v0
	v_mov_b32_e32 v121, v0
	v_mov_b32_e32 v122, v0
	v_mov_b32_e32 v123, v0
	v_mov_b32_e32 v124, v0
	v_mov_b32_e32 v125, v0
	v_mov_b32_e32 v126, v0
	v_mov_b32_e32 v127, v0
	s_waitcnt vmcnt(0)
	s_cbranch_vccnz .LBB0_1077
	s_barrier
	s_branch .LBB0_1077
